# u-pass: expert-id list reads issued one block ahead (no exposed LDS wait before the row loads)
# speedup vs baseline: 1.0009x; 1.0009x over previous
; __device__ __forceinline__ void peer_token(const Params& P, int t, int lane, int* sidx, float* sval, const int* sid, const float* sgate, const unsigned* szero) {
;     ...
;         float* sact = (float*)sidx + 128 * (lr & 3) + 4 * (g & 1);
;         const bool owner = (lr < 4) && ((g >> 1) == (lr & 1));
;         uint4 abuf[2][2][4];
;         unsigned off2[2];
; #pragma unroll
;         for (int hh = 0; hh < 2; ++hh) off2[hh] = (unsigned)sid[8 * hh + (lr & 7)] * 512u + lofs;
; #pragma unroll
;         for (int hh = 0; hh < 2; ++hh)
; #pragma unroll
;             for (int st = 0; st < 4; ++st) abuf[0][hh][st] = *(const uint4*)(Ub + (off2[hh] + 128 * st));
; #pragma unroll
;         for (int T = 0; T < 8; ++T) {
;             if (T + 1 < 8) {
; #pragma unroll
;                 for (int hh = 0; hh < 2; ++hh) off2[hh] = (unsigned)sid[16 * (T + 1) + 8 * hh + (lr & 7)] * 512u + lofs;
; #pragma unroll
;                 for (int hh = 0; hh < 2; ++hh)
; #pragma unroll
;                     for (int st = 0; st < 4; ++st) abuf[(T + 1) & 1][hh][st] = *(const uint4*)(Ub + (off2[hh] + 128 * st));
;             }
; #pragma unroll
;             for (int hh = 0; hh < 2; ++hh) {
;                 f32x4 au = (f32x4){0.f, 0.f, 0.f, 0.f};
; #pragma unroll
;                 for (int st = 0; st < 4; ++st) {
;                     const uint4 a4 = abuf[T & 1][hh][st];
;                     const v8i Av = {(int)a4.x, (int)a4.y, (int)a4.z, (int)a4.w, 0, 0, 0, 0};
;                     au = __builtin_amdgcn_mfma_scale_f32_16x16x128_f8f6f4(Av, Bv[st], au, 4, 0, 0, 0x7f7f7f7f, 0, 0x7f7f7f7f);
;                 }
;                 if (owner) *(f32x4*)(sact + 16 * T + 8 * hh) = au;
;             }
;         }
.Lbs_join:
	s_waitcnt lgkmcnt(0)
	s_mov_b64 exec, -1
	s_add_i32 s85, s85, 1
	s_cmp_lt_u32 s85, 8
	s_cbranch_scc1 .LBB0_1382
	v_add_u32_e32 v238, v114, v145
	v_add_u32_e32 v239, 1024, v238
	v_add_u32_e32 v240, 2048, v238
	v_add_u32_e32 v241, 3072, v238
	v_add_u32_e32 v242, 4096, v238
	v_add_u32_e32 v243, 5120, v238
	v_add_u32_e32 v244, 6144, v238
	v_add_u32_e32 v245, 7168, v238
	ds_read2_b32 v[96:97], v238 offset1:4
	ds_read2_b32 v[98:99], v238 offset0:8 offset1:12
	ds_read2_b32 v[230:231], v239 offset1:4
	ds_read2_b32 v[232:233], v239 offset0:8 offset1:12
	s_waitcnt lgkmcnt(0)
	v_lshl_add_u32 v96, v96, 9, v144
	v_lshl_add_u32 v97, v97, 9, v144
	v_lshl_add_u32 v98, v98, 9, v144
	v_lshl_add_u32 v99, v99, 9, v144
	global_load_dwordx4 v[0:3], v96, s[10:11]
	global_load_dwordx4 v[4:7], v96, s[10:11] offset:256
	global_load_dwordx4 v[8:11], v97, s[10:11]
	global_load_dwordx4 v[12:15], v97, s[10:11] offset:256
	global_load_dwordx4 v[16:19], v98, s[10:11]
	global_load_dwordx4 v[20:23], v98, s[10:11] offset:256
	global_load_dwordx4 v[24:27], v99, s[10:11]
	global_load_dwordx4 v[28:31], v99, s[10:11] offset:256
	s_waitcnt lgkmcnt(0)
	v_lshl_add_u32 v230, v230, 9, v144
	v_lshl_add_u32 v231, v231, 9, v144
	v_lshl_add_u32 v232, v232, 9, v144
	v_lshl_add_u32 v233, v233, 9, v144
	global_load_dwordx4 v[32:35], v230, s[10:11]
	global_load_dwordx4 v[36:39], v230, s[10:11] offset:256
	global_load_dwordx4 v[40:43], v231, s[10:11]
	global_load_dwordx4 v[44:47], v231, s[10:11] offset:256
	global_load_dwordx4 v[48:51], v232, s[10:11]
	global_load_dwordx4 v[52:55], v232, s[10:11] offset:256
	global_load_dwordx4 v[56:59], v233, s[10:11]
	global_load_dwordx4 v[60:63], v233, s[10:11] offset:256
	ds_read2_b32 v[96:97], v240 offset1:4
	ds_read2_b32 v[98:99], v240 offset0:8 offset1:12
	s_waitcnt vmcnt(8)
	v_mfma_scale_f32_16x16x128_f8f6f4 v[64:67], v[0:3], v[162:169], 0, v133, v133 op_sel_hi:[0,0,0] cbsz:4
	v_mfma_scale_f32_16x16x128_f8f6f4 v[64:67], v[4:7], v[170:177], v[64:67], v133, v133 op_sel_hi:[0,0,0] cbsz:4
	v_mfma_scale_f32_16x16x128_f8f6f4 v[68:71], v[8:11], v[162:169], 0, v133, v133 op_sel_hi:[0,0,0] cbsz:4
	v_mfma_scale_f32_16x16x128_f8f6f4 v[68:71], v[12:15], v[170:177], v[68:71], v133, v133 op_sel_hi:[0,0,0] cbsz:4
	v_mfma_scale_f32_16x16x128_f8f6f4 v[72:75], v[16:19], v[162:169], 0, v133, v133 op_sel_hi:[0,0,0] cbsz:4
	v_mfma_scale_f32_16x16x128_f8f6f4 v[72:75], v[20:23], v[170:177], v[72:75], v133, v133 op_sel_hi:[0,0,0] cbsz:4
	v_mfma_scale_f32_16x16x128_f8f6f4 v[76:79], v[24:27], v[162:169], 0, v133, v133 op_sel_hi:[0,0,0] cbsz:4
	v_mfma_scale_f32_16x16x128_f8f6f4 v[76:79], v[28:31], v[170:177], v[76:79], v133, v133 op_sel_hi:[0,0,0] cbsz:4
	s_waitcnt lgkmcnt(0)
	v_lshl_add_u32 v96, v96, 9, v144
	v_lshl_add_u32 v97, v97, 9, v144
	v_lshl_add_u32 v98, v98, 9, v144
	v_lshl_add_u32 v99, v99, 9, v144
	global_load_dwordx4 v[0:3], v96, s[10:11]
	global_load_dwordx4 v[4:7], v96, s[10:11] offset:256
	global_load_dwordx4 v[8:11], v97, s[10:11]
	global_load_dwordx4 v[12:15], v97, s[10:11] offset:256
	global_load_dwordx4 v[16:19], v98, s[10:11]
	global_load_dwordx4 v[20:23], v98, s[10:11] offset:256
	global_load_dwordx4 v[24:27], v99, s[10:11]
	global_load_dwordx4 v[28:31], v99, s[10:11] offset:256
	ds_read2_b32 v[230:231], v241 offset1:4
	ds_read2_b32 v[232:233], v241 offset0:8 offset1:12
	s_waitcnt vmcnt(8)
	v_mfma_scale_f32_16x16x128_f8f6f4 v[80:83], v[32:35], v[178:185], 0, v133, v133 op_sel_hi:[0,0,0] cbsz:4
	v_mfma_scale_f32_16x16x128_f8f6f4 v[80:83], v[36:39], v[186:193], v[80:83], v133, v133 op_sel_hi:[0,0,0] cbsz:4
	v_mfma_scale_f32_16x16x128_f8f6f4 v[84:87], v[40:43], v[178:185], 0, v133, v133 op_sel_hi:[0,0,0] cbsz:4
	v_mfma_scale_f32_16x16x128_f8f6f4 v[84:87], v[44:47], v[186:193], v[84:87], v133, v133 op_sel_hi:[0,0,0] cbsz:4
	v_mfma_scale_f32_16x16x128_f8f6f4 v[88:91], v[48:51], v[178:185], 0, v133, v133 op_sel_hi:[0,0,0] cbsz:4
	v_mfma_scale_f32_16x16x128_f8f6f4 v[88:91], v[52:55], v[186:193], v[88:91], v133, v133 op_sel_hi:[0,0,0] cbsz:4
	v_mfma_scale_f32_16x16x128_f8f6f4 v[92:95], v[56:59], v[178:185], 0, v133, v133 op_sel_hi:[0,0,0] cbsz:4
	v_mfma_scale_f32_16x16x128_f8f6f4 v[92:95], v[60:63], v[186:193], v[92:95], v133, v133 op_sel_hi:[0,0,0] cbsz:4
	s_nop 3
	v_mul_f32_e32 v234, v158, v64
	v_mul_f32_e32 v235, v158, v68
	v_mul_f32_e32 v236, v158, v72
	v_mul_f32_e32 v237, v158, v76
	v_fmac_f32_e32 v234, v159, v65
	v_fmac_f32_e32 v235, v159, v69
	v_fmac_f32_e32 v236, v159, v73
	v_fmac_f32_e32 v237, v159, v77
	v_fmac_f32_e32 v234, v160, v66
	v_fmac_f32_e32 v235, v160, v70
	v_fmac_f32_e32 v236, v160, v74
	v_fmac_f32_e32 v237, v160, v78
	v_fmac_f32_e32 v234, v161, v67
	v_fmac_f32_e32 v235, v161, v71
	v_fmac_f32_e32 v236, v161, v75
	v_fmac_f32_e32 v237, v161, v79
	v_add_f32_dpp v234, v234, v234 quad_perm:[1,0,3,2] row_mask:0xf bank_mask:0xf
	v_add_f32_dpp v235, v235, v235 quad_perm:[1,0,3,2] row_mask:0xf bank_mask:0xf
	v_add_f32_dpp v236, v236, v236 quad_perm:[1,0,3,2] row_mask:0xf bank_mask:0xf
	v_add_f32_dpp v237, v237, v237 quad_perm:[1,0,3,2] row_mask:0xf bank_mask:0xf
	v_add_f32_dpp v234, v234, v234 quad_perm:[2,3,0,1] row_mask:0xf bank_mask:0xf
	v_add_f32_dpp v235, v235, v235 quad_perm:[2,3,0,1] row_mask:0xf bank_mask:0xf
	v_add_f32_dpp v236, v236, v236 quad_perm:[2,3,0,1] row_mask:0xf bank_mask:0xf
	v_add_f32_dpp v237, v237, v237 quad_perm:[2,3,0,1] row_mask:0xf bank_mask:0xf
	v_add_f32_dpp v234, v234, v234 row_half_mirror row_mask:0xf bank_mask:0xf
	v_add_f32_dpp v235, v235, v235 row_half_mirror row_mask:0xf bank_mask:0xf
	v_add_f32_dpp v236, v236, v236 row_half_mirror row_mask:0xf bank_mask:0xf
	v_add_f32_dpp v237, v237, v237 row_half_mirror row_mask:0xf bank_mask:0xf
	s_mov_b32 exec_lo, 0x10001
	s_mov_b32 exec_hi, 0x10001
	ds_write_b32 v155, v234
	ds_write_b32 v155, v235 offset:16
	ds_write_b32 v155, v236 offset:32
	ds_write_b32 v155, v237 offset:48
	s_mov_b64 exec, -1
	s_waitcnt lgkmcnt(0)
; __device__ __forceinline__ void peer_token(const Params& P, int t, int lane, int* sidx, float* sval, const int* sid, const float* sgate, const unsigned* szero) {
;     ...
;         for (int hh = 0; hh < 2; ++hh) off2[hh] = (unsigned)sid[8 * hh + (lr & 7)] * 512u + lofs;
; #pragma unroll
;         for (int hh = 0; hh < 2; ++hh)
; #pragma unroll
;             for (int st = 0; st < 4; ++st) abuf[0][hh][st] = *(const uint4*)(Ub + (off2[hh] + 128 * st));
; #pragma unroll
;         for (int T = 0; T < 8; ++T) {
;             if (T + 1 < 8) {
; #pragma unroll
;                 for (int hh = 0; hh < 2; ++hh) off2[hh] = (unsigned)sid[16 * (T + 1) + 8 * hh + (lr & 7)] * 512u + lofs;
; #pragma unroll
;                 for (int hh = 0; hh < 2; ++hh)
; #pragma unroll
;                     for (int st = 0; st < 4; ++st) abuf[(T + 1) & 1][hh][st] = *(const uint4*)(Ub + (off2[hh] + 128 * st));
;             }
; #pragma unroll
;             for (int hh = 0; hh < 2; ++hh) {
;                 f32x4 au = (f32x4){0.f, 0.f, 0.f, 0.f};
; #pragma unroll
;                 for (int st = 0; st < 4; ++st) {
;                     const uint4 a4 = abuf[T & 1][hh][st];
;                     const v8i Av = {(int)a4.x, (int)a4.y, (int)a4.z, (int)a4.w, 0, 0, 0, 0};
;                     au = __builtin_amdgcn_mfma_scale_f32_16x16x128_f8f6f4(Av, Bv[st], au, 4, 0, 0, 0x7f7f7f7f, 0, 0x7f7f7f7f);
;                 }
;                 if (owner) *(f32x4*)(sact + 16 * T + 8 * hh) = au;
;             }
	v_lshl_add_u32 v230, v230, 9, v144
	v_lshl_add_u32 v231, v231, 9, v144
	v_lshl_add_u32 v232, v232, 9, v144
	v_lshl_add_u32 v233, v233, 9, v144
	global_load_dwordx4 v[32:35], v230, s[10:11]
	global_load_dwordx4 v[36:39], v230, s[10:11] offset:256
	global_load_dwordx4 v[40:43], v231, s[10:11]
	global_load_dwordx4 v[44:47], v231, s[10:11] offset:256
	global_load_dwordx4 v[48:51], v232, s[10:11]
	global_load_dwordx4 v[52:55], v232, s[10:11] offset:256
	global_load_dwordx4 v[56:59], v233, s[10:11]
	global_load_dwordx4 v[60:63], v233, s[10:11] offset:256
	ds_read2_b32 v[96:97], v242 offset1:4
	ds_read2_b32 v[98:99], v242 offset0:8 offset1:12
	s_waitcnt vmcnt(8)
	v_mfma_scale_f32_16x16x128_f8f6f4 v[64:67], v[0:3], v[194:201], 0, v133, v133 op_sel_hi:[0,0,0] cbsz:4
	v_mfma_scale_f32_16x16x128_f8f6f4 v[64:67], v[4:7], v[202:209], v[64:67], v133, v133 op_sel_hi:[0,0,0] cbsz:4
	v_mfma_scale_f32_16x16x128_f8f6f4 v[68:71], v[8:11], v[194:201], 0, v133, v133 op_sel_hi:[0,0,0] cbsz:4
	v_mfma_scale_f32_16x16x128_f8f6f4 v[68:71], v[12:15], v[202:209], v[68:71], v133, v133 op_sel_hi:[0,0,0] cbsz:4
	v_mfma_scale_f32_16x16x128_f8f6f4 v[72:75], v[16:19], v[194:201], 0, v133, v133 op_sel_hi:[0,0,0] cbsz:4
	v_mfma_scale_f32_16x16x128_f8f6f4 v[72:75], v[20:23], v[202:209], v[72:75], v133, v133 op_sel_hi:[0,0,0] cbsz:4
	v_mfma_scale_f32_16x16x128_f8f6f4 v[76:79], v[24:27], v[194:201], 0, v133, v133 op_sel_hi:[0,0,0] cbsz:4
	v_mfma_scale_f32_16x16x128_f8f6f4 v[76:79], v[28:31], v[202:209], v[76:79], v133, v133 op_sel_hi:[0,0,0] cbsz:4
	s_nop 3
	v_mul_f32_e32 v234, v158, v80
	v_mul_f32_e32 v235, v158, v84
	v_mul_f32_e32 v236, v158, v88
	v_mul_f32_e32 v237, v158, v92
	v_fmac_f32_e32 v234, v159, v81
	v_fmac_f32_e32 v235, v159, v85
	v_fmac_f32_e32 v236, v159, v89
	v_fmac_f32_e32 v237, v159, v93
	v_fmac_f32_e32 v234, v160, v82
	v_fmac_f32_e32 v235, v160, v86
	v_fmac_f32_e32 v236, v160, v90
	v_fmac_f32_e32 v237, v160, v94
	v_fmac_f32_e32 v234, v161, v83
	v_fmac_f32_e32 v235, v161, v87
	v_fmac_f32_e32 v236, v161, v91
	v_fmac_f32_e32 v237, v161, v95
	v_add_f32_dpp v234, v234, v234 quad_perm:[1,0,3,2] row_mask:0xf bank_mask:0xf
	v_add_f32_dpp v235, v235, v235 quad_perm:[1,0,3,2] row_mask:0xf bank_mask:0xf
	v_add_f32_dpp v236, v236, v236 quad_perm:[1,0,3,2] row_mask:0xf bank_mask:0xf
	v_add_f32_dpp v237, v237, v237 quad_perm:[1,0,3,2] row_mask:0xf bank_mask:0xf
	v_add_f32_dpp v234, v234, v234 quad_perm:[2,3,0,1] row_mask:0xf bank_mask:0xf
	v_add_f32_dpp v235, v235, v235 quad_perm:[2,3,0,1] row_mask:0xf bank_mask:0xf
	v_add_f32_dpp v236, v236, v236 quad_perm:[2,3,0,1] row_mask:0xf bank_mask:0xf
	v_add_f32_dpp v237, v237, v237 quad_perm:[2,3,0,1] row_mask:0xf bank_mask:0xf
	v_add_f32_dpp v234, v234, v234 row_half_mirror row_mask:0xf bank_mask:0xf
	v_add_f32_dpp v235, v235, v235 row_half_mirror row_mask:0xf bank_mask:0xf
	v_add_f32_dpp v236, v236, v236 row_half_mirror row_mask:0xf bank_mask:0xf
	v_add_f32_dpp v237, v237, v237 row_half_mirror row_mask:0xf bank_mask:0xf
	s_mov_b32 exec_lo, 0x10001
	s_mov_b32 exec_hi, 0x10001
	ds_write_b32 v155, v234 offset:512
	ds_write_b32 v155, v235 offset:528
	ds_write_b32 v155, v236 offset:544
	ds_write_b32 v155, v237 offset:560
	s_mov_b64 exec, -1
	s_waitcnt lgkmcnt(0)
	v_lshl_add_u32 v96, v96, 9, v144
	v_lshl_add_u32 v97, v97, 9, v144
	v_lshl_add_u32 v98, v98, 9, v144
	v_lshl_add_u32 v99, v99, 9, v144
	global_load_dwordx4 v[0:3], v96, s[10:11]
	global_load_dwordx4 v[4:7], v96, s[10:11] offset:256
	global_load_dwordx4 v[8:11], v97, s[10:11]
	global_load_dwordx4 v[12:15], v97, s[10:11] offset:256
	global_load_dwordx4 v[16:19], v98, s[10:11]
	global_load_dwordx4 v[20:23], v98, s[10:11] offset:256
	global_load_dwordx4 v[24:27], v99, s[10:11]
	global_load_dwordx4 v[28:31], v99, s[10:11] offset:256
	ds_read2_b32 v[230:231], v243 offset1:4
	ds_read2_b32 v[232:233], v243 offset0:8 offset1:12
	s_waitcnt vmcnt(8)
	v_mfma_scale_f32_16x16x128_f8f6f4 v[80:83], v[32:35], v[210:217], 0, v133, v133 op_sel_hi:[0,0,0] cbsz:4
	v_mfma_scale_f32_16x16x128_f8f6f4 v[80:83], v[36:39], v[218:225], v[80:83], v133, v133 op_sel_hi:[0,0,0] cbsz:4
	v_mfma_scale_f32_16x16x128_f8f6f4 v[84:87], v[40:43], v[210:217], 0, v133, v133 op_sel_hi:[0,0,0] cbsz:4
	v_mfma_scale_f32_16x16x128_f8f6f4 v[84:87], v[44:47], v[218:225], v[84:87], v133, v133 op_sel_hi:[0,0,0] cbsz:4
	v_mfma_scale_f32_16x16x128_f8f6f4 v[88:91], v[48:51], v[210:217], 0, v133, v133 op_sel_hi:[0,0,0] cbsz:4
	v_mfma_scale_f32_16x16x128_f8f6f4 v[88:91], v[52:55], v[218:225], v[88:91], v133, v133 op_sel_hi:[0,0,0] cbsz:4
	v_mfma_scale_f32_16x16x128_f8f6f4 v[92:95], v[56:59], v[210:217], 0, v133, v133 op_sel_hi:[0,0,0] cbsz:4
	v_mfma_scale_f32_16x16x128_f8f6f4 v[92:95], v[60:63], v[218:225], v[92:95], v133, v133 op_sel_hi:[0,0,0] cbsz:4
	s_nop 3
	v_mul_f32_e32 v234, v158, v64
	v_mul_f32_e32 v235, v158, v68
	v_mul_f32_e32 v236, v158, v72
	v_mul_f32_e32 v237, v158, v76
	v_fmac_f32_e32 v234, v159, v65
	v_fmac_f32_e32 v235, v159, v69
	v_fmac_f32_e32 v236, v159, v73
	v_fmac_f32_e32 v237, v159, v77
	v_fmac_f32_e32 v234, v160, v66
	v_fmac_f32_e32 v235, v160, v70
	v_fmac_f32_e32 v236, v160, v74
	v_fmac_f32_e32 v237, v160, v78
	v_fmac_f32_e32 v234, v161, v67
	v_fmac_f32_e32 v235, v161, v71
	v_fmac_f32_e32 v236, v161, v75
	v_fmac_f32_e32 v237, v161, v79
	v_add_f32_dpp v234, v234, v234 quad_perm:[1,0,3,2] row_mask:0xf bank_mask:0xf
	v_add_f32_dpp v235, v235, v235 quad_perm:[1,0,3,2] row_mask:0xf bank_mask:0xf
	v_add_f32_dpp v236, v236, v236 quad_perm:[1,0,3,2] row_mask:0xf bank_mask:0xf
	v_add_f32_dpp v237, v237, v237 quad_perm:[1,0,3,2] row_mask:0xf bank_mask:0xf
	v_add_f32_dpp v234, v234, v234 quad_perm:[2,3,0,1] row_mask:0xf bank_mask:0xf
	v_add_f32_dpp v235, v235, v235 quad_perm:[2,3,0,1] row_mask:0xf bank_mask:0xf
	v_add_f32_dpp v236, v236, v236 quad_perm:[2,3,0,1] row_mask:0xf bank_mask:0xf
	v_add_f32_dpp v237, v237, v237 quad_perm:[2,3,0,1] row_mask:0xf bank_mask:0xf
	v_add_f32_dpp v234, v234, v234 row_half_mirror row_mask:0xf bank_mask:0xf
	v_add_f32_dpp v235, v235, v235 row_half_mirror row_mask:0xf bank_mask:0xf
	v_add_f32_dpp v236, v236, v236 row_half_mirror row_mask:0xf bank_mask:0xf
	v_add_f32_dpp v237, v237, v237 row_half_mirror row_mask:0xf bank_mask:0xf
	s_mov_b32 exec_lo, 0x10001
	s_mov_b32 exec_hi, 0x10001
	ds_write_b32 v155, v234 offset:1024
	ds_write_b32 v155, v235 offset:1040
	ds_write_b32 v155, v236 offset:1056
	ds_write_b32 v155, v237 offset:1072
	s_mov_b64 exec, -1
	s_waitcnt lgkmcnt(0)
; __device__ __forceinline__ void peer_token(const Params& P, int t, int lane, int* sidx, float* sval, const int* sid, const float* sgate, const unsigned* szero) {
;     ...
;         for (int hh = 0; hh < 2; ++hh) off2[hh] = (unsigned)sid[8 * hh + (lr & 7)] * 512u + lofs;
; #pragma unroll
;         for (int hh = 0; hh < 2; ++hh)
; #pragma unroll
;             for (int st = 0; st < 4; ++st) abuf[0][hh][st] = *(const uint4*)(Ub + (off2[hh] + 128 * st));
; #pragma unroll
;         for (int T = 0; T < 8; ++T) {
;             if (T + 1 < 8) {
; #pragma unroll
;                 for (int hh = 0; hh < 2; ++hh) off2[hh] = (unsigned)sid[16 * (T + 1) + 8 * hh + (lr & 7)] * 512u + lofs;
; #pragma unroll
;                 for (int hh = 0; hh < 2; ++hh)
; #pragma unroll
;                     for (int st = 0; st < 4; ++st) abuf[(T + 1) & 1][hh][st] = *(const uint4*)(Ub + (off2[hh] + 128 * st));
;             }
; #pragma unroll
;             for (int hh = 0; hh < 2; ++hh) {
;                 f32x4 au = (f32x4){0.f, 0.f, 0.f, 0.f};
; #pragma unroll
;                 for (int st = 0; st < 4; ++st) {
;                     const uint4 a4 = abuf[T & 1][hh][st];
;                     const v8i Av = {(int)a4.x, (int)a4.y, (int)a4.z, (int)a4.w, 0, 0, 0, 0};
;                     au = __builtin_amdgcn_mfma_scale_f32_16x16x128_f8f6f4(Av, Bv[st], au, 4, 0, 0, 0x7f7f7f7f, 0, 0x7f7f7f7f);
;                 }
;                 if (owner) *(f32x4*)(sact + 16 * T + 8 * hh) = au;
;             }
	v_lshl_add_u32 v230, v230, 9, v144
	v_lshl_add_u32 v231, v231, 9, v144
	v_lshl_add_u32 v232, v232, 9, v144
	v_lshl_add_u32 v233, v233, 9, v144
	global_load_dwordx4 v[32:35], v230, s[10:11]
	global_load_dwordx4 v[36:39], v230, s[10:11] offset:256
	global_load_dwordx4 v[40:43], v231, s[10:11]
	global_load_dwordx4 v[44:47], v231, s[10:11] offset:256
	global_load_dwordx4 v[48:51], v232, s[10:11]
	global_load_dwordx4 v[52:55], v232, s[10:11] offset:256
	global_load_dwordx4 v[56:59], v233, s[10:11]
	global_load_dwordx4 v[60:63], v233, s[10:11] offset:256
	ds_read2_b32 v[96:97], v244 offset1:4
	ds_read2_b32 v[98:99], v244 offset0:8 offset1:12
	s_waitcnt vmcnt(8)
	v_mfma_scale_f32_16x16x128_f8f6f4 v[64:67], v[0:3], v[162:169], 0, v133, v133 op_sel_hi:[0,0,0] cbsz:4
	v_mfma_scale_f32_16x16x128_f8f6f4 v[64:67], v[4:7], v[170:177], v[64:67], v133, v133 op_sel_hi:[0,0,0] cbsz:4
	v_mfma_scale_f32_16x16x128_f8f6f4 v[68:71], v[8:11], v[162:169], 0, v133, v133 op_sel_hi:[0,0,0] cbsz:4
	v_mfma_scale_f32_16x16x128_f8f6f4 v[68:71], v[12:15], v[170:177], v[68:71], v133, v133 op_sel_hi:[0,0,0] cbsz:4
	v_mfma_scale_f32_16x16x128_f8f6f4 v[72:75], v[16:19], v[162:169], 0, v133, v133 op_sel_hi:[0,0,0] cbsz:4
	v_mfma_scale_f32_16x16x128_f8f6f4 v[72:75], v[20:23], v[170:177], v[72:75], v133, v133 op_sel_hi:[0,0,0] cbsz:4
	v_mfma_scale_f32_16x16x128_f8f6f4 v[76:79], v[24:27], v[162:169], 0, v133, v133 op_sel_hi:[0,0,0] cbsz:4
	v_mfma_scale_f32_16x16x128_f8f6f4 v[76:79], v[28:31], v[170:177], v[76:79], v133, v133 op_sel_hi:[0,0,0] cbsz:4
	s_nop 3
	v_mul_f32_e32 v234, v158, v80
	v_mul_f32_e32 v235, v158, v84
	v_mul_f32_e32 v236, v158, v88
	v_mul_f32_e32 v237, v158, v92
	v_fmac_f32_e32 v234, v159, v81
	v_fmac_f32_e32 v235, v159, v85
	v_fmac_f32_e32 v236, v159, v89
	v_fmac_f32_e32 v237, v159, v93
	v_fmac_f32_e32 v234, v160, v82
	v_fmac_f32_e32 v235, v160, v86
	v_fmac_f32_e32 v236, v160, v90
	v_fmac_f32_e32 v237, v160, v94
	v_fmac_f32_e32 v234, v161, v83
	v_fmac_f32_e32 v235, v161, v87
	v_fmac_f32_e32 v236, v161, v91
	v_fmac_f32_e32 v237, v161, v95
	v_add_f32_dpp v234, v234, v234 quad_perm:[1,0,3,2] row_mask:0xf bank_mask:0xf
	v_add_f32_dpp v235, v235, v235 quad_perm:[1,0,3,2] row_mask:0xf bank_mask:0xf
	v_add_f32_dpp v236, v236, v236 quad_perm:[1,0,3,2] row_mask:0xf bank_mask:0xf
	v_add_f32_dpp v237, v237, v237 quad_perm:[1,0,3,2] row_mask:0xf bank_mask:0xf
	v_add_f32_dpp v234, v234, v234 quad_perm:[2,3,0,1] row_mask:0xf bank_mask:0xf
	v_add_f32_dpp v235, v235, v235 quad_perm:[2,3,0,1] row_mask:0xf bank_mask:0xf
	v_add_f32_dpp v236, v236, v236 quad_perm:[2,3,0,1] row_mask:0xf bank_mask:0xf
	v_add_f32_dpp v237, v237, v237 quad_perm:[2,3,0,1] row_mask:0xf bank_mask:0xf
	v_add_f32_dpp v234, v234, v234 row_half_mirror row_mask:0xf bank_mask:0xf
	v_add_f32_dpp v235, v235, v235 row_half_mirror row_mask:0xf bank_mask:0xf
	v_add_f32_dpp v236, v236, v236 row_half_mirror row_mask:0xf bank_mask:0xf
	v_add_f32_dpp v237, v237, v237 row_half_mirror row_mask:0xf bank_mask:0xf
	s_mov_b32 exec_lo, 0x10001
	s_mov_b32 exec_hi, 0x10001
	ds_write_b32 v155, v234 offset:1536
	ds_write_b32 v155, v235 offset:1552
	ds_write_b32 v155, v236 offset:1568
	ds_write_b32 v155, v237 offset:1584
	s_mov_b64 exec, -1
	s_waitcnt lgkmcnt(0)
	v_lshl_add_u32 v96, v96, 9, v144
	v_lshl_add_u32 v97, v97, 9, v144
	v_lshl_add_u32 v98, v98, 9, v144
	v_lshl_add_u32 v99, v99, 9, v144
	global_load_dwordx4 v[0:3], v96, s[10:11]
	global_load_dwordx4 v[4:7], v96, s[10:11] offset:256
	global_load_dwordx4 v[8:11], v97, s[10:11]
	global_load_dwordx4 v[12:15], v97, s[10:11] offset:256
	global_load_dwordx4 v[16:19], v98, s[10:11]
	global_load_dwordx4 v[20:23], v98, s[10:11] offset:256
	global_load_dwordx4 v[24:27], v99, s[10:11]
	global_load_dwordx4 v[28:31], v99, s[10:11] offset:256
	ds_read2_b32 v[230:231], v245 offset1:4
	ds_read2_b32 v[232:233], v245 offset0:8 offset1:12
	s_waitcnt vmcnt(8)
	v_mfma_scale_f32_16x16x128_f8f6f4 v[80:83], v[32:35], v[178:185], 0, v133, v133 op_sel_hi:[0,0,0] cbsz:4
	v_mfma_scale_f32_16x16x128_f8f6f4 v[80:83], v[36:39], v[186:193], v[80:83], v133, v133 op_sel_hi:[0,0,0] cbsz:4
	v_mfma_scale_f32_16x16x128_f8f6f4 v[84:87], v[40:43], v[178:185], 0, v133, v133 op_sel_hi:[0,0,0] cbsz:4
	v_mfma_scale_f32_16x16x128_f8f6f4 v[84:87], v[44:47], v[186:193], v[84:87], v133, v133 op_sel_hi:[0,0,0] cbsz:4
	v_mfma_scale_f32_16x16x128_f8f6f4 v[88:91], v[48:51], v[178:185], 0, v133, v133 op_sel_hi:[0,0,0] cbsz:4
	v_mfma_scale_f32_16x16x128_f8f6f4 v[88:91], v[52:55], v[186:193], v[88:91], v133, v133 op_sel_hi:[0,0,0] cbsz:4
	v_mfma_scale_f32_16x16x128_f8f6f4 v[92:95], v[56:59], v[178:185], 0, v133, v133 op_sel_hi:[0,0,0] cbsz:4
	v_mfma_scale_f32_16x16x128_f8f6f4 v[92:95], v[60:63], v[186:193], v[92:95], v133, v133 op_sel_hi:[0,0,0] cbsz:4
	s_nop 3
	v_mul_f32_e32 v234, v226, v64
	v_mul_f32_e32 v235, v226, v68
	v_mul_f32_e32 v236, v226, v72
	v_mul_f32_e32 v237, v226, v76
	v_fmac_f32_e32 v234, v227, v65
	v_fmac_f32_e32 v235, v227, v69
	v_fmac_f32_e32 v236, v227, v73
	v_fmac_f32_e32 v237, v227, v77
	v_fmac_f32_e32 v234, v228, v66
	v_fmac_f32_e32 v235, v228, v70
	v_fmac_f32_e32 v236, v228, v74
	v_fmac_f32_e32 v237, v228, v78
	v_fmac_f32_e32 v234, v229, v67
	v_fmac_f32_e32 v235, v229, v71
	v_fmac_f32_e32 v236, v229, v75
	v_fmac_f32_e32 v237, v229, v79
	v_add_f32_dpp v234, v234, v234 quad_perm:[1,0,3,2] row_mask:0xf bank_mask:0xf
	v_add_f32_dpp v235, v235, v235 quad_perm:[1,0,3,2] row_mask:0xf bank_mask:0xf
	v_add_f32_dpp v236, v236, v236 quad_perm:[1,0,3,2] row_mask:0xf bank_mask:0xf
	v_add_f32_dpp v237, v237, v237 quad_perm:[1,0,3,2] row_mask:0xf bank_mask:0xf
	v_add_f32_dpp v234, v234, v234 quad_perm:[2,3,0,1] row_mask:0xf bank_mask:0xf
	v_add_f32_dpp v235, v235, v235 quad_perm:[2,3,0,1] row_mask:0xf bank_mask:0xf
	v_add_f32_dpp v236, v236, v236 quad_perm:[2,3,0,1] row_mask:0xf bank_mask:0xf
	v_add_f32_dpp v237, v237, v237 quad_perm:[2,3,0,1] row_mask:0xf bank_mask:0xf
	v_add_f32_dpp v234, v234, v234 row_half_mirror row_mask:0xf bank_mask:0xf
	v_add_f32_dpp v235, v235, v235 row_half_mirror row_mask:0xf bank_mask:0xf
	v_add_f32_dpp v236, v236, v236 row_half_mirror row_mask:0xf bank_mask:0xf
	v_add_f32_dpp v237, v237, v237 row_half_mirror row_mask:0xf bank_mask:0xf
	s_mov_b32 exec_lo, 0x1000100
	s_mov_b32 exec_hi, 0x1000100
	ds_write_b32 v155, v234 offset:2048
	ds_write_b32 v155, v235 offset:2064
	ds_write_b32 v155, v236 offset:2080
	ds_write_b32 v155, v237 offset:2096
	s_mov_b64 exec, -1
	s_waitcnt lgkmcnt(0)
; __device__ __forceinline__ void peer_token(const Params& P, int t, int lane, int* sidx, float* sval, const int* sid, const float* sgate, const unsigned* szero) {
;     ...
;         for (int hh = 0; hh < 2; ++hh) off2[hh] = (unsigned)sid[8 * hh + (lr & 7)] * 512u + lofs;
; #pragma unroll
;         for (int hh = 0; hh < 2; ++hh)
; #pragma unroll
;             for (int st = 0; st < 4; ++st) abuf[0][hh][st] = *(const uint4*)(Ub + (off2[hh] + 128 * st));
; #pragma unroll
;         for (int T = 0; T < 8; ++T) {
;             if (T + 1 < 8) {
; #pragma unroll
;                 for (int hh = 0; hh < 2; ++hh) off2[hh] = (unsigned)sid[16 * (T + 1) + 8 * hh + (lr & 7)] * 512u + lofs;
; #pragma unroll
;                 for (int hh = 0; hh < 2; ++hh)
; #pragma unroll
;                     for (int st = 0; st < 4; ++st) abuf[(T + 1) & 1][hh][st] = *(const uint4*)(Ub + (off2[hh] + 128 * st));
;             }
; #pragma unroll
;             for (int hh = 0; hh < 2; ++hh) {
;                 f32x4 au = (f32x4){0.f, 0.f, 0.f, 0.f};
; #pragma unroll
;                 for (int st = 0; st < 4; ++st) {
;                     const uint4 a4 = abuf[T & 1][hh][st];
;                     const v8i Av = {(int)a4.x, (int)a4.y, (int)a4.z, (int)a4.w, 0, 0, 0, 0};
;                     au = __builtin_amdgcn_mfma_scale_f32_16x16x128_f8f6f4(Av, Bv[st], au, 4, 0, 0, 0x7f7f7f7f, 0, 0x7f7f7f7f);
;                 }
;                 if (owner) *(f32x4*)(sact + 16 * T + 8 * hh) = au;
;             }
	v_lshl_add_u32 v230, v230, 9, v144
	v_lshl_add_u32 v231, v231, 9, v144
	v_lshl_add_u32 v232, v232, 9, v144
	v_lshl_add_u32 v233, v233, 9, v144
	global_load_dwordx4 v[32:35], v230, s[10:11]
	global_load_dwordx4 v[36:39], v230, s[10:11] offset:256
	global_load_dwordx4 v[40:43], v231, s[10:11]
	global_load_dwordx4 v[44:47], v231, s[10:11] offset:256
	global_load_dwordx4 v[48:51], v232, s[10:11]
	global_load_dwordx4 v[52:55], v232, s[10:11] offset:256
	global_load_dwordx4 v[56:59], v233, s[10:11]
	global_load_dwordx4 v[60:63], v233, s[10:11] offset:256
	ds_read2_b32 v[96:97], v238 offset0:16 offset1:20
	ds_read2_b32 v[98:99], v238 offset0:24 offset1:28
	s_waitcnt vmcnt(8)
	v_mfma_scale_f32_16x16x128_f8f6f4 v[64:67], v[0:3], v[194:201], 0, v133, v133 op_sel_hi:[0,0,0] cbsz:4
	v_mfma_scale_f32_16x16x128_f8f6f4 v[64:67], v[4:7], v[202:209], v[64:67], v133, v133 op_sel_hi:[0,0,0] cbsz:4
	v_mfma_scale_f32_16x16x128_f8f6f4 v[68:71], v[8:11], v[194:201], 0, v133, v133 op_sel_hi:[0,0,0] cbsz:4
	v_mfma_scale_f32_16x16x128_f8f6f4 v[68:71], v[12:15], v[202:209], v[68:71], v133, v133 op_sel_hi:[0,0,0] cbsz:4
	v_mfma_scale_f32_16x16x128_f8f6f4 v[72:75], v[16:19], v[194:201], 0, v133, v133 op_sel_hi:[0,0,0] cbsz:4
	v_mfma_scale_f32_16x16x128_f8f6f4 v[72:75], v[20:23], v[202:209], v[72:75], v133, v133 op_sel_hi:[0,0,0] cbsz:4
	v_mfma_scale_f32_16x16x128_f8f6f4 v[76:79], v[24:27], v[194:201], 0, v133, v133 op_sel_hi:[0,0,0] cbsz:4
	v_mfma_scale_f32_16x16x128_f8f6f4 v[76:79], v[28:31], v[202:209], v[76:79], v133, v133 op_sel_hi:[0,0,0] cbsz:4
	s_nop 3
	v_mul_f32_e32 v234, v226, v80
	v_mul_f32_e32 v235, v226, v84
	v_mul_f32_e32 v236, v226, v88
	v_mul_f32_e32 v237, v226, v92
	v_fmac_f32_e32 v234, v227, v81
	v_fmac_f32_e32 v235, v227, v85
	v_fmac_f32_e32 v236, v227, v89
	v_fmac_f32_e32 v237, v227, v93
	v_fmac_f32_e32 v234, v228, v82
	v_fmac_f32_e32 v235, v228, v86
	v_fmac_f32_e32 v236, v228, v90
	v_fmac_f32_e32 v237, v228, v94
	v_fmac_f32_e32 v234, v229, v83
	v_fmac_f32_e32 v235, v229, v87
	v_fmac_f32_e32 v236, v229, v91
	v_fmac_f32_e32 v237, v229, v95
	v_add_f32_dpp v234, v234, v234 quad_perm:[1,0,3,2] row_mask:0xf bank_mask:0xf
	v_add_f32_dpp v235, v235, v235 quad_perm:[1,0,3,2] row_mask:0xf bank_mask:0xf
	v_add_f32_dpp v236, v236, v236 quad_perm:[1,0,3,2] row_mask:0xf bank_mask:0xf
	v_add_f32_dpp v237, v237, v237 quad_perm:[1,0,3,2] row_mask:0xf bank_mask:0xf
	v_add_f32_dpp v234, v234, v234 quad_perm:[2,3,0,1] row_mask:0xf bank_mask:0xf
	v_add_f32_dpp v235, v235, v235 quad_perm:[2,3,0,1] row_mask:0xf bank_mask:0xf
	v_add_f32_dpp v236, v236, v236 quad_perm:[2,3,0,1] row_mask:0xf bank_mask:0xf
	v_add_f32_dpp v237, v237, v237 quad_perm:[2,3,0,1] row_mask:0xf bank_mask:0xf
	v_add_f32_dpp v234, v234, v234 row_half_mirror row_mask:0xf bank_mask:0xf
	v_add_f32_dpp v235, v235, v235 row_half_mirror row_mask:0xf bank_mask:0xf
	v_add_f32_dpp v236, v236, v236 row_half_mirror row_mask:0xf bank_mask:0xf
	v_add_f32_dpp v237, v237, v237 row_half_mirror row_mask:0xf bank_mask:0xf
	s_mov_b32 exec_lo, 0x1000100
	s_mov_b32 exec_hi, 0x1000100
	ds_write_b32 v155, v234 offset:2560
	ds_write_b32 v155, v235 offset:2576
	ds_write_b32 v155, v236 offset:2592
	ds_write_b32 v155, v237 offset:2608
	s_mov_b64 exec, -1
	s_waitcnt lgkmcnt(0)
	v_lshl_add_u32 v96, v96, 9, v144
	v_lshl_add_u32 v97, v97, 9, v144
	v_lshl_add_u32 v98, v98, 9, v144
	v_lshl_add_u32 v99, v99, 9, v144
	global_load_dwordx4 v[0:3], v96, s[10:11]
	global_load_dwordx4 v[4:7], v96, s[10:11] offset:256
	global_load_dwordx4 v[8:11], v97, s[10:11]
	global_load_dwordx4 v[12:15], v97, s[10:11] offset:256
	global_load_dwordx4 v[16:19], v98, s[10:11]
	global_load_dwordx4 v[20:23], v98, s[10:11] offset:256
	global_load_dwordx4 v[24:27], v99, s[10:11]
	global_load_dwordx4 v[28:31], v99, s[10:11] offset:256
	ds_read2_b32 v[230:231], v239 offset0:16 offset1:20
	ds_read2_b32 v[232:233], v239 offset0:24 offset1:28
	s_waitcnt vmcnt(8)
	v_mfma_scale_f32_16x16x128_f8f6f4 v[80:83], v[32:35], v[210:217], 0, v133, v133 op_sel_hi:[0,0,0] cbsz:4
	v_mfma_scale_f32_16x16x128_f8f6f4 v[80:83], v[36:39], v[218:225], v[80:83], v133, v133 op_sel_hi:[0,0,0] cbsz:4
	v_mfma_scale_f32_16x16x128_f8f6f4 v[84:87], v[40:43], v[210:217], 0, v133, v133 op_sel_hi:[0,0,0] cbsz:4
	v_mfma_scale_f32_16x16x128_f8f6f4 v[84:87], v[44:47], v[218:225], v[84:87], v133, v133 op_sel_hi:[0,0,0] cbsz:4
	v_mfma_scale_f32_16x16x128_f8f6f4 v[88:91], v[48:51], v[210:217], 0, v133, v133 op_sel_hi:[0,0,0] cbsz:4
	v_mfma_scale_f32_16x16x128_f8f6f4 v[88:91], v[52:55], v[218:225], v[88:91], v133, v133 op_sel_hi:[0,0,0] cbsz:4
	v_mfma_scale_f32_16x16x128_f8f6f4 v[92:95], v[56:59], v[210:217], 0, v133, v133 op_sel_hi:[0,0,0] cbsz:4
	v_mfma_scale_f32_16x16x128_f8f6f4 v[92:95], v[60:63], v[218:225], v[92:95], v133, v133 op_sel_hi:[0,0,0] cbsz:4
	s_nop 3
	v_mul_f32_e32 v234, v226, v64
	v_mul_f32_e32 v235, v226, v68
	v_mul_f32_e32 v236, v226, v72
	v_mul_f32_e32 v237, v226, v76
	v_fmac_f32_e32 v234, v227, v65
	v_fmac_f32_e32 v235, v227, v69
	v_fmac_f32_e32 v236, v227, v73
	v_fmac_f32_e32 v237, v227, v77
	v_fmac_f32_e32 v234, v228, v66
	v_fmac_f32_e32 v235, v228, v70
	v_fmac_f32_e32 v236, v228, v74
	v_fmac_f32_e32 v237, v228, v78
	v_fmac_f32_e32 v234, v229, v67
	v_fmac_f32_e32 v235, v229, v71
	v_fmac_f32_e32 v236, v229, v75
	v_fmac_f32_e32 v237, v229, v79
	v_add_f32_dpp v234, v234, v234 quad_perm:[1,0,3,2] row_mask:0xf bank_mask:0xf
	v_add_f32_dpp v235, v235, v235 quad_perm:[1,0,3,2] row_mask:0xf bank_mask:0xf
	v_add_f32_dpp v236, v236, v236 quad_perm:[1,0,3,2] row_mask:0xf bank_mask:0xf
	v_add_f32_dpp v237, v237, v237 quad_perm:[1,0,3,2] row_mask:0xf bank_mask:0xf
	v_add_f32_dpp v234, v234, v234 quad_perm:[2,3,0,1] row_mask:0xf bank_mask:0xf
	v_add_f32_dpp v235, v235, v235 quad_perm:[2,3,0,1] row_mask:0xf bank_mask:0xf
	v_add_f32_dpp v236, v236, v236 quad_perm:[2,3,0,1] row_mask:0xf bank_mask:0xf
	v_add_f32_dpp v237, v237, v237 quad_perm:[2,3,0,1] row_mask:0xf bank_mask:0xf
	v_add_f32_dpp v234, v234, v234 row_half_mirror row_mask:0xf bank_mask:0xf
	v_add_f32_dpp v235, v235, v235 row_half_mirror row_mask:0xf bank_mask:0xf
	v_add_f32_dpp v236, v236, v236 row_half_mirror row_mask:0xf bank_mask:0xf
	v_add_f32_dpp v237, v237, v237 row_half_mirror row_mask:0xf bank_mask:0xf
	s_mov_b32 exec_lo, 0x1000100
	s_mov_b32 exec_hi, 0x1000100
	ds_write_b32 v155, v234 offset:3072
	ds_write_b32 v155, v235 offset:3088
	ds_write_b32 v155, v236 offset:3104
	ds_write_b32 v155, v237 offset:3120
	s_mov_b64 exec, -1
	s_waitcnt lgkmcnt(0)
; __device__ __forceinline__ void peer_token(const Params& P, int t, int lane, int* sidx, float* sval, const int* sid, const float* sgate, const unsigned* szero) {
;     ...
;         for (int hh = 0; hh < 2; ++hh) off2[hh] = (unsigned)sid[8 * hh + (lr & 7)] * 512u + lofs;
; #pragma unroll
;         for (int hh = 0; hh < 2; ++hh)
; #pragma unroll
;             for (int st = 0; st < 4; ++st) abuf[0][hh][st] = *(const uint4*)(Ub + (off2[hh] + 128 * st));
; #pragma unroll
;         for (int T = 0; T < 8; ++T) {
;             if (T + 1 < 8) {
; #pragma unroll
;                 for (int hh = 0; hh < 2; ++hh) off2[hh] = (unsigned)sid[16 * (T + 1) + 8 * hh + (lr & 7)] * 512u + lofs;
; #pragma unroll
;                 for (int hh = 0; hh < 2; ++hh)
; #pragma unroll
;                     for (int st = 0; st < 4; ++st) abuf[(T + 1) & 1][hh][st] = *(const uint4*)(Ub + (off2[hh] + 128 * st));
;             }
; #pragma unroll
;             for (int hh = 0; hh < 2; ++hh) {
;                 f32x4 au = (f32x4){0.f, 0.f, 0.f, 0.f};
; #pragma unroll
;                 for (int st = 0; st < 4; ++st) {
;                     const uint4 a4 = abuf[T & 1][hh][st];
;                     const v8i Av = {(int)a4.x, (int)a4.y, (int)a4.z, (int)a4.w, 0, 0, 0, 0};
;                     au = __builtin_amdgcn_mfma_scale_f32_16x16x128_f8f6f4(Av, Bv[st], au, 4, 0, 0, 0x7f7f7f7f, 0, 0x7f7f7f7f);
;                 }
;                 if (owner) *(f32x4*)(sact + 16 * T + 8 * hh) = au;
;             }
	v_lshl_add_u32 v230, v230, 9, v144
	v_lshl_add_u32 v231, v231, 9, v144
	v_lshl_add_u32 v232, v232, 9, v144
	v_lshl_add_u32 v233, v233, 9, v144
	global_load_dwordx4 v[32:35], v230, s[10:11]
	global_load_dwordx4 v[36:39], v230, s[10:11] offset:256
	global_load_dwordx4 v[40:43], v231, s[10:11]
	global_load_dwordx4 v[44:47], v231, s[10:11] offset:256
	global_load_dwordx4 v[48:51], v232, s[10:11]
	global_load_dwordx4 v[52:55], v232, s[10:11] offset:256
	global_load_dwordx4 v[56:59], v233, s[10:11]
	global_load_dwordx4 v[60:63], v233, s[10:11] offset:256
	ds_read2_b32 v[96:97], v240 offset0:16 offset1:20
	ds_read2_b32 v[98:99], v240 offset0:24 offset1:28
	s_waitcnt vmcnt(8)
	v_mfma_scale_f32_16x16x128_f8f6f4 v[64:67], v[0:3], v[162:169], 0, v133, v133 op_sel_hi:[0,0,0] cbsz:4
	v_mfma_scale_f32_16x16x128_f8f6f4 v[64:67], v[4:7], v[170:177], v[64:67], v133, v133 op_sel_hi:[0,0,0] cbsz:4
	v_mfma_scale_f32_16x16x128_f8f6f4 v[68:71], v[8:11], v[162:169], 0, v133, v133 op_sel_hi:[0,0,0] cbsz:4
	v_mfma_scale_f32_16x16x128_f8f6f4 v[68:71], v[12:15], v[170:177], v[68:71], v133, v133 op_sel_hi:[0,0,0] cbsz:4
	v_mfma_scale_f32_16x16x128_f8f6f4 v[72:75], v[16:19], v[162:169], 0, v133, v133 op_sel_hi:[0,0,0] cbsz:4
	v_mfma_scale_f32_16x16x128_f8f6f4 v[72:75], v[20:23], v[170:177], v[72:75], v133, v133 op_sel_hi:[0,0,0] cbsz:4
	v_mfma_scale_f32_16x16x128_f8f6f4 v[76:79], v[24:27], v[162:169], 0, v133, v133 op_sel_hi:[0,0,0] cbsz:4
	v_mfma_scale_f32_16x16x128_f8f6f4 v[76:79], v[28:31], v[170:177], v[76:79], v133, v133 op_sel_hi:[0,0,0] cbsz:4
	s_nop 3
	v_mul_f32_e32 v234, v226, v80
	v_mul_f32_e32 v235, v226, v84
	v_mul_f32_e32 v236, v226, v88
	v_mul_f32_e32 v237, v226, v92
	v_fmac_f32_e32 v234, v227, v81
	v_fmac_f32_e32 v235, v227, v85
	v_fmac_f32_e32 v236, v227, v89
	v_fmac_f32_e32 v237, v227, v93
	v_fmac_f32_e32 v234, v228, v82
	v_fmac_f32_e32 v235, v228, v86
	v_fmac_f32_e32 v236, v228, v90
	v_fmac_f32_e32 v237, v228, v94
	v_fmac_f32_e32 v234, v229, v83
	v_fmac_f32_e32 v235, v229, v87
	v_fmac_f32_e32 v236, v229, v91
	v_fmac_f32_e32 v237, v229, v95
	v_add_f32_dpp v234, v234, v234 quad_perm:[1,0,3,2] row_mask:0xf bank_mask:0xf
	v_add_f32_dpp v235, v235, v235 quad_perm:[1,0,3,2] row_mask:0xf bank_mask:0xf
	v_add_f32_dpp v236, v236, v236 quad_perm:[1,0,3,2] row_mask:0xf bank_mask:0xf
	v_add_f32_dpp v237, v237, v237 quad_perm:[1,0,3,2] row_mask:0xf bank_mask:0xf
	v_add_f32_dpp v234, v234, v234 quad_perm:[2,3,0,1] row_mask:0xf bank_mask:0xf
	v_add_f32_dpp v235, v235, v235 quad_perm:[2,3,0,1] row_mask:0xf bank_mask:0xf
	v_add_f32_dpp v236, v236, v236 quad_perm:[2,3,0,1] row_mask:0xf bank_mask:0xf
	v_add_f32_dpp v237, v237, v237 quad_perm:[2,3,0,1] row_mask:0xf bank_mask:0xf
	v_add_f32_dpp v234, v234, v234 row_half_mirror row_mask:0xf bank_mask:0xf
	v_add_f32_dpp v235, v235, v235 row_half_mirror row_mask:0xf bank_mask:0xf
	v_add_f32_dpp v236, v236, v236 row_half_mirror row_mask:0xf bank_mask:0xf
	v_add_f32_dpp v237, v237, v237 row_half_mirror row_mask:0xf bank_mask:0xf
	s_mov_b32 exec_lo, 0x1000100
	s_mov_b32 exec_hi, 0x1000100
	ds_write_b32 v155, v234 offset:3584
	ds_write_b32 v155, v235 offset:3600
	ds_write_b32 v155, v236 offset:3616
	ds_write_b32 v155, v237 offset:3632
	s_mov_b64 exec, -1
	s_waitcnt lgkmcnt(0)
	v_lshl_add_u32 v96, v96, 9, v144
	v_lshl_add_u32 v97, v97, 9, v144
	v_lshl_add_u32 v98, v98, 9, v144
	v_lshl_add_u32 v99, v99, 9, v144
	global_load_dwordx4 v[0:3], v96, s[10:11]
	global_load_dwordx4 v[4:7], v96, s[10:11] offset:256
	global_load_dwordx4 v[8:11], v97, s[10:11]
	global_load_dwordx4 v[12:15], v97, s[10:11] offset:256
	global_load_dwordx4 v[16:19], v98, s[10:11]
	global_load_dwordx4 v[20:23], v98, s[10:11] offset:256
	global_load_dwordx4 v[24:27], v99, s[10:11]
	global_load_dwordx4 v[28:31], v99, s[10:11] offset:256
	ds_read2_b32 v[230:231], v241 offset0:16 offset1:20
	ds_read2_b32 v[232:233], v241 offset0:24 offset1:28
	s_waitcnt vmcnt(8)
	v_mfma_scale_f32_16x16x128_f8f6f4 v[80:83], v[32:35], v[178:185], 0, v133, v133 op_sel_hi:[0,0,0] cbsz:4
	v_mfma_scale_f32_16x16x128_f8f6f4 v[80:83], v[36:39], v[186:193], v[80:83], v133, v133 op_sel_hi:[0,0,0] cbsz:4
	v_mfma_scale_f32_16x16x128_f8f6f4 v[84:87], v[40:43], v[178:185], 0, v133, v133 op_sel_hi:[0,0,0] cbsz:4
	v_mfma_scale_f32_16x16x128_f8f6f4 v[84:87], v[44:47], v[186:193], v[84:87], v133, v133 op_sel_hi:[0,0,0] cbsz:4
	v_mfma_scale_f32_16x16x128_f8f6f4 v[88:91], v[48:51], v[178:185], 0, v133, v133 op_sel_hi:[0,0,0] cbsz:4
	v_mfma_scale_f32_16x16x128_f8f6f4 v[88:91], v[52:55], v[186:193], v[88:91], v133, v133 op_sel_hi:[0,0,0] cbsz:4
	v_mfma_scale_f32_16x16x128_f8f6f4 v[92:95], v[56:59], v[178:185], 0, v133, v133 op_sel_hi:[0,0,0] cbsz:4
	v_mfma_scale_f32_16x16x128_f8f6f4 v[92:95], v[60:63], v[186:193], v[92:95], v133, v133 op_sel_hi:[0,0,0] cbsz:4
	s_nop 3
	v_mul_f32_e32 v234, v158, v64
	v_mul_f32_e32 v235, v158, v68
	v_mul_f32_e32 v236, v158, v72
	v_mul_f32_e32 v237, v158, v76
	v_fmac_f32_e32 v234, v159, v65
	v_fmac_f32_e32 v235, v159, v69
	v_fmac_f32_e32 v236, v159, v73
	v_fmac_f32_e32 v237, v159, v77
	v_fmac_f32_e32 v234, v160, v66
	v_fmac_f32_e32 v235, v160, v70
	v_fmac_f32_e32 v236, v160, v74
	v_fmac_f32_e32 v237, v160, v78
	v_fmac_f32_e32 v234, v161, v67
	v_fmac_f32_e32 v235, v161, v71
	v_fmac_f32_e32 v236, v161, v75
	v_fmac_f32_e32 v237, v161, v79
	v_add_f32_dpp v234, v234, v234 quad_perm:[1,0,3,2] row_mask:0xf bank_mask:0xf
	v_add_f32_dpp v235, v235, v235 quad_perm:[1,0,3,2] row_mask:0xf bank_mask:0xf
	v_add_f32_dpp v236, v236, v236 quad_perm:[1,0,3,2] row_mask:0xf bank_mask:0xf
	v_add_f32_dpp v237, v237, v237 quad_perm:[1,0,3,2] row_mask:0xf bank_mask:0xf
	v_add_f32_dpp v234, v234, v234 quad_perm:[2,3,0,1] row_mask:0xf bank_mask:0xf
	v_add_f32_dpp v235, v235, v235 quad_perm:[2,3,0,1] row_mask:0xf bank_mask:0xf
	v_add_f32_dpp v236, v236, v236 quad_perm:[2,3,0,1] row_mask:0xf bank_mask:0xf
	v_add_f32_dpp v237, v237, v237 quad_perm:[2,3,0,1] row_mask:0xf bank_mask:0xf
	v_add_f32_dpp v234, v234, v234 row_half_mirror row_mask:0xf bank_mask:0xf
	v_add_f32_dpp v235, v235, v235 row_half_mirror row_mask:0xf bank_mask:0xf
	v_add_f32_dpp v236, v236, v236 row_half_mirror row_mask:0xf bank_mask:0xf
	v_add_f32_dpp v237, v237, v237 row_half_mirror row_mask:0xf bank_mask:0xf
	s_mov_b32 exec_lo, 0x10001
	s_mov_b32 exec_hi, 0x10001
	ds_write_b32 v155, v234 offset:64
	ds_write_b32 v155, v235 offset:80
	ds_write_b32 v155, v236 offset:96
	ds_write_b32 v155, v237 offset:112
	s_mov_b64 exec, -1
	s_waitcnt lgkmcnt(0)
; __device__ __forceinline__ void peer_token(const Params& P, int t, int lane, int* sidx, float* sval, const int* sid, const float* sgate, const unsigned* szero) {
;     ...
;         for (int hh = 0; hh < 2; ++hh) off2[hh] = (unsigned)sid[8 * hh + (lr & 7)] * 512u + lofs;
; #pragma unroll
;         for (int hh = 0; hh < 2; ++hh)
; #pragma unroll
;             for (int st = 0; st < 4; ++st) abuf[0][hh][st] = *(const uint4*)(Ub + (off2[hh] + 128 * st));
; #pragma unroll
;         for (int T = 0; T < 8; ++T) {
;             if (T + 1 < 8) {
; #pragma unroll
;                 for (int hh = 0; hh < 2; ++hh) off2[hh] = (unsigned)sid[16 * (T + 1) + 8 * hh + (lr & 7)] * 512u + lofs;
; #pragma unroll
;                 for (int hh = 0; hh < 2; ++hh)
; #pragma unroll
;                     for (int st = 0; st < 4; ++st) abuf[(T + 1) & 1][hh][st] = *(const uint4*)(Ub + (off2[hh] + 128 * st));
;             }
; #pragma unroll
;             for (int hh = 0; hh < 2; ++hh) {
;                 f32x4 au = (f32x4){0.f, 0.f, 0.f, 0.f};
; #pragma unroll
;                 for (int st = 0; st < 4; ++st) {
;                     const uint4 a4 = abuf[T & 1][hh][st];
;                     const v8i Av = {(int)a4.x, (int)a4.y, (int)a4.z, (int)a4.w, 0, 0, 0, 0};
;                     au = __builtin_amdgcn_mfma_scale_f32_16x16x128_f8f6f4(Av, Bv[st], au, 4, 0, 0, 0x7f7f7f7f, 0, 0x7f7f7f7f);
;                 }
;                 if (owner) *(f32x4*)(sact + 16 * T + 8 * hh) = au;
;             }
	v_lshl_add_u32 v230, v230, 9, v144
	v_lshl_add_u32 v231, v231, 9, v144
	v_lshl_add_u32 v232, v232, 9, v144
	v_lshl_add_u32 v233, v233, 9, v144
	global_load_dwordx4 v[32:35], v230, s[10:11]
	global_load_dwordx4 v[36:39], v230, s[10:11] offset:256
	global_load_dwordx4 v[40:43], v231, s[10:11]
	global_load_dwordx4 v[44:47], v231, s[10:11] offset:256
	global_load_dwordx4 v[48:51], v232, s[10:11]
	global_load_dwordx4 v[52:55], v232, s[10:11] offset:256
	global_load_dwordx4 v[56:59], v233, s[10:11]
	global_load_dwordx4 v[60:63], v233, s[10:11] offset:256
	ds_read2_b32 v[96:97], v242 offset0:16 offset1:20
	ds_read2_b32 v[98:99], v242 offset0:24 offset1:28
	s_waitcnt vmcnt(8)
	v_mfma_scale_f32_16x16x128_f8f6f4 v[64:67], v[0:3], v[194:201], 0, v133, v133 op_sel_hi:[0,0,0] cbsz:4
	v_mfma_scale_f32_16x16x128_f8f6f4 v[64:67], v[4:7], v[202:209], v[64:67], v133, v133 op_sel_hi:[0,0,0] cbsz:4
	v_mfma_scale_f32_16x16x128_f8f6f4 v[68:71], v[8:11], v[194:201], 0, v133, v133 op_sel_hi:[0,0,0] cbsz:4
	v_mfma_scale_f32_16x16x128_f8f6f4 v[68:71], v[12:15], v[202:209], v[68:71], v133, v133 op_sel_hi:[0,0,0] cbsz:4
	v_mfma_scale_f32_16x16x128_f8f6f4 v[72:75], v[16:19], v[194:201], 0, v133, v133 op_sel_hi:[0,0,0] cbsz:4
	v_mfma_scale_f32_16x16x128_f8f6f4 v[72:75], v[20:23], v[202:209], v[72:75], v133, v133 op_sel_hi:[0,0,0] cbsz:4
	v_mfma_scale_f32_16x16x128_f8f6f4 v[76:79], v[24:27], v[194:201], 0, v133, v133 op_sel_hi:[0,0,0] cbsz:4
	v_mfma_scale_f32_16x16x128_f8f6f4 v[76:79], v[28:31], v[202:209], v[76:79], v133, v133 op_sel_hi:[0,0,0] cbsz:4
	s_nop 3
	v_mul_f32_e32 v234, v158, v80
	v_mul_f32_e32 v235, v158, v84
	v_mul_f32_e32 v236, v158, v88
	v_mul_f32_e32 v237, v158, v92
	v_fmac_f32_e32 v234, v159, v81
	v_fmac_f32_e32 v235, v159, v85
	v_fmac_f32_e32 v236, v159, v89
	v_fmac_f32_e32 v237, v159, v93
	v_fmac_f32_e32 v234, v160, v82
	v_fmac_f32_e32 v235, v160, v86
	v_fmac_f32_e32 v236, v160, v90
	v_fmac_f32_e32 v237, v160, v94
	v_fmac_f32_e32 v234, v161, v83
	v_fmac_f32_e32 v235, v161, v87
	v_fmac_f32_e32 v236, v161, v91
	v_fmac_f32_e32 v237, v161, v95
	v_add_f32_dpp v234, v234, v234 quad_perm:[1,0,3,2] row_mask:0xf bank_mask:0xf
	v_add_f32_dpp v235, v235, v235 quad_perm:[1,0,3,2] row_mask:0xf bank_mask:0xf
	v_add_f32_dpp v236, v236, v236 quad_perm:[1,0,3,2] row_mask:0xf bank_mask:0xf
	v_add_f32_dpp v237, v237, v237 quad_perm:[1,0,3,2] row_mask:0xf bank_mask:0xf
	v_add_f32_dpp v234, v234, v234 quad_perm:[2,3,0,1] row_mask:0xf bank_mask:0xf
	v_add_f32_dpp v235, v235, v235 quad_perm:[2,3,0,1] row_mask:0xf bank_mask:0xf
	v_add_f32_dpp v236, v236, v236 quad_perm:[2,3,0,1] row_mask:0xf bank_mask:0xf
	v_add_f32_dpp v237, v237, v237 quad_perm:[2,3,0,1] row_mask:0xf bank_mask:0xf
	v_add_f32_dpp v234, v234, v234 row_half_mirror row_mask:0xf bank_mask:0xf
	v_add_f32_dpp v235, v235, v235 row_half_mirror row_mask:0xf bank_mask:0xf
	v_add_f32_dpp v236, v236, v236 row_half_mirror row_mask:0xf bank_mask:0xf
	v_add_f32_dpp v237, v237, v237 row_half_mirror row_mask:0xf bank_mask:0xf
	s_mov_b32 exec_lo, 0x10001
	s_mov_b32 exec_hi, 0x10001
	ds_write_b32 v155, v234 offset:576
	ds_write_b32 v155, v235 offset:592
	ds_write_b32 v155, v236 offset:608
	ds_write_b32 v155, v237 offset:624
	s_mov_b64 exec, -1
	s_waitcnt lgkmcnt(0)
	v_lshl_add_u32 v96, v96, 9, v144
	v_lshl_add_u32 v97, v97, 9, v144
	v_lshl_add_u32 v98, v98, 9, v144
	v_lshl_add_u32 v99, v99, 9, v144
	global_load_dwordx4 v[0:3], v96, s[10:11]
	global_load_dwordx4 v[4:7], v96, s[10:11] offset:256
	global_load_dwordx4 v[8:11], v97, s[10:11]
	global_load_dwordx4 v[12:15], v97, s[10:11] offset:256
	global_load_dwordx4 v[16:19], v98, s[10:11]
	global_load_dwordx4 v[20:23], v98, s[10:11] offset:256
	global_load_dwordx4 v[24:27], v99, s[10:11]
	global_load_dwordx4 v[28:31], v99, s[10:11] offset:256
	ds_read2_b32 v[230:231], v243 offset0:16 offset1:20
	ds_read2_b32 v[232:233], v243 offset0:24 offset1:28
	s_waitcnt vmcnt(8)
	v_mfma_scale_f32_16x16x128_f8f6f4 v[80:83], v[32:35], v[210:217], 0, v133, v133 op_sel_hi:[0,0,0] cbsz:4
	v_mfma_scale_f32_16x16x128_f8f6f4 v[80:83], v[36:39], v[218:225], v[80:83], v133, v133 op_sel_hi:[0,0,0] cbsz:4
	v_mfma_scale_f32_16x16x128_f8f6f4 v[84:87], v[40:43], v[210:217], 0, v133, v133 op_sel_hi:[0,0,0] cbsz:4
	v_mfma_scale_f32_16x16x128_f8f6f4 v[84:87], v[44:47], v[218:225], v[84:87], v133, v133 op_sel_hi:[0,0,0] cbsz:4
	v_mfma_scale_f32_16x16x128_f8f6f4 v[88:91], v[48:51], v[210:217], 0, v133, v133 op_sel_hi:[0,0,0] cbsz:4
	v_mfma_scale_f32_16x16x128_f8f6f4 v[88:91], v[52:55], v[218:225], v[88:91], v133, v133 op_sel_hi:[0,0,0] cbsz:4
	v_mfma_scale_f32_16x16x128_f8f6f4 v[92:95], v[56:59], v[210:217], 0, v133, v133 op_sel_hi:[0,0,0] cbsz:4
	v_mfma_scale_f32_16x16x128_f8f6f4 v[92:95], v[60:63], v[218:225], v[92:95], v133, v133 op_sel_hi:[0,0,0] cbsz:4
	s_nop 3
	v_mul_f32_e32 v234, v158, v64
	v_mul_f32_e32 v235, v158, v68
	v_mul_f32_e32 v236, v158, v72
	v_mul_f32_e32 v237, v158, v76
	v_fmac_f32_e32 v234, v159, v65
	v_fmac_f32_e32 v235, v159, v69
	v_fmac_f32_e32 v236, v159, v73
	v_fmac_f32_e32 v237, v159, v77
	v_fmac_f32_e32 v234, v160, v66
	v_fmac_f32_e32 v235, v160, v70
	v_fmac_f32_e32 v236, v160, v74
	v_fmac_f32_e32 v237, v160, v78
	v_fmac_f32_e32 v234, v161, v67
	v_fmac_f32_e32 v235, v161, v71
	v_fmac_f32_e32 v236, v161, v75
	v_fmac_f32_e32 v237, v161, v79
	v_add_f32_dpp v234, v234, v234 quad_perm:[1,0,3,2] row_mask:0xf bank_mask:0xf
	v_add_f32_dpp v235, v235, v235 quad_perm:[1,0,3,2] row_mask:0xf bank_mask:0xf
	v_add_f32_dpp v236, v236, v236 quad_perm:[1,0,3,2] row_mask:0xf bank_mask:0xf
	v_add_f32_dpp v237, v237, v237 quad_perm:[1,0,3,2] row_mask:0xf bank_mask:0xf
	v_add_f32_dpp v234, v234, v234 quad_perm:[2,3,0,1] row_mask:0xf bank_mask:0xf
	v_add_f32_dpp v235, v235, v235 quad_perm:[2,3,0,1] row_mask:0xf bank_mask:0xf
	v_add_f32_dpp v236, v236, v236 quad_perm:[2,3,0,1] row_mask:0xf bank_mask:0xf
	v_add_f32_dpp v237, v237, v237 quad_perm:[2,3,0,1] row_mask:0xf bank_mask:0xf
	v_add_f32_dpp v234, v234, v234 row_half_mirror row_mask:0xf bank_mask:0xf
	v_add_f32_dpp v235, v235, v235 row_half_mirror row_mask:0xf bank_mask:0xf
	v_add_f32_dpp v236, v236, v236 row_half_mirror row_mask:0xf bank_mask:0xf
	v_add_f32_dpp v237, v237, v237 row_half_mirror row_mask:0xf bank_mask:0xf
	s_mov_b32 exec_lo, 0x10001
	s_mov_b32 exec_hi, 0x10001
	ds_write_b32 v155, v234 offset:1088
	ds_write_b32 v155, v235 offset:1104
	ds_write_b32 v155, v236 offset:1120
	ds_write_b32 v155, v237 offset:1136
	s_mov_b64 exec, -1
	s_waitcnt lgkmcnt(0)
; __device__ __forceinline__ void peer_token(const Params& P, int t, int lane, int* sidx, float* sval, const int* sid, const float* sgate, const unsigned* szero) {
;     ...
;         for (int hh = 0; hh < 2; ++hh) off2[hh] = (unsigned)sid[8 * hh + (lr & 7)] * 512u + lofs;
; #pragma unroll
;         for (int hh = 0; hh < 2; ++hh)
; #pragma unroll
;             for (int st = 0; st < 4; ++st) abuf[0][hh][st] = *(const uint4*)(Ub + (off2[hh] + 128 * st));
; #pragma unroll
;         for (int T = 0; T < 8; ++T) {
;             if (T + 1 < 8) {
; #pragma unroll
;                 for (int hh = 0; hh < 2; ++hh) off2[hh] = (unsigned)sid[16 * (T + 1) + 8 * hh + (lr & 7)] * 512u + lofs;
; #pragma unroll
;                 for (int hh = 0; hh < 2; ++hh)
; #pragma unroll
;                     for (int st = 0; st < 4; ++st) abuf[(T + 1) & 1][hh][st] = *(const uint4*)(Ub + (off2[hh] + 128 * st));
;             }
; #pragma unroll
;             for (int hh = 0; hh < 2; ++hh) {
;                 f32x4 au = (f32x4){0.f, 0.f, 0.f, 0.f};
; #pragma unroll
;                 for (int st = 0; st < 4; ++st) {
;                     const uint4 a4 = abuf[T & 1][hh][st];
;                     const v8i Av = {(int)a4.x, (int)a4.y, (int)a4.z, (int)a4.w, 0, 0, 0, 0};
;                     au = __builtin_amdgcn_mfma_scale_f32_16x16x128_f8f6f4(Av, Bv[st], au, 4, 0, 0, 0x7f7f7f7f, 0, 0x7f7f7f7f);
;                 }
;                 if (owner) *(f32x4*)(sact + 16 * T + 8 * hh) = au;
;             }
	v_lshl_add_u32 v230, v230, 9, v144
	v_lshl_add_u32 v231, v231, 9, v144
	v_lshl_add_u32 v232, v232, 9, v144
	v_lshl_add_u32 v233, v233, 9, v144
	global_load_dwordx4 v[32:35], v230, s[10:11]
	global_load_dwordx4 v[36:39], v230, s[10:11] offset:256
	global_load_dwordx4 v[40:43], v231, s[10:11]
	global_load_dwordx4 v[44:47], v231, s[10:11] offset:256
	global_load_dwordx4 v[48:51], v232, s[10:11]
	global_load_dwordx4 v[52:55], v232, s[10:11] offset:256
	global_load_dwordx4 v[56:59], v233, s[10:11]
	global_load_dwordx4 v[60:63], v233, s[10:11] offset:256
	ds_read2_b32 v[96:97], v244 offset0:16 offset1:20
	ds_read2_b32 v[98:99], v244 offset0:24 offset1:28
	s_waitcnt vmcnt(8)
	v_mfma_scale_f32_16x16x128_f8f6f4 v[64:67], v[0:3], v[162:169], 0, v133, v133 op_sel_hi:[0,0,0] cbsz:4
	v_mfma_scale_f32_16x16x128_f8f6f4 v[64:67], v[4:7], v[170:177], v[64:67], v133, v133 op_sel_hi:[0,0,0] cbsz:4
	v_mfma_scale_f32_16x16x128_f8f6f4 v[68:71], v[8:11], v[162:169], 0, v133, v133 op_sel_hi:[0,0,0] cbsz:4
	v_mfma_scale_f32_16x16x128_f8f6f4 v[68:71], v[12:15], v[170:177], v[68:71], v133, v133 op_sel_hi:[0,0,0] cbsz:4
	v_mfma_scale_f32_16x16x128_f8f6f4 v[72:75], v[16:19], v[162:169], 0, v133, v133 op_sel_hi:[0,0,0] cbsz:4
	v_mfma_scale_f32_16x16x128_f8f6f4 v[72:75], v[20:23], v[170:177], v[72:75], v133, v133 op_sel_hi:[0,0,0] cbsz:4
	v_mfma_scale_f32_16x16x128_f8f6f4 v[76:79], v[24:27], v[162:169], 0, v133, v133 op_sel_hi:[0,0,0] cbsz:4
	v_mfma_scale_f32_16x16x128_f8f6f4 v[76:79], v[28:31], v[170:177], v[76:79], v133, v133 op_sel_hi:[0,0,0] cbsz:4
	s_nop 3
	v_mul_f32_e32 v234, v158, v80
	v_mul_f32_e32 v235, v158, v84
	v_mul_f32_e32 v236, v158, v88
	v_mul_f32_e32 v237, v158, v92
	v_fmac_f32_e32 v234, v159, v81
	v_fmac_f32_e32 v235, v159, v85
	v_fmac_f32_e32 v236, v159, v89
	v_fmac_f32_e32 v237, v159, v93
	v_fmac_f32_e32 v234, v160, v82
	v_fmac_f32_e32 v235, v160, v86
	v_fmac_f32_e32 v236, v160, v90
	v_fmac_f32_e32 v237, v160, v94
	v_fmac_f32_e32 v234, v161, v83
	v_fmac_f32_e32 v235, v161, v87
	v_fmac_f32_e32 v236, v161, v91
	v_fmac_f32_e32 v237, v161, v95
	v_add_f32_dpp v234, v234, v234 quad_perm:[1,0,3,2] row_mask:0xf bank_mask:0xf
	v_add_f32_dpp v235, v235, v235 quad_perm:[1,0,3,2] row_mask:0xf bank_mask:0xf
	v_add_f32_dpp v236, v236, v236 quad_perm:[1,0,3,2] row_mask:0xf bank_mask:0xf
	v_add_f32_dpp v237, v237, v237 quad_perm:[1,0,3,2] row_mask:0xf bank_mask:0xf
	v_add_f32_dpp v234, v234, v234 quad_perm:[2,3,0,1] row_mask:0xf bank_mask:0xf
	v_add_f32_dpp v235, v235, v235 quad_perm:[2,3,0,1] row_mask:0xf bank_mask:0xf
	v_add_f32_dpp v236, v236, v236 quad_perm:[2,3,0,1] row_mask:0xf bank_mask:0xf
	v_add_f32_dpp v237, v237, v237 quad_perm:[2,3,0,1] row_mask:0xf bank_mask:0xf
	v_add_f32_dpp v234, v234, v234 row_half_mirror row_mask:0xf bank_mask:0xf
	v_add_f32_dpp v235, v235, v235 row_half_mirror row_mask:0xf bank_mask:0xf
	v_add_f32_dpp v236, v236, v236 row_half_mirror row_mask:0xf bank_mask:0xf
	v_add_f32_dpp v237, v237, v237 row_half_mirror row_mask:0xf bank_mask:0xf
	s_mov_b32 exec_lo, 0x10001
	s_mov_b32 exec_hi, 0x10001
	ds_write_b32 v155, v234 offset:1600
	ds_write_b32 v155, v235 offset:1616
	ds_write_b32 v155, v236 offset:1632
	ds_write_b32 v155, v237 offset:1648
	s_mov_b64 exec, -1
	s_waitcnt lgkmcnt(0)
	v_lshl_add_u32 v96, v96, 9, v144
	v_lshl_add_u32 v97, v97, 9, v144
	v_lshl_add_u32 v98, v98, 9, v144
	v_lshl_add_u32 v99, v99, 9, v144
	global_load_dwordx4 v[0:3], v96, s[10:11]
	global_load_dwordx4 v[4:7], v96, s[10:11] offset:256
	global_load_dwordx4 v[8:11], v97, s[10:11]
	global_load_dwordx4 v[12:15], v97, s[10:11] offset:256
	global_load_dwordx4 v[16:19], v98, s[10:11]
	global_load_dwordx4 v[20:23], v98, s[10:11] offset:256
	global_load_dwordx4 v[24:27], v99, s[10:11]
	global_load_dwordx4 v[28:31], v99, s[10:11] offset:256
	ds_read2_b32 v[230:231], v245 offset0:16 offset1:20
	ds_read2_b32 v[232:233], v245 offset0:24 offset1:28
	s_waitcnt vmcnt(8)
	v_mfma_scale_f32_16x16x128_f8f6f4 v[80:83], v[32:35], v[178:185], 0, v133, v133 op_sel_hi:[0,0,0] cbsz:4
	v_mfma_scale_f32_16x16x128_f8f6f4 v[80:83], v[36:39], v[186:193], v[80:83], v133, v133 op_sel_hi:[0,0,0] cbsz:4
	v_mfma_scale_f32_16x16x128_f8f6f4 v[84:87], v[40:43], v[178:185], 0, v133, v133 op_sel_hi:[0,0,0] cbsz:4
	v_mfma_scale_f32_16x16x128_f8f6f4 v[84:87], v[44:47], v[186:193], v[84:87], v133, v133 op_sel_hi:[0,0,0] cbsz:4
	v_mfma_scale_f32_16x16x128_f8f6f4 v[88:91], v[48:51], v[178:185], 0, v133, v133 op_sel_hi:[0,0,0] cbsz:4
	v_mfma_scale_f32_16x16x128_f8f6f4 v[88:91], v[52:55], v[186:193], v[88:91], v133, v133 op_sel_hi:[0,0,0] cbsz:4
	v_mfma_scale_f32_16x16x128_f8f6f4 v[92:95], v[56:59], v[178:185], 0, v133, v133 op_sel_hi:[0,0,0] cbsz:4
	v_mfma_scale_f32_16x16x128_f8f6f4 v[92:95], v[60:63], v[186:193], v[92:95], v133, v133 op_sel_hi:[0,0,0] cbsz:4
	s_nop 3
	v_mul_f32_e32 v234, v226, v64
	v_mul_f32_e32 v235, v226, v68
	v_mul_f32_e32 v236, v226, v72
	v_mul_f32_e32 v237, v226, v76
	v_fmac_f32_e32 v234, v227, v65
	v_fmac_f32_e32 v235, v227, v69
	v_fmac_f32_e32 v236, v227, v73
	v_fmac_f32_e32 v237, v227, v77
	v_fmac_f32_e32 v234, v228, v66
	v_fmac_f32_e32 v235, v228, v70
	v_fmac_f32_e32 v236, v228, v74
	v_fmac_f32_e32 v237, v228, v78
	v_fmac_f32_e32 v234, v229, v67
	v_fmac_f32_e32 v235, v229, v71
	v_fmac_f32_e32 v236, v229, v75
	v_fmac_f32_e32 v237, v229, v79
	v_add_f32_dpp v234, v234, v234 quad_perm:[1,0,3,2] row_mask:0xf bank_mask:0xf
	v_add_f32_dpp v235, v235, v235 quad_perm:[1,0,3,2] row_mask:0xf bank_mask:0xf
	v_add_f32_dpp v236, v236, v236 quad_perm:[1,0,3,2] row_mask:0xf bank_mask:0xf
	v_add_f32_dpp v237, v237, v237 quad_perm:[1,0,3,2] row_mask:0xf bank_mask:0xf
	v_add_f32_dpp v234, v234, v234 quad_perm:[2,3,0,1] row_mask:0xf bank_mask:0xf
	v_add_f32_dpp v235, v235, v235 quad_perm:[2,3,0,1] row_mask:0xf bank_mask:0xf
	v_add_f32_dpp v236, v236, v236 quad_perm:[2,3,0,1] row_mask:0xf bank_mask:0xf
	v_add_f32_dpp v237, v237, v237 quad_perm:[2,3,0,1] row_mask:0xf bank_mask:0xf
	v_add_f32_dpp v234, v234, v234 row_half_mirror row_mask:0xf bank_mask:0xf
	v_add_f32_dpp v235, v235, v235 row_half_mirror row_mask:0xf bank_mask:0xf
	v_add_f32_dpp v236, v236, v236 row_half_mirror row_mask:0xf bank_mask:0xf
	v_add_f32_dpp v237, v237, v237 row_half_mirror row_mask:0xf bank_mask:0xf
	s_mov_b32 exec_lo, 0x1000100
	s_mov_b32 exec_hi, 0x1000100
	ds_write_b32 v155, v234 offset:2112
	ds_write_b32 v155, v235 offset:2128
	ds_write_b32 v155, v236 offset:2144
	ds_write_b32 v155, v237 offset:2160
	s_mov_b64 exec, -1
	s_waitcnt lgkmcnt(0)
; __device__ __forceinline__ void peer_token(const Params& P, int t, int lane, int* sidx, float* sval, const int* sid, const float* sgate, const unsigned* szero) {
;     ...
;         for (int hh = 0; hh < 2; ++hh) off2[hh] = (unsigned)sid[8 * hh + (lr & 7)] * 512u + lofs;
; #pragma unroll
;         for (int hh = 0; hh < 2; ++hh)
; #pragma unroll
;             for (int st = 0; st < 4; ++st) abuf[0][hh][st] = *(const uint4*)(Ub + (off2[hh] + 128 * st));
; #pragma unroll
;         for (int T = 0; T < 8; ++T) {
;             if (T + 1 < 8) {
; #pragma unroll
;                 for (int hh = 0; hh < 2; ++hh) off2[hh] = (unsigned)sid[16 * (T + 1) + 8 * hh + (lr & 7)] * 512u + lofs;
; #pragma unroll
;                 for (int hh = 0; hh < 2; ++hh)
; #pragma unroll
;                     for (int st = 0; st < 4; ++st) abuf[(T + 1) & 1][hh][st] = *(const uint4*)(Ub + (off2[hh] + 128 * st));
;             }
; #pragma unroll
;             for (int hh = 0; hh < 2; ++hh) {
;                 f32x4 au = (f32x4){0.f, 0.f, 0.f, 0.f};
; #pragma unroll
;                 for (int st = 0; st < 4; ++st) {
;                     const uint4 a4 = abuf[T & 1][hh][st];
;                     const v8i Av = {(int)a4.x, (int)a4.y, (int)a4.z, (int)a4.w, 0, 0, 0, 0};
;                     au = __builtin_amdgcn_mfma_scale_f32_16x16x128_f8f6f4(Av, Bv[st], au, 4, 0, 0, 0x7f7f7f7f, 0, 0x7f7f7f7f);
;                 }
;                 if (owner) *(f32x4*)(sact + 16 * T + 8 * hh) = au;
;             }
	v_lshl_add_u32 v230, v230, 9, v144
	v_lshl_add_u32 v231, v231, 9, v144
	v_lshl_add_u32 v232, v232, 9, v144
	v_lshl_add_u32 v233, v233, 9, v144
	global_load_dwordx4 v[32:35], v230, s[10:11]
	global_load_dwordx4 v[36:39], v230, s[10:11] offset:256
	global_load_dwordx4 v[40:43], v231, s[10:11]
	global_load_dwordx4 v[44:47], v231, s[10:11] offset:256
	global_load_dwordx4 v[48:51], v232, s[10:11]
	global_load_dwordx4 v[52:55], v232, s[10:11] offset:256
	global_load_dwordx4 v[56:59], v233, s[10:11]
	global_load_dwordx4 v[60:63], v233, s[10:11] offset:256
	ds_read2_b32 v[96:97], v238 offset0:32 offset1:36
	ds_read2_b32 v[98:99], v238 offset0:40 offset1:44
	s_waitcnt vmcnt(8)
	v_mfma_scale_f32_16x16x128_f8f6f4 v[64:67], v[0:3], v[194:201], 0, v133, v133 op_sel_hi:[0,0,0] cbsz:4
	v_mfma_scale_f32_16x16x128_f8f6f4 v[64:67], v[4:7], v[202:209], v[64:67], v133, v133 op_sel_hi:[0,0,0] cbsz:4
	v_mfma_scale_f32_16x16x128_f8f6f4 v[68:71], v[8:11], v[194:201], 0, v133, v133 op_sel_hi:[0,0,0] cbsz:4
	v_mfma_scale_f32_16x16x128_f8f6f4 v[68:71], v[12:15], v[202:209], v[68:71], v133, v133 op_sel_hi:[0,0,0] cbsz:4
	v_mfma_scale_f32_16x16x128_f8f6f4 v[72:75], v[16:19], v[194:201], 0, v133, v133 op_sel_hi:[0,0,0] cbsz:4
	v_mfma_scale_f32_16x16x128_f8f6f4 v[72:75], v[20:23], v[202:209], v[72:75], v133, v133 op_sel_hi:[0,0,0] cbsz:4
	v_mfma_scale_f32_16x16x128_f8f6f4 v[76:79], v[24:27], v[194:201], 0, v133, v133 op_sel_hi:[0,0,0] cbsz:4
	v_mfma_scale_f32_16x16x128_f8f6f4 v[76:79], v[28:31], v[202:209], v[76:79], v133, v133 op_sel_hi:[0,0,0] cbsz:4
	s_nop 3
	v_mul_f32_e32 v234, v226, v80
	v_mul_f32_e32 v235, v226, v84
	v_mul_f32_e32 v236, v226, v88
	v_mul_f32_e32 v237, v226, v92
	v_fmac_f32_e32 v234, v227, v81
	v_fmac_f32_e32 v235, v227, v85
	v_fmac_f32_e32 v236, v227, v89
	v_fmac_f32_e32 v237, v227, v93
	v_fmac_f32_e32 v234, v228, v82
	v_fmac_f32_e32 v235, v228, v86
	v_fmac_f32_e32 v236, v228, v90
	v_fmac_f32_e32 v237, v228, v94
	v_fmac_f32_e32 v234, v229, v83
	v_fmac_f32_e32 v235, v229, v87
	v_fmac_f32_e32 v236, v229, v91
	v_fmac_f32_e32 v237, v229, v95
	v_add_f32_dpp v234, v234, v234 quad_perm:[1,0,3,2] row_mask:0xf bank_mask:0xf
	v_add_f32_dpp v235, v235, v235 quad_perm:[1,0,3,2] row_mask:0xf bank_mask:0xf
	v_add_f32_dpp v236, v236, v236 quad_perm:[1,0,3,2] row_mask:0xf bank_mask:0xf
	v_add_f32_dpp v237, v237, v237 quad_perm:[1,0,3,2] row_mask:0xf bank_mask:0xf
	v_add_f32_dpp v234, v234, v234 quad_perm:[2,3,0,1] row_mask:0xf bank_mask:0xf
	v_add_f32_dpp v235, v235, v235 quad_perm:[2,3,0,1] row_mask:0xf bank_mask:0xf
	v_add_f32_dpp v236, v236, v236 quad_perm:[2,3,0,1] row_mask:0xf bank_mask:0xf
	v_add_f32_dpp v237, v237, v237 quad_perm:[2,3,0,1] row_mask:0xf bank_mask:0xf
	v_add_f32_dpp v234, v234, v234 row_half_mirror row_mask:0xf bank_mask:0xf
	v_add_f32_dpp v235, v235, v235 row_half_mirror row_mask:0xf bank_mask:0xf
	v_add_f32_dpp v236, v236, v236 row_half_mirror row_mask:0xf bank_mask:0xf
	v_add_f32_dpp v237, v237, v237 row_half_mirror row_mask:0xf bank_mask:0xf
	s_mov_b32 exec_lo, 0x1000100
	s_mov_b32 exec_hi, 0x1000100
	ds_write_b32 v155, v234 offset:2624
	ds_write_b32 v155, v235 offset:2640
	ds_write_b32 v155, v236 offset:2656
	ds_write_b32 v155, v237 offset:2672
	s_mov_b64 exec, -1
	s_waitcnt lgkmcnt(0)
	v_lshl_add_u32 v96, v96, 9, v144
	v_lshl_add_u32 v97, v97, 9, v144
	v_lshl_add_u32 v98, v98, 9, v144
	v_lshl_add_u32 v99, v99, 9, v144
	global_load_dwordx4 v[0:3], v96, s[10:11]
	global_load_dwordx4 v[4:7], v96, s[10:11] offset:256
	global_load_dwordx4 v[8:11], v97, s[10:11]
	global_load_dwordx4 v[12:15], v97, s[10:11] offset:256
	global_load_dwordx4 v[16:19], v98, s[10:11]
	global_load_dwordx4 v[20:23], v98, s[10:11] offset:256
	global_load_dwordx4 v[24:27], v99, s[10:11]
	global_load_dwordx4 v[28:31], v99, s[10:11] offset:256
	ds_read2_b32 v[230:231], v239 offset0:32 offset1:36
	ds_read2_b32 v[232:233], v239 offset0:40 offset1:44
	s_waitcnt vmcnt(8)
	v_mfma_scale_f32_16x16x128_f8f6f4 v[80:83], v[32:35], v[210:217], 0, v133, v133 op_sel_hi:[0,0,0] cbsz:4
	v_mfma_scale_f32_16x16x128_f8f6f4 v[80:83], v[36:39], v[218:225], v[80:83], v133, v133 op_sel_hi:[0,0,0] cbsz:4
	v_mfma_scale_f32_16x16x128_f8f6f4 v[84:87], v[40:43], v[210:217], 0, v133, v133 op_sel_hi:[0,0,0] cbsz:4
	v_mfma_scale_f32_16x16x128_f8f6f4 v[84:87], v[44:47], v[218:225], v[84:87], v133, v133 op_sel_hi:[0,0,0] cbsz:4
	v_mfma_scale_f32_16x16x128_f8f6f4 v[88:91], v[48:51], v[210:217], 0, v133, v133 op_sel_hi:[0,0,0] cbsz:4
	v_mfma_scale_f32_16x16x128_f8f6f4 v[88:91], v[52:55], v[218:225], v[88:91], v133, v133 op_sel_hi:[0,0,0] cbsz:4
	v_mfma_scale_f32_16x16x128_f8f6f4 v[92:95], v[56:59], v[210:217], 0, v133, v133 op_sel_hi:[0,0,0] cbsz:4
	v_mfma_scale_f32_16x16x128_f8f6f4 v[92:95], v[60:63], v[218:225], v[92:95], v133, v133 op_sel_hi:[0,0,0] cbsz:4
	s_nop 3
	v_mul_f32_e32 v234, v226, v64
	v_mul_f32_e32 v235, v226, v68
	v_mul_f32_e32 v236, v226, v72
	v_mul_f32_e32 v237, v226, v76
	v_fmac_f32_e32 v234, v227, v65
	v_fmac_f32_e32 v235, v227, v69
	v_fmac_f32_e32 v236, v227, v73
	v_fmac_f32_e32 v237, v227, v77
	v_fmac_f32_e32 v234, v228, v66
	v_fmac_f32_e32 v235, v228, v70
	v_fmac_f32_e32 v236, v228, v74
	v_fmac_f32_e32 v237, v228, v78
	v_fmac_f32_e32 v234, v229, v67
	v_fmac_f32_e32 v235, v229, v71
	v_fmac_f32_e32 v236, v229, v75
	v_fmac_f32_e32 v237, v229, v79
	v_add_f32_dpp v234, v234, v234 quad_perm:[1,0,3,2] row_mask:0xf bank_mask:0xf
	v_add_f32_dpp v235, v235, v235 quad_perm:[1,0,3,2] row_mask:0xf bank_mask:0xf
	v_add_f32_dpp v236, v236, v236 quad_perm:[1,0,3,2] row_mask:0xf bank_mask:0xf
	v_add_f32_dpp v237, v237, v237 quad_perm:[1,0,3,2] row_mask:0xf bank_mask:0xf
	v_add_f32_dpp v234, v234, v234 quad_perm:[2,3,0,1] row_mask:0xf bank_mask:0xf
	v_add_f32_dpp v235, v235, v235 quad_perm:[2,3,0,1] row_mask:0xf bank_mask:0xf
	v_add_f32_dpp v236, v236, v236 quad_perm:[2,3,0,1] row_mask:0xf bank_mask:0xf
	v_add_f32_dpp v237, v237, v237 quad_perm:[2,3,0,1] row_mask:0xf bank_mask:0xf
	v_add_f32_dpp v234, v234, v234 row_half_mirror row_mask:0xf bank_mask:0xf
	v_add_f32_dpp v235, v235, v235 row_half_mirror row_mask:0xf bank_mask:0xf
	v_add_f32_dpp v236, v236, v236 row_half_mirror row_mask:0xf bank_mask:0xf
	v_add_f32_dpp v237, v237, v237 row_half_mirror row_mask:0xf bank_mask:0xf
	s_mov_b32 exec_lo, 0x1000100
	s_mov_b32 exec_hi, 0x1000100
	ds_write_b32 v155, v234 offset:3136
	ds_write_b32 v155, v235 offset:3152
	ds_write_b32 v155, v236 offset:3168
	ds_write_b32 v155, v237 offset:3184
	s_mov_b64 exec, -1
	s_waitcnt lgkmcnt(0)
; __device__ __forceinline__ void peer_token(const Params& P, int t, int lane, int* sidx, float* sval, const int* sid, const float* sgate, const unsigned* szero) {
;     ...
;         for (int hh = 0; hh < 2; ++hh) off2[hh] = (unsigned)sid[8 * hh + (lr & 7)] * 512u + lofs;
; #pragma unroll
;         for (int hh = 0; hh < 2; ++hh)
; #pragma unroll
;             for (int st = 0; st < 4; ++st) abuf[0][hh][st] = *(const uint4*)(Ub + (off2[hh] + 128 * st));
; #pragma unroll
;         for (int T = 0; T < 8; ++T) {
;             if (T + 1 < 8) {
; #pragma unroll
;                 for (int hh = 0; hh < 2; ++hh) off2[hh] = (unsigned)sid[16 * (T + 1) + 8 * hh + (lr & 7)] * 512u + lofs;
; #pragma unroll
;                 for (int hh = 0; hh < 2; ++hh)
; #pragma unroll
;                     for (int st = 0; st < 4; ++st) abuf[(T + 1) & 1][hh][st] = *(const uint4*)(Ub + (off2[hh] + 128 * st));
;             }
; #pragma unroll
;             for (int hh = 0; hh < 2; ++hh) {
;                 f32x4 au = (f32x4){0.f, 0.f, 0.f, 0.f};
; #pragma unroll
;                 for (int st = 0; st < 4; ++st) {
;                     const uint4 a4 = abuf[T & 1][hh][st];
;                     const v8i Av = {(int)a4.x, (int)a4.y, (int)a4.z, (int)a4.w, 0, 0, 0, 0};
;                     au = __builtin_amdgcn_mfma_scale_f32_16x16x128_f8f6f4(Av, Bv[st], au, 4, 0, 0, 0x7f7f7f7f, 0, 0x7f7f7f7f);
;                 }
;                 if (owner) *(f32x4*)(sact + 16 * T + 8 * hh) = au;
;             }
	v_lshl_add_u32 v230, v230, 9, v144
	v_lshl_add_u32 v231, v231, 9, v144
	v_lshl_add_u32 v232, v232, 9, v144
	v_lshl_add_u32 v233, v233, 9, v144
	global_load_dwordx4 v[32:35], v230, s[10:11]
	global_load_dwordx4 v[36:39], v230, s[10:11] offset:256
	global_load_dwordx4 v[40:43], v231, s[10:11]
	global_load_dwordx4 v[44:47], v231, s[10:11] offset:256
	global_load_dwordx4 v[48:51], v232, s[10:11]
	global_load_dwordx4 v[52:55], v232, s[10:11] offset:256
	global_load_dwordx4 v[56:59], v233, s[10:11]
	global_load_dwordx4 v[60:63], v233, s[10:11] offset:256
	ds_read2_b32 v[96:97], v240 offset0:32 offset1:36
	ds_read2_b32 v[98:99], v240 offset0:40 offset1:44
	s_waitcnt vmcnt(8)
	v_mfma_scale_f32_16x16x128_f8f6f4 v[64:67], v[0:3], v[162:169], 0, v133, v133 op_sel_hi:[0,0,0] cbsz:4
	v_mfma_scale_f32_16x16x128_f8f6f4 v[64:67], v[4:7], v[170:177], v[64:67], v133, v133 op_sel_hi:[0,0,0] cbsz:4
	v_mfma_scale_f32_16x16x128_f8f6f4 v[68:71], v[8:11], v[162:169], 0, v133, v133 op_sel_hi:[0,0,0] cbsz:4
	v_mfma_scale_f32_16x16x128_f8f6f4 v[68:71], v[12:15], v[170:177], v[68:71], v133, v133 op_sel_hi:[0,0,0] cbsz:4
	v_mfma_scale_f32_16x16x128_f8f6f4 v[72:75], v[16:19], v[162:169], 0, v133, v133 op_sel_hi:[0,0,0] cbsz:4
	v_mfma_scale_f32_16x16x128_f8f6f4 v[72:75], v[20:23], v[170:177], v[72:75], v133, v133 op_sel_hi:[0,0,0] cbsz:4
	v_mfma_scale_f32_16x16x128_f8f6f4 v[76:79], v[24:27], v[162:169], 0, v133, v133 op_sel_hi:[0,0,0] cbsz:4
	v_mfma_scale_f32_16x16x128_f8f6f4 v[76:79], v[28:31], v[170:177], v[76:79], v133, v133 op_sel_hi:[0,0,0] cbsz:4
	s_nop 3
	v_mul_f32_e32 v234, v226, v80
	v_mul_f32_e32 v235, v226, v84
	v_mul_f32_e32 v236, v226, v88
	v_mul_f32_e32 v237, v226, v92
	v_fmac_f32_e32 v234, v227, v81
	v_fmac_f32_e32 v235, v227, v85
	v_fmac_f32_e32 v236, v227, v89
	v_fmac_f32_e32 v237, v227, v93
	v_fmac_f32_e32 v234, v228, v82
	v_fmac_f32_e32 v235, v228, v86
	v_fmac_f32_e32 v236, v228, v90
	v_fmac_f32_e32 v237, v228, v94
	v_fmac_f32_e32 v234, v229, v83
	v_fmac_f32_e32 v235, v229, v87
	v_fmac_f32_e32 v236, v229, v91
	v_fmac_f32_e32 v237, v229, v95
	v_add_f32_dpp v234, v234, v234 quad_perm:[1,0,3,2] row_mask:0xf bank_mask:0xf
	v_add_f32_dpp v235, v235, v235 quad_perm:[1,0,3,2] row_mask:0xf bank_mask:0xf
	v_add_f32_dpp v236, v236, v236 quad_perm:[1,0,3,2] row_mask:0xf bank_mask:0xf
	v_add_f32_dpp v237, v237, v237 quad_perm:[1,0,3,2] row_mask:0xf bank_mask:0xf
	v_add_f32_dpp v234, v234, v234 quad_perm:[2,3,0,1] row_mask:0xf bank_mask:0xf
	v_add_f32_dpp v235, v235, v235 quad_perm:[2,3,0,1] row_mask:0xf bank_mask:0xf
	v_add_f32_dpp v236, v236, v236 quad_perm:[2,3,0,1] row_mask:0xf bank_mask:0xf
	v_add_f32_dpp v237, v237, v237 quad_perm:[2,3,0,1] row_mask:0xf bank_mask:0xf
	v_add_f32_dpp v234, v234, v234 row_half_mirror row_mask:0xf bank_mask:0xf
	v_add_f32_dpp v235, v235, v235 row_half_mirror row_mask:0xf bank_mask:0xf
	v_add_f32_dpp v236, v236, v236 row_half_mirror row_mask:0xf bank_mask:0xf
	v_add_f32_dpp v237, v237, v237 row_half_mirror row_mask:0xf bank_mask:0xf
	s_mov_b32 exec_lo, 0x1000100
	s_mov_b32 exec_hi, 0x1000100
	ds_write_b32 v155, v234 offset:3648
	ds_write_b32 v155, v235 offset:3664
	ds_write_b32 v155, v236 offset:3680
	ds_write_b32 v155, v237 offset:3696
	s_mov_b64 exec, -1
	s_waitcnt lgkmcnt(0)
	v_lshl_add_u32 v96, v96, 9, v144
	v_lshl_add_u32 v97, v97, 9, v144
	v_lshl_add_u32 v98, v98, 9, v144
	v_lshl_add_u32 v99, v99, 9, v144
	global_load_dwordx4 v[0:3], v96, s[10:11]
	global_load_dwordx4 v[4:7], v96, s[10:11] offset:256
	global_load_dwordx4 v[8:11], v97, s[10:11]
	global_load_dwordx4 v[12:15], v97, s[10:11] offset:256
	global_load_dwordx4 v[16:19], v98, s[10:11]
	global_load_dwordx4 v[20:23], v98, s[10:11] offset:256
	global_load_dwordx4 v[24:27], v99, s[10:11]
	global_load_dwordx4 v[28:31], v99, s[10:11] offset:256
	ds_read2_b32 v[230:231], v241 offset0:32 offset1:36
	ds_read2_b32 v[232:233], v241 offset0:40 offset1:44
	s_waitcnt vmcnt(8)
	v_mfma_scale_f32_16x16x128_f8f6f4 v[80:83], v[32:35], v[178:185], 0, v133, v133 op_sel_hi:[0,0,0] cbsz:4
	v_mfma_scale_f32_16x16x128_f8f6f4 v[80:83], v[36:39], v[186:193], v[80:83], v133, v133 op_sel_hi:[0,0,0] cbsz:4
	v_mfma_scale_f32_16x16x128_f8f6f4 v[84:87], v[40:43], v[178:185], 0, v133, v133 op_sel_hi:[0,0,0] cbsz:4
	v_mfma_scale_f32_16x16x128_f8f6f4 v[84:87], v[44:47], v[186:193], v[84:87], v133, v133 op_sel_hi:[0,0,0] cbsz:4
	v_mfma_scale_f32_16x16x128_f8f6f4 v[88:91], v[48:51], v[178:185], 0, v133, v133 op_sel_hi:[0,0,0] cbsz:4
	v_mfma_scale_f32_16x16x128_f8f6f4 v[88:91], v[52:55], v[186:193], v[88:91], v133, v133 op_sel_hi:[0,0,0] cbsz:4
	v_mfma_scale_f32_16x16x128_f8f6f4 v[92:95], v[56:59], v[178:185], 0, v133, v133 op_sel_hi:[0,0,0] cbsz:4
	v_mfma_scale_f32_16x16x128_f8f6f4 v[92:95], v[60:63], v[186:193], v[92:95], v133, v133 op_sel_hi:[0,0,0] cbsz:4
	s_nop 3
	v_mul_f32_e32 v234, v158, v64
	v_mul_f32_e32 v235, v158, v68
	v_mul_f32_e32 v236, v158, v72
	v_mul_f32_e32 v237, v158, v76
	v_fmac_f32_e32 v234, v159, v65
	v_fmac_f32_e32 v235, v159, v69
	v_fmac_f32_e32 v236, v159, v73
	v_fmac_f32_e32 v237, v159, v77
	v_fmac_f32_e32 v234, v160, v66
	v_fmac_f32_e32 v235, v160, v70
	v_fmac_f32_e32 v236, v160, v74
	v_fmac_f32_e32 v237, v160, v78
	v_fmac_f32_e32 v234, v161, v67
	v_fmac_f32_e32 v235, v161, v71
	v_fmac_f32_e32 v236, v161, v75
	v_fmac_f32_e32 v237, v161, v79
	v_add_f32_dpp v234, v234, v234 quad_perm:[1,0,3,2] row_mask:0xf bank_mask:0xf
	v_add_f32_dpp v235, v235, v235 quad_perm:[1,0,3,2] row_mask:0xf bank_mask:0xf
	v_add_f32_dpp v236, v236, v236 quad_perm:[1,0,3,2] row_mask:0xf bank_mask:0xf
	v_add_f32_dpp v237, v237, v237 quad_perm:[1,0,3,2] row_mask:0xf bank_mask:0xf
	v_add_f32_dpp v234, v234, v234 quad_perm:[2,3,0,1] row_mask:0xf bank_mask:0xf
	v_add_f32_dpp v235, v235, v235 quad_perm:[2,3,0,1] row_mask:0xf bank_mask:0xf
	v_add_f32_dpp v236, v236, v236 quad_perm:[2,3,0,1] row_mask:0xf bank_mask:0xf
	v_add_f32_dpp v237, v237, v237 quad_perm:[2,3,0,1] row_mask:0xf bank_mask:0xf
	v_add_f32_dpp v234, v234, v234 row_half_mirror row_mask:0xf bank_mask:0xf
	v_add_f32_dpp v235, v235, v235 row_half_mirror row_mask:0xf bank_mask:0xf
	v_add_f32_dpp v236, v236, v236 row_half_mirror row_mask:0xf bank_mask:0xf
	v_add_f32_dpp v237, v237, v237 row_half_mirror row_mask:0xf bank_mask:0xf
	s_mov_b32 exec_lo, 0x10001
	s_mov_b32 exec_hi, 0x10001
	ds_write_b32 v155, v234 offset:128
	ds_write_b32 v155, v235 offset:144
	ds_write_b32 v155, v236 offset:160
	ds_write_b32 v155, v237 offset:176
	s_mov_b64 exec, -1
	s_waitcnt lgkmcnt(0)
; __device__ __forceinline__ void peer_token(const Params& P, int t, int lane, int* sidx, float* sval, const int* sid, const float* sgate, const unsigned* szero) {
;     ...
;         for (int hh = 0; hh < 2; ++hh) off2[hh] = (unsigned)sid[8 * hh + (lr & 7)] * 512u + lofs;
; #pragma unroll
;         for (int hh = 0; hh < 2; ++hh)
; #pragma unroll
;             for (int st = 0; st < 4; ++st) abuf[0][hh][st] = *(const uint4*)(Ub + (off2[hh] + 128 * st));
; #pragma unroll
;         for (int T = 0; T < 8; ++T) {
;             if (T + 1 < 8) {
; #pragma unroll
;                 for (int hh = 0; hh < 2; ++hh) off2[hh] = (unsigned)sid[16 * (T + 1) + 8 * hh + (lr & 7)] * 512u + lofs;
; #pragma unroll
;                 for (int hh = 0; hh < 2; ++hh)
; #pragma unroll
;                     for (int st = 0; st < 4; ++st) abuf[(T + 1) & 1][hh][st] = *(const uint4*)(Ub + (off2[hh] + 128 * st));
;             }
; #pragma unroll
;             for (int hh = 0; hh < 2; ++hh) {
;                 f32x4 au = (f32x4){0.f, 0.f, 0.f, 0.f};
; #pragma unroll
;                 for (int st = 0; st < 4; ++st) {
;                     const uint4 a4 = abuf[T & 1][hh][st];
;                     const v8i Av = {(int)a4.x, (int)a4.y, (int)a4.z, (int)a4.w, 0, 0, 0, 0};
;                     au = __builtin_amdgcn_mfma_scale_f32_16x16x128_f8f6f4(Av, Bv[st], au, 4, 0, 0, 0x7f7f7f7f, 0, 0x7f7f7f7f);
;                 }
;                 if (owner) *(f32x4*)(sact + 16 * T + 8 * hh) = au;
;             }
	v_lshl_add_u32 v230, v230, 9, v144
	v_lshl_add_u32 v231, v231, 9, v144
	v_lshl_add_u32 v232, v232, 9, v144
	v_lshl_add_u32 v233, v233, 9, v144
	global_load_dwordx4 v[32:35], v230, s[10:11]
	global_load_dwordx4 v[36:39], v230, s[10:11] offset:256
	global_load_dwordx4 v[40:43], v231, s[10:11]
	global_load_dwordx4 v[44:47], v231, s[10:11] offset:256
	global_load_dwordx4 v[48:51], v232, s[10:11]
	global_load_dwordx4 v[52:55], v232, s[10:11] offset:256
	global_load_dwordx4 v[56:59], v233, s[10:11]
	global_load_dwordx4 v[60:63], v233, s[10:11] offset:256
	ds_read2_b32 v[96:97], v242 offset0:32 offset1:36
	ds_read2_b32 v[98:99], v242 offset0:40 offset1:44
	s_waitcnt vmcnt(8)
	v_mfma_scale_f32_16x16x128_f8f6f4 v[64:67], v[0:3], v[194:201], 0, v133, v133 op_sel_hi:[0,0,0] cbsz:4
	v_mfma_scale_f32_16x16x128_f8f6f4 v[64:67], v[4:7], v[202:209], v[64:67], v133, v133 op_sel_hi:[0,0,0] cbsz:4
	v_mfma_scale_f32_16x16x128_f8f6f4 v[68:71], v[8:11], v[194:201], 0, v133, v133 op_sel_hi:[0,0,0] cbsz:4
	v_mfma_scale_f32_16x16x128_f8f6f4 v[68:71], v[12:15], v[202:209], v[68:71], v133, v133 op_sel_hi:[0,0,0] cbsz:4
	v_mfma_scale_f32_16x16x128_f8f6f4 v[72:75], v[16:19], v[194:201], 0, v133, v133 op_sel_hi:[0,0,0] cbsz:4
	v_mfma_scale_f32_16x16x128_f8f6f4 v[72:75], v[20:23], v[202:209], v[72:75], v133, v133 op_sel_hi:[0,0,0] cbsz:4
	v_mfma_scale_f32_16x16x128_f8f6f4 v[76:79], v[24:27], v[194:201], 0, v133, v133 op_sel_hi:[0,0,0] cbsz:4
	v_mfma_scale_f32_16x16x128_f8f6f4 v[76:79], v[28:31], v[202:209], v[76:79], v133, v133 op_sel_hi:[0,0,0] cbsz:4
	s_nop 3
	v_mul_f32_e32 v234, v158, v80
	v_mul_f32_e32 v235, v158, v84
	v_mul_f32_e32 v236, v158, v88
	v_mul_f32_e32 v237, v158, v92
	v_fmac_f32_e32 v234, v159, v81
	v_fmac_f32_e32 v235, v159, v85
	v_fmac_f32_e32 v236, v159, v89
	v_fmac_f32_e32 v237, v159, v93
	v_fmac_f32_e32 v234, v160, v82
	v_fmac_f32_e32 v235, v160, v86
	v_fmac_f32_e32 v236, v160, v90
	v_fmac_f32_e32 v237, v160, v94
	v_fmac_f32_e32 v234, v161, v83
	v_fmac_f32_e32 v235, v161, v87
	v_fmac_f32_e32 v236, v161, v91
	v_fmac_f32_e32 v237, v161, v95
	v_add_f32_dpp v234, v234, v234 quad_perm:[1,0,3,2] row_mask:0xf bank_mask:0xf
	v_add_f32_dpp v235, v235, v235 quad_perm:[1,0,3,2] row_mask:0xf bank_mask:0xf
	v_add_f32_dpp v236, v236, v236 quad_perm:[1,0,3,2] row_mask:0xf bank_mask:0xf
	v_add_f32_dpp v237, v237, v237 quad_perm:[1,0,3,2] row_mask:0xf bank_mask:0xf
	v_add_f32_dpp v234, v234, v234 quad_perm:[2,3,0,1] row_mask:0xf bank_mask:0xf
	v_add_f32_dpp v235, v235, v235 quad_perm:[2,3,0,1] row_mask:0xf bank_mask:0xf
	v_add_f32_dpp v236, v236, v236 quad_perm:[2,3,0,1] row_mask:0xf bank_mask:0xf
	v_add_f32_dpp v237, v237, v237 quad_perm:[2,3,0,1] row_mask:0xf bank_mask:0xf
	v_add_f32_dpp v234, v234, v234 row_half_mirror row_mask:0xf bank_mask:0xf
	v_add_f32_dpp v235, v235, v235 row_half_mirror row_mask:0xf bank_mask:0xf
	v_add_f32_dpp v236, v236, v236 row_half_mirror row_mask:0xf bank_mask:0xf
	v_add_f32_dpp v237, v237, v237 row_half_mirror row_mask:0xf bank_mask:0xf
	s_mov_b32 exec_lo, 0x10001
	s_mov_b32 exec_hi, 0x10001
	ds_write_b32 v155, v234 offset:640
	ds_write_b32 v155, v235 offset:656
	ds_write_b32 v155, v236 offset:672
	ds_write_b32 v155, v237 offset:688
	s_mov_b64 exec, -1
	s_waitcnt lgkmcnt(0)
	v_lshl_add_u32 v96, v96, 9, v144
	v_lshl_add_u32 v97, v97, 9, v144
	v_lshl_add_u32 v98, v98, 9, v144
	v_lshl_add_u32 v99, v99, 9, v144
	global_load_dwordx4 v[0:3], v96, s[10:11]
	global_load_dwordx4 v[4:7], v96, s[10:11] offset:256
	global_load_dwordx4 v[8:11], v97, s[10:11]
	global_load_dwordx4 v[12:15], v97, s[10:11] offset:256
	global_load_dwordx4 v[16:19], v98, s[10:11]
	global_load_dwordx4 v[20:23], v98, s[10:11] offset:256
	global_load_dwordx4 v[24:27], v99, s[10:11]
	global_load_dwordx4 v[28:31], v99, s[10:11] offset:256
	ds_read2_b32 v[230:231], v243 offset0:32 offset1:36
	ds_read2_b32 v[232:233], v243 offset0:40 offset1:44
	s_waitcnt vmcnt(8)
	v_mfma_scale_f32_16x16x128_f8f6f4 v[80:83], v[32:35], v[210:217], 0, v133, v133 op_sel_hi:[0,0,0] cbsz:4
	v_mfma_scale_f32_16x16x128_f8f6f4 v[80:83], v[36:39], v[218:225], v[80:83], v133, v133 op_sel_hi:[0,0,0] cbsz:4
	v_mfma_scale_f32_16x16x128_f8f6f4 v[84:87], v[40:43], v[210:217], 0, v133, v133 op_sel_hi:[0,0,0] cbsz:4
	v_mfma_scale_f32_16x16x128_f8f6f4 v[84:87], v[44:47], v[218:225], v[84:87], v133, v133 op_sel_hi:[0,0,0] cbsz:4
	v_mfma_scale_f32_16x16x128_f8f6f4 v[88:91], v[48:51], v[210:217], 0, v133, v133 op_sel_hi:[0,0,0] cbsz:4
	v_mfma_scale_f32_16x16x128_f8f6f4 v[88:91], v[52:55], v[218:225], v[88:91], v133, v133 op_sel_hi:[0,0,0] cbsz:4
	v_mfma_scale_f32_16x16x128_f8f6f4 v[92:95], v[56:59], v[210:217], 0, v133, v133 op_sel_hi:[0,0,0] cbsz:4
	v_mfma_scale_f32_16x16x128_f8f6f4 v[92:95], v[60:63], v[218:225], v[92:95], v133, v133 op_sel_hi:[0,0,0] cbsz:4
	s_nop 3
	v_mul_f32_e32 v234, v158, v64
	v_mul_f32_e32 v235, v158, v68
	v_mul_f32_e32 v236, v158, v72
	v_mul_f32_e32 v237, v158, v76
	v_fmac_f32_e32 v234, v159, v65
	v_fmac_f32_e32 v235, v159, v69
	v_fmac_f32_e32 v236, v159, v73
	v_fmac_f32_e32 v237, v159, v77
	v_fmac_f32_e32 v234, v160, v66
	v_fmac_f32_e32 v235, v160, v70
	v_fmac_f32_e32 v236, v160, v74
	v_fmac_f32_e32 v237, v160, v78
	v_fmac_f32_e32 v234, v161, v67
	v_fmac_f32_e32 v235, v161, v71
	v_fmac_f32_e32 v236, v161, v75
	v_fmac_f32_e32 v237, v161, v79
	v_add_f32_dpp v234, v234, v234 quad_perm:[1,0,3,2] row_mask:0xf bank_mask:0xf
	v_add_f32_dpp v235, v235, v235 quad_perm:[1,0,3,2] row_mask:0xf bank_mask:0xf
	v_add_f32_dpp v236, v236, v236 quad_perm:[1,0,3,2] row_mask:0xf bank_mask:0xf
	v_add_f32_dpp v237, v237, v237 quad_perm:[1,0,3,2] row_mask:0xf bank_mask:0xf
	v_add_f32_dpp v234, v234, v234 quad_perm:[2,3,0,1] row_mask:0xf bank_mask:0xf
	v_add_f32_dpp v235, v235, v235 quad_perm:[2,3,0,1] row_mask:0xf bank_mask:0xf
	v_add_f32_dpp v236, v236, v236 quad_perm:[2,3,0,1] row_mask:0xf bank_mask:0xf
	v_add_f32_dpp v237, v237, v237 quad_perm:[2,3,0,1] row_mask:0xf bank_mask:0xf
	v_add_f32_dpp v234, v234, v234 row_half_mirror row_mask:0xf bank_mask:0xf
	v_add_f32_dpp v235, v235, v235 row_half_mirror row_mask:0xf bank_mask:0xf
	v_add_f32_dpp v236, v236, v236 row_half_mirror row_mask:0xf bank_mask:0xf
	v_add_f32_dpp v237, v237, v237 row_half_mirror row_mask:0xf bank_mask:0xf
	s_mov_b32 exec_lo, 0x10001
	s_mov_b32 exec_hi, 0x10001
	ds_write_b32 v155, v234 offset:1152
	ds_write_b32 v155, v235 offset:1168
	ds_write_b32 v155, v236 offset:1184
	ds_write_b32 v155, v237 offset:1200
	s_mov_b64 exec, -1
	s_waitcnt lgkmcnt(0)
; __device__ __forceinline__ void peer_token(const Params& P, int t, int lane, int* sidx, float* sval, const int* sid, const float* sgate, const unsigned* szero) {
;     ...
;         for (int hh = 0; hh < 2; ++hh) off2[hh] = (unsigned)sid[8 * hh + (lr & 7)] * 512u + lofs;
; #pragma unroll
;         for (int hh = 0; hh < 2; ++hh)
; #pragma unroll
;             for (int st = 0; st < 4; ++st) abuf[0][hh][st] = *(const uint4*)(Ub + (off2[hh] + 128 * st));
; #pragma unroll
;         for (int T = 0; T < 8; ++T) {
;             if (T + 1 < 8) {
; #pragma unroll
;                 for (int hh = 0; hh < 2; ++hh) off2[hh] = (unsigned)sid[16 * (T + 1) + 8 * hh + (lr & 7)] * 512u + lofs;
; #pragma unroll
;                 for (int hh = 0; hh < 2; ++hh)
; #pragma unroll
;                     for (int st = 0; st < 4; ++st) abuf[(T + 1) & 1][hh][st] = *(const uint4*)(Ub + (off2[hh] + 128 * st));
;             }
; #pragma unroll
;             for (int hh = 0; hh < 2; ++hh) {
;                 f32x4 au = (f32x4){0.f, 0.f, 0.f, 0.f};
; #pragma unroll
;                 for (int st = 0; st < 4; ++st) {
;                     const uint4 a4 = abuf[T & 1][hh][st];
;                     const v8i Av = {(int)a4.x, (int)a4.y, (int)a4.z, (int)a4.w, 0, 0, 0, 0};
;                     au = __builtin_amdgcn_mfma_scale_f32_16x16x128_f8f6f4(Av, Bv[st], au, 4, 0, 0, 0x7f7f7f7f, 0, 0x7f7f7f7f);
;                 }
;                 if (owner) *(f32x4*)(sact + 16 * T + 8 * hh) = au;
;             }
	v_lshl_add_u32 v230, v230, 9, v144
	v_lshl_add_u32 v231, v231, 9, v144
	v_lshl_add_u32 v232, v232, 9, v144
	v_lshl_add_u32 v233, v233, 9, v144
	global_load_dwordx4 v[32:35], v230, s[10:11]
	global_load_dwordx4 v[36:39], v230, s[10:11] offset:256
	global_load_dwordx4 v[40:43], v231, s[10:11]
	global_load_dwordx4 v[44:47], v231, s[10:11] offset:256
	global_load_dwordx4 v[48:51], v232, s[10:11]
	global_load_dwordx4 v[52:55], v232, s[10:11] offset:256
	global_load_dwordx4 v[56:59], v233, s[10:11]
	global_load_dwordx4 v[60:63], v233, s[10:11] offset:256
	ds_read2_b32 v[96:97], v244 offset0:32 offset1:36
	ds_read2_b32 v[98:99], v244 offset0:40 offset1:44
	s_waitcnt vmcnt(8)
	v_mfma_scale_f32_16x16x128_f8f6f4 v[64:67], v[0:3], v[162:169], 0, v133, v133 op_sel_hi:[0,0,0] cbsz:4
	v_mfma_scale_f32_16x16x128_f8f6f4 v[64:67], v[4:7], v[170:177], v[64:67], v133, v133 op_sel_hi:[0,0,0] cbsz:4
	v_mfma_scale_f32_16x16x128_f8f6f4 v[68:71], v[8:11], v[162:169], 0, v133, v133 op_sel_hi:[0,0,0] cbsz:4
	v_mfma_scale_f32_16x16x128_f8f6f4 v[68:71], v[12:15], v[170:177], v[68:71], v133, v133 op_sel_hi:[0,0,0] cbsz:4
	v_mfma_scale_f32_16x16x128_f8f6f4 v[72:75], v[16:19], v[162:169], 0, v133, v133 op_sel_hi:[0,0,0] cbsz:4
	v_mfma_scale_f32_16x16x128_f8f6f4 v[72:75], v[20:23], v[170:177], v[72:75], v133, v133 op_sel_hi:[0,0,0] cbsz:4
	v_mfma_scale_f32_16x16x128_f8f6f4 v[76:79], v[24:27], v[162:169], 0, v133, v133 op_sel_hi:[0,0,0] cbsz:4
	v_mfma_scale_f32_16x16x128_f8f6f4 v[76:79], v[28:31], v[170:177], v[76:79], v133, v133 op_sel_hi:[0,0,0] cbsz:4
	s_nop 3
	v_mul_f32_e32 v234, v158, v80
	v_mul_f32_e32 v235, v158, v84
	v_mul_f32_e32 v236, v158, v88
	v_mul_f32_e32 v237, v158, v92
	v_fmac_f32_e32 v234, v159, v81
	v_fmac_f32_e32 v235, v159, v85
	v_fmac_f32_e32 v236, v159, v89
	v_fmac_f32_e32 v237, v159, v93
	v_fmac_f32_e32 v234, v160, v82
	v_fmac_f32_e32 v235, v160, v86
	v_fmac_f32_e32 v236, v160, v90
	v_fmac_f32_e32 v237, v160, v94
	v_fmac_f32_e32 v234, v161, v83
	v_fmac_f32_e32 v235, v161, v87
	v_fmac_f32_e32 v236, v161, v91
	v_fmac_f32_e32 v237, v161, v95
	v_add_f32_dpp v234, v234, v234 quad_perm:[1,0,3,2] row_mask:0xf bank_mask:0xf
	v_add_f32_dpp v235, v235, v235 quad_perm:[1,0,3,2] row_mask:0xf bank_mask:0xf
	v_add_f32_dpp v236, v236, v236 quad_perm:[1,0,3,2] row_mask:0xf bank_mask:0xf
	v_add_f32_dpp v237, v237, v237 quad_perm:[1,0,3,2] row_mask:0xf bank_mask:0xf
	v_add_f32_dpp v234, v234, v234 quad_perm:[2,3,0,1] row_mask:0xf bank_mask:0xf
	v_add_f32_dpp v235, v235, v235 quad_perm:[2,3,0,1] row_mask:0xf bank_mask:0xf
	v_add_f32_dpp v236, v236, v236 quad_perm:[2,3,0,1] row_mask:0xf bank_mask:0xf
	v_add_f32_dpp v237, v237, v237 quad_perm:[2,3,0,1] row_mask:0xf bank_mask:0xf
	v_add_f32_dpp v234, v234, v234 row_half_mirror row_mask:0xf bank_mask:0xf
	v_add_f32_dpp v235, v235, v235 row_half_mirror row_mask:0xf bank_mask:0xf
	v_add_f32_dpp v236, v236, v236 row_half_mirror row_mask:0xf bank_mask:0xf
	v_add_f32_dpp v237, v237, v237 row_half_mirror row_mask:0xf bank_mask:0xf
	s_mov_b32 exec_lo, 0x10001
	s_mov_b32 exec_hi, 0x10001
	ds_write_b32 v155, v234 offset:1664
	ds_write_b32 v155, v235 offset:1680
	ds_write_b32 v155, v236 offset:1696
	ds_write_b32 v155, v237 offset:1712
	s_mov_b64 exec, -1
	s_waitcnt lgkmcnt(0)
	v_lshl_add_u32 v96, v96, 9, v144
	v_lshl_add_u32 v97, v97, 9, v144
	v_lshl_add_u32 v98, v98, 9, v144
	v_lshl_add_u32 v99, v99, 9, v144
	global_load_dwordx4 v[0:3], v96, s[10:11]
	global_load_dwordx4 v[4:7], v96, s[10:11] offset:256
	global_load_dwordx4 v[8:11], v97, s[10:11]
	global_load_dwordx4 v[12:15], v97, s[10:11] offset:256
	global_load_dwordx4 v[16:19], v98, s[10:11]
	global_load_dwordx4 v[20:23], v98, s[10:11] offset:256
	global_load_dwordx4 v[24:27], v99, s[10:11]
	global_load_dwordx4 v[28:31], v99, s[10:11] offset:256
	ds_read2_b32 v[230:231], v245 offset0:32 offset1:36
	ds_read2_b32 v[232:233], v245 offset0:40 offset1:44
	s_waitcnt vmcnt(8)
	v_mfma_scale_f32_16x16x128_f8f6f4 v[80:83], v[32:35], v[178:185], 0, v133, v133 op_sel_hi:[0,0,0] cbsz:4
	v_mfma_scale_f32_16x16x128_f8f6f4 v[80:83], v[36:39], v[186:193], v[80:83], v133, v133 op_sel_hi:[0,0,0] cbsz:4
	v_mfma_scale_f32_16x16x128_f8f6f4 v[84:87], v[40:43], v[178:185], 0, v133, v133 op_sel_hi:[0,0,0] cbsz:4
	v_mfma_scale_f32_16x16x128_f8f6f4 v[84:87], v[44:47], v[186:193], v[84:87], v133, v133 op_sel_hi:[0,0,0] cbsz:4
	v_mfma_scale_f32_16x16x128_f8f6f4 v[88:91], v[48:51], v[178:185], 0, v133, v133 op_sel_hi:[0,0,0] cbsz:4
	v_mfma_scale_f32_16x16x128_f8f6f4 v[88:91], v[52:55], v[186:193], v[88:91], v133, v133 op_sel_hi:[0,0,0] cbsz:4
	v_mfma_scale_f32_16x16x128_f8f6f4 v[92:95], v[56:59], v[178:185], 0, v133, v133 op_sel_hi:[0,0,0] cbsz:4
	v_mfma_scale_f32_16x16x128_f8f6f4 v[92:95], v[60:63], v[186:193], v[92:95], v133, v133 op_sel_hi:[0,0,0] cbsz:4
	s_nop 3
	v_mul_f32_e32 v234, v226, v64
	v_mul_f32_e32 v235, v226, v68
	v_mul_f32_e32 v236, v226, v72
	v_mul_f32_e32 v237, v226, v76
	v_fmac_f32_e32 v234, v227, v65
	v_fmac_f32_e32 v235, v227, v69
	v_fmac_f32_e32 v236, v227, v73
	v_fmac_f32_e32 v237, v227, v77
	v_fmac_f32_e32 v234, v228, v66
	v_fmac_f32_e32 v235, v228, v70
	v_fmac_f32_e32 v236, v228, v74
	v_fmac_f32_e32 v237, v228, v78
	v_fmac_f32_e32 v234, v229, v67
	v_fmac_f32_e32 v235, v229, v71
	v_fmac_f32_e32 v236, v229, v75
	v_fmac_f32_e32 v237, v229, v79
	v_add_f32_dpp v234, v234, v234 quad_perm:[1,0,3,2] row_mask:0xf bank_mask:0xf
	v_add_f32_dpp v235, v235, v235 quad_perm:[1,0,3,2] row_mask:0xf bank_mask:0xf
	v_add_f32_dpp v236, v236, v236 quad_perm:[1,0,3,2] row_mask:0xf bank_mask:0xf
	v_add_f32_dpp v237, v237, v237 quad_perm:[1,0,3,2] row_mask:0xf bank_mask:0xf
	v_add_f32_dpp v234, v234, v234 quad_perm:[2,3,0,1] row_mask:0xf bank_mask:0xf
	v_add_f32_dpp v235, v235, v235 quad_perm:[2,3,0,1] row_mask:0xf bank_mask:0xf
	v_add_f32_dpp v236, v236, v236 quad_perm:[2,3,0,1] row_mask:0xf bank_mask:0xf
	v_add_f32_dpp v237, v237, v237 quad_perm:[2,3,0,1] row_mask:0xf bank_mask:0xf
	v_add_f32_dpp v234, v234, v234 row_half_mirror row_mask:0xf bank_mask:0xf
	v_add_f32_dpp v235, v235, v235 row_half_mirror row_mask:0xf bank_mask:0xf
	v_add_f32_dpp v236, v236, v236 row_half_mirror row_mask:0xf bank_mask:0xf
	v_add_f32_dpp v237, v237, v237 row_half_mirror row_mask:0xf bank_mask:0xf
	s_mov_b32 exec_lo, 0x1000100
	s_mov_b32 exec_hi, 0x1000100
	ds_write_b32 v155, v234 offset:2176
	ds_write_b32 v155, v235 offset:2192
	ds_write_b32 v155, v236 offset:2208
	ds_write_b32 v155, v237 offset:2224
	s_mov_b64 exec, -1
	s_waitcnt lgkmcnt(0)
; __device__ __forceinline__ void peer_token(const Params& P, int t, int lane, int* sidx, float* sval, const int* sid, const float* sgate, const unsigned* szero) {
;     ...
;         for (int hh = 0; hh < 2; ++hh) off2[hh] = (unsigned)sid[8 * hh + (lr & 7)] * 512u + lofs;
; #pragma unroll
;         for (int hh = 0; hh < 2; ++hh)
; #pragma unroll
;             for (int st = 0; st < 4; ++st) abuf[0][hh][st] = *(const uint4*)(Ub + (off2[hh] + 128 * st));
; #pragma unroll
;         for (int T = 0; T < 8; ++T) {
;             if (T + 1 < 8) {
; #pragma unroll
;                 for (int hh = 0; hh < 2; ++hh) off2[hh] = (unsigned)sid[16 * (T + 1) + 8 * hh + (lr & 7)] * 512u + lofs;
; #pragma unroll
;                 for (int hh = 0; hh < 2; ++hh)
; #pragma unroll
;                     for (int st = 0; st < 4; ++st) abuf[(T + 1) & 1][hh][st] = *(const uint4*)(Ub + (off2[hh] + 128 * st));
;             }
; #pragma unroll
;             for (int hh = 0; hh < 2; ++hh) {
;                 f32x4 au = (f32x4){0.f, 0.f, 0.f, 0.f};
; #pragma unroll
;                 for (int st = 0; st < 4; ++st) {
;                     const uint4 a4 = abuf[T & 1][hh][st];
;                     const v8i Av = {(int)a4.x, (int)a4.y, (int)a4.z, (int)a4.w, 0, 0, 0, 0};
;                     au = __builtin_amdgcn_mfma_scale_f32_16x16x128_f8f6f4(Av, Bv[st], au, 4, 0, 0, 0x7f7f7f7f, 0, 0x7f7f7f7f);
;                 }
;                 if (owner) *(f32x4*)(sact + 16 * T + 8 * hh) = au;
;             }
	v_lshl_add_u32 v230, v230, 9, v144
	v_lshl_add_u32 v231, v231, 9, v144
	v_lshl_add_u32 v232, v232, 9, v144
	v_lshl_add_u32 v233, v233, 9, v144
	global_load_dwordx4 v[32:35], v230, s[10:11]
	global_load_dwordx4 v[36:39], v230, s[10:11] offset:256
	global_load_dwordx4 v[40:43], v231, s[10:11]
	global_load_dwordx4 v[44:47], v231, s[10:11] offset:256
	global_load_dwordx4 v[48:51], v232, s[10:11]
	global_load_dwordx4 v[52:55], v232, s[10:11] offset:256
	global_load_dwordx4 v[56:59], v233, s[10:11]
	global_load_dwordx4 v[60:63], v233, s[10:11] offset:256
	ds_read2_b32 v[96:97], v238 offset0:48 offset1:52
	ds_read2_b32 v[98:99], v238 offset0:56 offset1:60
	s_waitcnt vmcnt(8)
	v_mfma_scale_f32_16x16x128_f8f6f4 v[64:67], v[0:3], v[194:201], 0, v133, v133 op_sel_hi:[0,0,0] cbsz:4
	v_mfma_scale_f32_16x16x128_f8f6f4 v[64:67], v[4:7], v[202:209], v[64:67], v133, v133 op_sel_hi:[0,0,0] cbsz:4
	v_mfma_scale_f32_16x16x128_f8f6f4 v[68:71], v[8:11], v[194:201], 0, v133, v133 op_sel_hi:[0,0,0] cbsz:4
	v_mfma_scale_f32_16x16x128_f8f6f4 v[68:71], v[12:15], v[202:209], v[68:71], v133, v133 op_sel_hi:[0,0,0] cbsz:4
	v_mfma_scale_f32_16x16x128_f8f6f4 v[72:75], v[16:19], v[194:201], 0, v133, v133 op_sel_hi:[0,0,0] cbsz:4
	v_mfma_scale_f32_16x16x128_f8f6f4 v[72:75], v[20:23], v[202:209], v[72:75], v133, v133 op_sel_hi:[0,0,0] cbsz:4
	v_mfma_scale_f32_16x16x128_f8f6f4 v[76:79], v[24:27], v[194:201], 0, v133, v133 op_sel_hi:[0,0,0] cbsz:4
	v_mfma_scale_f32_16x16x128_f8f6f4 v[76:79], v[28:31], v[202:209], v[76:79], v133, v133 op_sel_hi:[0,0,0] cbsz:4
	s_nop 3
	v_mul_f32_e32 v234, v226, v80
	v_mul_f32_e32 v235, v226, v84
	v_mul_f32_e32 v236, v226, v88
	v_mul_f32_e32 v237, v226, v92
	v_fmac_f32_e32 v234, v227, v81
	v_fmac_f32_e32 v235, v227, v85
	v_fmac_f32_e32 v236, v227, v89
	v_fmac_f32_e32 v237, v227, v93
	v_fmac_f32_e32 v234, v228, v82
	v_fmac_f32_e32 v235, v228, v86
	v_fmac_f32_e32 v236, v228, v90
	v_fmac_f32_e32 v237, v228, v94
	v_fmac_f32_e32 v234, v229, v83
	v_fmac_f32_e32 v235, v229, v87
	v_fmac_f32_e32 v236, v229, v91
	v_fmac_f32_e32 v237, v229, v95
	v_add_f32_dpp v234, v234, v234 quad_perm:[1,0,3,2] row_mask:0xf bank_mask:0xf
	v_add_f32_dpp v235, v235, v235 quad_perm:[1,0,3,2] row_mask:0xf bank_mask:0xf
	v_add_f32_dpp v236, v236, v236 quad_perm:[1,0,3,2] row_mask:0xf bank_mask:0xf
	v_add_f32_dpp v237, v237, v237 quad_perm:[1,0,3,2] row_mask:0xf bank_mask:0xf
	v_add_f32_dpp v234, v234, v234 quad_perm:[2,3,0,1] row_mask:0xf bank_mask:0xf
	v_add_f32_dpp v235, v235, v235 quad_perm:[2,3,0,1] row_mask:0xf bank_mask:0xf
	v_add_f32_dpp v236, v236, v236 quad_perm:[2,3,0,1] row_mask:0xf bank_mask:0xf
	v_add_f32_dpp v237, v237, v237 quad_perm:[2,3,0,1] row_mask:0xf bank_mask:0xf
	v_add_f32_dpp v234, v234, v234 row_half_mirror row_mask:0xf bank_mask:0xf
	v_add_f32_dpp v235, v235, v235 row_half_mirror row_mask:0xf bank_mask:0xf
	v_add_f32_dpp v236, v236, v236 row_half_mirror row_mask:0xf bank_mask:0xf
	v_add_f32_dpp v237, v237, v237 row_half_mirror row_mask:0xf bank_mask:0xf
	s_mov_b32 exec_lo, 0x1000100
	s_mov_b32 exec_hi, 0x1000100
	ds_write_b32 v155, v234 offset:2688
	ds_write_b32 v155, v235 offset:2704
	ds_write_b32 v155, v236 offset:2720
	ds_write_b32 v155, v237 offset:2736
	s_mov_b64 exec, -1
	s_waitcnt lgkmcnt(0)
	v_lshl_add_u32 v96, v96, 9, v144
	v_lshl_add_u32 v97, v97, 9, v144
	v_lshl_add_u32 v98, v98, 9, v144
	v_lshl_add_u32 v99, v99, 9, v144
	global_load_dwordx4 v[0:3], v96, s[10:11]
	global_load_dwordx4 v[4:7], v96, s[10:11] offset:256
	global_load_dwordx4 v[8:11], v97, s[10:11]
	global_load_dwordx4 v[12:15], v97, s[10:11] offset:256
	global_load_dwordx4 v[16:19], v98, s[10:11]
	global_load_dwordx4 v[20:23], v98, s[10:11] offset:256
	global_load_dwordx4 v[24:27], v99, s[10:11]
	global_load_dwordx4 v[28:31], v99, s[10:11] offset:256
	ds_read2_b32 v[230:231], v239 offset0:48 offset1:52
	ds_read2_b32 v[232:233], v239 offset0:56 offset1:60
	s_waitcnt vmcnt(8)
	v_mfma_scale_f32_16x16x128_f8f6f4 v[80:83], v[32:35], v[210:217], 0, v133, v133 op_sel_hi:[0,0,0] cbsz:4
	v_mfma_scale_f32_16x16x128_f8f6f4 v[80:83], v[36:39], v[218:225], v[80:83], v133, v133 op_sel_hi:[0,0,0] cbsz:4
	v_mfma_scale_f32_16x16x128_f8f6f4 v[84:87], v[40:43], v[210:217], 0, v133, v133 op_sel_hi:[0,0,0] cbsz:4
	v_mfma_scale_f32_16x16x128_f8f6f4 v[84:87], v[44:47], v[218:225], v[84:87], v133, v133 op_sel_hi:[0,0,0] cbsz:4
	v_mfma_scale_f32_16x16x128_f8f6f4 v[88:91], v[48:51], v[210:217], 0, v133, v133 op_sel_hi:[0,0,0] cbsz:4
	v_mfma_scale_f32_16x16x128_f8f6f4 v[88:91], v[52:55], v[218:225], v[88:91], v133, v133 op_sel_hi:[0,0,0] cbsz:4
	v_mfma_scale_f32_16x16x128_f8f6f4 v[92:95], v[56:59], v[210:217], 0, v133, v133 op_sel_hi:[0,0,0] cbsz:4
	v_mfma_scale_f32_16x16x128_f8f6f4 v[92:95], v[60:63], v[218:225], v[92:95], v133, v133 op_sel_hi:[0,0,0] cbsz:4
	s_nop 3
	v_mul_f32_e32 v234, v226, v64
	v_mul_f32_e32 v235, v226, v68
	v_mul_f32_e32 v236, v226, v72
	v_mul_f32_e32 v237, v226, v76
	v_fmac_f32_e32 v234, v227, v65
	v_fmac_f32_e32 v235, v227, v69
	v_fmac_f32_e32 v236, v227, v73
	v_fmac_f32_e32 v237, v227, v77
	v_fmac_f32_e32 v234, v228, v66
	v_fmac_f32_e32 v235, v228, v70
	v_fmac_f32_e32 v236, v228, v74
	v_fmac_f32_e32 v237, v228, v78
	v_fmac_f32_e32 v234, v229, v67
	v_fmac_f32_e32 v235, v229, v71
	v_fmac_f32_e32 v236, v229, v75
	v_fmac_f32_e32 v237, v229, v79
	v_add_f32_dpp v234, v234, v234 quad_perm:[1,0,3,2] row_mask:0xf bank_mask:0xf
	v_add_f32_dpp v235, v235, v235 quad_perm:[1,0,3,2] row_mask:0xf bank_mask:0xf
	v_add_f32_dpp v236, v236, v236 quad_perm:[1,0,3,2] row_mask:0xf bank_mask:0xf
	v_add_f32_dpp v237, v237, v237 quad_perm:[1,0,3,2] row_mask:0xf bank_mask:0xf
	v_add_f32_dpp v234, v234, v234 quad_perm:[2,3,0,1] row_mask:0xf bank_mask:0xf
	v_add_f32_dpp v235, v235, v235 quad_perm:[2,3,0,1] row_mask:0xf bank_mask:0xf
	v_add_f32_dpp v236, v236, v236 quad_perm:[2,3,0,1] row_mask:0xf bank_mask:0xf
	v_add_f32_dpp v237, v237, v237 quad_perm:[2,3,0,1] row_mask:0xf bank_mask:0xf
	v_add_f32_dpp v234, v234, v234 row_half_mirror row_mask:0xf bank_mask:0xf
	v_add_f32_dpp v235, v235, v235 row_half_mirror row_mask:0xf bank_mask:0xf
	v_add_f32_dpp v236, v236, v236 row_half_mirror row_mask:0xf bank_mask:0xf
	v_add_f32_dpp v237, v237, v237 row_half_mirror row_mask:0xf bank_mask:0xf
	s_mov_b32 exec_lo, 0x1000100
	s_mov_b32 exec_hi, 0x1000100
	ds_write_b32 v155, v234 offset:3200
	ds_write_b32 v155, v235 offset:3216
	ds_write_b32 v155, v236 offset:3232
	ds_write_b32 v155, v237 offset:3248
	s_mov_b64 exec, -1
	s_waitcnt lgkmcnt(0)
; __device__ __forceinline__ void peer_token(const Params& P, int t, int lane, int* sidx, float* sval, const int* sid, const float* sgate, const unsigned* szero) {
;     ...
;         for (int hh = 0; hh < 2; ++hh) off2[hh] = (unsigned)sid[8 * hh + (lr & 7)] * 512u + lofs;
; #pragma unroll
;         for (int hh = 0; hh < 2; ++hh)
; #pragma unroll
;             for (int st = 0; st < 4; ++st) abuf[0][hh][st] = *(const uint4*)(Ub + (off2[hh] + 128 * st));
; #pragma unroll
;         for (int T = 0; T < 8; ++T) {
;             if (T + 1 < 8) {
; #pragma unroll
;                 for (int hh = 0; hh < 2; ++hh) off2[hh] = (unsigned)sid[16 * (T + 1) + 8 * hh + (lr & 7)] * 512u + lofs;
; #pragma unroll
;                 for (int hh = 0; hh < 2; ++hh)
; #pragma unroll
;                     for (int st = 0; st < 4; ++st) abuf[(T + 1) & 1][hh][st] = *(const uint4*)(Ub + (off2[hh] + 128 * st));
;             }
; #pragma unroll
;             for (int hh = 0; hh < 2; ++hh) {
;                 f32x4 au = (f32x4){0.f, 0.f, 0.f, 0.f};
; #pragma unroll
;                 for (int st = 0; st < 4; ++st) {
;                     const uint4 a4 = abuf[T & 1][hh][st];
;                     const v8i Av = {(int)a4.x, (int)a4.y, (int)a4.z, (int)a4.w, 0, 0, 0, 0};
;                     au = __builtin_amdgcn_mfma_scale_f32_16x16x128_f8f6f4(Av, Bv[st], au, 4, 0, 0, 0x7f7f7f7f, 0, 0x7f7f7f7f);
;                 }
;                 if (owner) *(f32x4*)(sact + 16 * T + 8 * hh) = au;
;             }
	v_lshl_add_u32 v230, v230, 9, v144
	v_lshl_add_u32 v231, v231, 9, v144
	v_lshl_add_u32 v232, v232, 9, v144
	v_lshl_add_u32 v233, v233, 9, v144
	global_load_dwordx4 v[32:35], v230, s[10:11]
	global_load_dwordx4 v[36:39], v230, s[10:11] offset:256
	global_load_dwordx4 v[40:43], v231, s[10:11]
	global_load_dwordx4 v[44:47], v231, s[10:11] offset:256
	global_load_dwordx4 v[48:51], v232, s[10:11]
	global_load_dwordx4 v[52:55], v232, s[10:11] offset:256
	global_load_dwordx4 v[56:59], v233, s[10:11]
	global_load_dwordx4 v[60:63], v233, s[10:11] offset:256
	ds_read2_b32 v[96:97], v240 offset0:48 offset1:52
	ds_read2_b32 v[98:99], v240 offset0:56 offset1:60
	s_waitcnt vmcnt(8)
	v_mfma_scale_f32_16x16x128_f8f6f4 v[64:67], v[0:3], v[162:169], 0, v133, v133 op_sel_hi:[0,0,0] cbsz:4
	v_mfma_scale_f32_16x16x128_f8f6f4 v[64:67], v[4:7], v[170:177], v[64:67], v133, v133 op_sel_hi:[0,0,0] cbsz:4
	v_mfma_scale_f32_16x16x128_f8f6f4 v[68:71], v[8:11], v[162:169], 0, v133, v133 op_sel_hi:[0,0,0] cbsz:4
	v_mfma_scale_f32_16x16x128_f8f6f4 v[68:71], v[12:15], v[170:177], v[68:71], v133, v133 op_sel_hi:[0,0,0] cbsz:4
	v_mfma_scale_f32_16x16x128_f8f6f4 v[72:75], v[16:19], v[162:169], 0, v133, v133 op_sel_hi:[0,0,0] cbsz:4
	v_mfma_scale_f32_16x16x128_f8f6f4 v[72:75], v[20:23], v[170:177], v[72:75], v133, v133 op_sel_hi:[0,0,0] cbsz:4
	v_mfma_scale_f32_16x16x128_f8f6f4 v[76:79], v[24:27], v[162:169], 0, v133, v133 op_sel_hi:[0,0,0] cbsz:4
	v_mfma_scale_f32_16x16x128_f8f6f4 v[76:79], v[28:31], v[170:177], v[76:79], v133, v133 op_sel_hi:[0,0,0] cbsz:4
	s_nop 3
	v_mul_f32_e32 v234, v226, v80
	v_mul_f32_e32 v235, v226, v84
	v_mul_f32_e32 v236, v226, v88
	v_mul_f32_e32 v237, v226, v92
	v_fmac_f32_e32 v234, v227, v81
	v_fmac_f32_e32 v235, v227, v85
	v_fmac_f32_e32 v236, v227, v89
	v_fmac_f32_e32 v237, v227, v93
	v_fmac_f32_e32 v234, v228, v82
	v_fmac_f32_e32 v235, v228, v86
	v_fmac_f32_e32 v236, v228, v90
	v_fmac_f32_e32 v237, v228, v94
	v_fmac_f32_e32 v234, v229, v83
	v_fmac_f32_e32 v235, v229, v87
	v_fmac_f32_e32 v236, v229, v91
	v_fmac_f32_e32 v237, v229, v95
	v_add_f32_dpp v234, v234, v234 quad_perm:[1,0,3,2] row_mask:0xf bank_mask:0xf
	v_add_f32_dpp v235, v235, v235 quad_perm:[1,0,3,2] row_mask:0xf bank_mask:0xf
	v_add_f32_dpp v236, v236, v236 quad_perm:[1,0,3,2] row_mask:0xf bank_mask:0xf
	v_add_f32_dpp v237, v237, v237 quad_perm:[1,0,3,2] row_mask:0xf bank_mask:0xf
	v_add_f32_dpp v234, v234, v234 quad_perm:[2,3,0,1] row_mask:0xf bank_mask:0xf
	v_add_f32_dpp v235, v235, v235 quad_perm:[2,3,0,1] row_mask:0xf bank_mask:0xf
	v_add_f32_dpp v236, v236, v236 quad_perm:[2,3,0,1] row_mask:0xf bank_mask:0xf
	v_add_f32_dpp v237, v237, v237 quad_perm:[2,3,0,1] row_mask:0xf bank_mask:0xf
	v_add_f32_dpp v234, v234, v234 row_half_mirror row_mask:0xf bank_mask:0xf
	v_add_f32_dpp v235, v235, v235 row_half_mirror row_mask:0xf bank_mask:0xf
	v_add_f32_dpp v236, v236, v236 row_half_mirror row_mask:0xf bank_mask:0xf
	v_add_f32_dpp v237, v237, v237 row_half_mirror row_mask:0xf bank_mask:0xf
	s_mov_b32 exec_lo, 0x1000100
	s_mov_b32 exec_hi, 0x1000100
	ds_write_b32 v155, v234 offset:3712
	ds_write_b32 v155, v235 offset:3728
	ds_write_b32 v155, v236 offset:3744
	ds_write_b32 v155, v237 offset:3760
	s_mov_b64 exec, -1
	s_waitcnt lgkmcnt(0)
	v_lshl_add_u32 v96, v96, 9, v144
	v_lshl_add_u32 v97, v97, 9, v144
	v_lshl_add_u32 v98, v98, 9, v144
	v_lshl_add_u32 v99, v99, 9, v144
	global_load_dwordx4 v[0:3], v96, s[10:11]
	global_load_dwordx4 v[4:7], v96, s[10:11] offset:256
	global_load_dwordx4 v[8:11], v97, s[10:11]
	global_load_dwordx4 v[12:15], v97, s[10:11] offset:256
	global_load_dwordx4 v[16:19], v98, s[10:11]
	global_load_dwordx4 v[20:23], v98, s[10:11] offset:256
	global_load_dwordx4 v[24:27], v99, s[10:11]
	global_load_dwordx4 v[28:31], v99, s[10:11] offset:256
	ds_read2_b32 v[230:231], v241 offset0:48 offset1:52
	ds_read2_b32 v[232:233], v241 offset0:56 offset1:60
	s_waitcnt vmcnt(8)
	v_mfma_scale_f32_16x16x128_f8f6f4 v[80:83], v[32:35], v[178:185], 0, v133, v133 op_sel_hi:[0,0,0] cbsz:4
	v_mfma_scale_f32_16x16x128_f8f6f4 v[80:83], v[36:39], v[186:193], v[80:83], v133, v133 op_sel_hi:[0,0,0] cbsz:4
	v_mfma_scale_f32_16x16x128_f8f6f4 v[84:87], v[40:43], v[178:185], 0, v133, v133 op_sel_hi:[0,0,0] cbsz:4
	v_mfma_scale_f32_16x16x128_f8f6f4 v[84:87], v[44:47], v[186:193], v[84:87], v133, v133 op_sel_hi:[0,0,0] cbsz:4
	v_mfma_scale_f32_16x16x128_f8f6f4 v[88:91], v[48:51], v[178:185], 0, v133, v133 op_sel_hi:[0,0,0] cbsz:4
	v_mfma_scale_f32_16x16x128_f8f6f4 v[88:91], v[52:55], v[186:193], v[88:91], v133, v133 op_sel_hi:[0,0,0] cbsz:4
	v_mfma_scale_f32_16x16x128_f8f6f4 v[92:95], v[56:59], v[178:185], 0, v133, v133 op_sel_hi:[0,0,0] cbsz:4
	v_mfma_scale_f32_16x16x128_f8f6f4 v[92:95], v[60:63], v[186:193], v[92:95], v133, v133 op_sel_hi:[0,0,0] cbsz:4
	s_nop 3
	v_mul_f32_e32 v234, v158, v64
	v_mul_f32_e32 v235, v158, v68
	v_mul_f32_e32 v236, v158, v72
	v_mul_f32_e32 v237, v158, v76
	v_fmac_f32_e32 v234, v159, v65
	v_fmac_f32_e32 v235, v159, v69
	v_fmac_f32_e32 v236, v159, v73
	v_fmac_f32_e32 v237, v159, v77
	v_fmac_f32_e32 v234, v160, v66
	v_fmac_f32_e32 v235, v160, v70
	v_fmac_f32_e32 v236, v160, v74
	v_fmac_f32_e32 v237, v160, v78
	v_fmac_f32_e32 v234, v161, v67
	v_fmac_f32_e32 v235, v161, v71
	v_fmac_f32_e32 v236, v161, v75
	v_fmac_f32_e32 v237, v161, v79
	v_add_f32_dpp v234, v234, v234 quad_perm:[1,0,3,2] row_mask:0xf bank_mask:0xf
	v_add_f32_dpp v235, v235, v235 quad_perm:[1,0,3,2] row_mask:0xf bank_mask:0xf
	v_add_f32_dpp v236, v236, v236 quad_perm:[1,0,3,2] row_mask:0xf bank_mask:0xf
	v_add_f32_dpp v237, v237, v237 quad_perm:[1,0,3,2] row_mask:0xf bank_mask:0xf
	v_add_f32_dpp v234, v234, v234 quad_perm:[2,3,0,1] row_mask:0xf bank_mask:0xf
	v_add_f32_dpp v235, v235, v235 quad_perm:[2,3,0,1] row_mask:0xf bank_mask:0xf
	v_add_f32_dpp v236, v236, v236 quad_perm:[2,3,0,1] row_mask:0xf bank_mask:0xf
	v_add_f32_dpp v237, v237, v237 quad_perm:[2,3,0,1] row_mask:0xf bank_mask:0xf
	v_add_f32_dpp v234, v234, v234 row_half_mirror row_mask:0xf bank_mask:0xf
	v_add_f32_dpp v235, v235, v235 row_half_mirror row_mask:0xf bank_mask:0xf
	v_add_f32_dpp v236, v236, v236 row_half_mirror row_mask:0xf bank_mask:0xf
	v_add_f32_dpp v237, v237, v237 row_half_mirror row_mask:0xf bank_mask:0xf
	s_mov_b32 exec_lo, 0x10001
	s_mov_b32 exec_hi, 0x10001
	ds_write_b32 v155, v234 offset:192
	ds_write_b32 v155, v235 offset:208
	ds_write_b32 v155, v236 offset:224
	ds_write_b32 v155, v237 offset:240
	s_mov_b64 exec, -1
	s_waitcnt lgkmcnt(0)
; __device__ __forceinline__ void peer_token(const Params& P, int t, int lane, int* sidx, float* sval, const int* sid, const float* sgate, const unsigned* szero) {
;     ...
;         for (int hh = 0; hh < 2; ++hh) off2[hh] = (unsigned)sid[8 * hh + (lr & 7)] * 512u + lofs;
; #pragma unroll
;         for (int hh = 0; hh < 2; ++hh)
; #pragma unroll
;             for (int st = 0; st < 4; ++st) abuf[0][hh][st] = *(const uint4*)(Ub + (off2[hh] + 128 * st));
; #pragma unroll
;         for (int T = 0; T < 8; ++T) {
;             if (T + 1 < 8) {
; #pragma unroll
;                 for (int hh = 0; hh < 2; ++hh) off2[hh] = (unsigned)sid[16 * (T + 1) + 8 * hh + (lr & 7)] * 512u + lofs;
; #pragma unroll
;                 for (int hh = 0; hh < 2; ++hh)
; #pragma unroll
;                     for (int st = 0; st < 4; ++st) abuf[(T + 1) & 1][hh][st] = *(const uint4*)(Ub + (off2[hh] + 128 * st));
;             }
; #pragma unroll
;             for (int hh = 0; hh < 2; ++hh) {
;                 f32x4 au = (f32x4){0.f, 0.f, 0.f, 0.f};
; #pragma unroll
;                 for (int st = 0; st < 4; ++st) {
;                     const uint4 a4 = abuf[T & 1][hh][st];
;                     const v8i Av = {(int)a4.x, (int)a4.y, (int)a4.z, (int)a4.w, 0, 0, 0, 0};
;                     au = __builtin_amdgcn_mfma_scale_f32_16x16x128_f8f6f4(Av, Bv[st], au, 4, 0, 0, 0x7f7f7f7f, 0, 0x7f7f7f7f);
;                 }
;                 if (owner) *(f32x4*)(sact + 16 * T + 8 * hh) = au;
;             }
	v_lshl_add_u32 v230, v230, 9, v144
	v_lshl_add_u32 v231, v231, 9, v144
	v_lshl_add_u32 v232, v232, 9, v144
	v_lshl_add_u32 v233, v233, 9, v144
	global_load_dwordx4 v[32:35], v230, s[10:11]
	global_load_dwordx4 v[36:39], v230, s[10:11] offset:256
	global_load_dwordx4 v[40:43], v231, s[10:11]
	global_load_dwordx4 v[44:47], v231, s[10:11] offset:256
	global_load_dwordx4 v[48:51], v232, s[10:11]
	global_load_dwordx4 v[52:55], v232, s[10:11] offset:256
	global_load_dwordx4 v[56:59], v233, s[10:11]
	global_load_dwordx4 v[60:63], v233, s[10:11] offset:256
	ds_read2_b32 v[96:97], v242 offset0:48 offset1:52
	ds_read2_b32 v[98:99], v242 offset0:56 offset1:60
	s_waitcnt vmcnt(8)
	v_mfma_scale_f32_16x16x128_f8f6f4 v[64:67], v[0:3], v[194:201], 0, v133, v133 op_sel_hi:[0,0,0] cbsz:4
	v_mfma_scale_f32_16x16x128_f8f6f4 v[64:67], v[4:7], v[202:209], v[64:67], v133, v133 op_sel_hi:[0,0,0] cbsz:4
	v_mfma_scale_f32_16x16x128_f8f6f4 v[68:71], v[8:11], v[194:201], 0, v133, v133 op_sel_hi:[0,0,0] cbsz:4
	v_mfma_scale_f32_16x16x128_f8f6f4 v[68:71], v[12:15], v[202:209], v[68:71], v133, v133 op_sel_hi:[0,0,0] cbsz:4
	v_mfma_scale_f32_16x16x128_f8f6f4 v[72:75], v[16:19], v[194:201], 0, v133, v133 op_sel_hi:[0,0,0] cbsz:4
	v_mfma_scale_f32_16x16x128_f8f6f4 v[72:75], v[20:23], v[202:209], v[72:75], v133, v133 op_sel_hi:[0,0,0] cbsz:4
	v_mfma_scale_f32_16x16x128_f8f6f4 v[76:79], v[24:27], v[194:201], 0, v133, v133 op_sel_hi:[0,0,0] cbsz:4
	v_mfma_scale_f32_16x16x128_f8f6f4 v[76:79], v[28:31], v[202:209], v[76:79], v133, v133 op_sel_hi:[0,0,0] cbsz:4
	s_nop 3
	v_mul_f32_e32 v234, v158, v80
	v_mul_f32_e32 v235, v158, v84
	v_mul_f32_e32 v236, v158, v88
	v_mul_f32_e32 v237, v158, v92
	v_fmac_f32_e32 v234, v159, v81
	v_fmac_f32_e32 v235, v159, v85
	v_fmac_f32_e32 v236, v159, v89
	v_fmac_f32_e32 v237, v159, v93
	v_fmac_f32_e32 v234, v160, v82
	v_fmac_f32_e32 v235, v160, v86
	v_fmac_f32_e32 v236, v160, v90
	v_fmac_f32_e32 v237, v160, v94
	v_fmac_f32_e32 v234, v161, v83
	v_fmac_f32_e32 v235, v161, v87
	v_fmac_f32_e32 v236, v161, v91
	v_fmac_f32_e32 v237, v161, v95
	v_add_f32_dpp v234, v234, v234 quad_perm:[1,0,3,2] row_mask:0xf bank_mask:0xf
	v_add_f32_dpp v235, v235, v235 quad_perm:[1,0,3,2] row_mask:0xf bank_mask:0xf
	v_add_f32_dpp v236, v236, v236 quad_perm:[1,0,3,2] row_mask:0xf bank_mask:0xf
	v_add_f32_dpp v237, v237, v237 quad_perm:[1,0,3,2] row_mask:0xf bank_mask:0xf
	v_add_f32_dpp v234, v234, v234 quad_perm:[2,3,0,1] row_mask:0xf bank_mask:0xf
	v_add_f32_dpp v235, v235, v235 quad_perm:[2,3,0,1] row_mask:0xf bank_mask:0xf
	v_add_f32_dpp v236, v236, v236 quad_perm:[2,3,0,1] row_mask:0xf bank_mask:0xf
	v_add_f32_dpp v237, v237, v237 quad_perm:[2,3,0,1] row_mask:0xf bank_mask:0xf
	v_add_f32_dpp v234, v234, v234 row_half_mirror row_mask:0xf bank_mask:0xf
	v_add_f32_dpp v235, v235, v235 row_half_mirror row_mask:0xf bank_mask:0xf
	v_add_f32_dpp v236, v236, v236 row_half_mirror row_mask:0xf bank_mask:0xf
	v_add_f32_dpp v237, v237, v237 row_half_mirror row_mask:0xf bank_mask:0xf
	s_mov_b32 exec_lo, 0x10001
	s_mov_b32 exec_hi, 0x10001
	ds_write_b32 v155, v234 offset:704
	ds_write_b32 v155, v235 offset:720
	ds_write_b32 v155, v236 offset:736
	ds_write_b32 v155, v237 offset:752
	s_mov_b64 exec, -1
	s_waitcnt lgkmcnt(0)
	v_lshl_add_u32 v96, v96, 9, v144
	v_lshl_add_u32 v97, v97, 9, v144
	v_lshl_add_u32 v98, v98, 9, v144
	v_lshl_add_u32 v99, v99, 9, v144
	global_load_dwordx4 v[0:3], v96, s[10:11]
	global_load_dwordx4 v[4:7], v96, s[10:11] offset:256
	global_load_dwordx4 v[8:11], v97, s[10:11]
	global_load_dwordx4 v[12:15], v97, s[10:11] offset:256
	global_load_dwordx4 v[16:19], v98, s[10:11]
	global_load_dwordx4 v[20:23], v98, s[10:11] offset:256
	global_load_dwordx4 v[24:27], v99, s[10:11]
	global_load_dwordx4 v[28:31], v99, s[10:11] offset:256
	ds_read2_b32 v[230:231], v243 offset0:48 offset1:52
	ds_read2_b32 v[232:233], v243 offset0:56 offset1:60
	s_waitcnt vmcnt(8)
	v_mfma_scale_f32_16x16x128_f8f6f4 v[80:83], v[32:35], v[210:217], 0, v133, v133 op_sel_hi:[0,0,0] cbsz:4
	v_mfma_scale_f32_16x16x128_f8f6f4 v[80:83], v[36:39], v[218:225], v[80:83], v133, v133 op_sel_hi:[0,0,0] cbsz:4
	v_mfma_scale_f32_16x16x128_f8f6f4 v[84:87], v[40:43], v[210:217], 0, v133, v133 op_sel_hi:[0,0,0] cbsz:4
	v_mfma_scale_f32_16x16x128_f8f6f4 v[84:87], v[44:47], v[218:225], v[84:87], v133, v133 op_sel_hi:[0,0,0] cbsz:4
	v_mfma_scale_f32_16x16x128_f8f6f4 v[88:91], v[48:51], v[210:217], 0, v133, v133 op_sel_hi:[0,0,0] cbsz:4
	v_mfma_scale_f32_16x16x128_f8f6f4 v[88:91], v[52:55], v[218:225], v[88:91], v133, v133 op_sel_hi:[0,0,0] cbsz:4
	v_mfma_scale_f32_16x16x128_f8f6f4 v[92:95], v[56:59], v[210:217], 0, v133, v133 op_sel_hi:[0,0,0] cbsz:4
	v_mfma_scale_f32_16x16x128_f8f6f4 v[92:95], v[60:63], v[218:225], v[92:95], v133, v133 op_sel_hi:[0,0,0] cbsz:4
	s_nop 3
	v_mul_f32_e32 v234, v158, v64
	v_mul_f32_e32 v235, v158, v68
	v_mul_f32_e32 v236, v158, v72
	v_mul_f32_e32 v237, v158, v76
	v_fmac_f32_e32 v234, v159, v65
	v_fmac_f32_e32 v235, v159, v69
	v_fmac_f32_e32 v236, v159, v73
	v_fmac_f32_e32 v237, v159, v77
	v_fmac_f32_e32 v234, v160, v66
	v_fmac_f32_e32 v235, v160, v70
	v_fmac_f32_e32 v236, v160, v74
	v_fmac_f32_e32 v237, v160, v78
	v_fmac_f32_e32 v234, v161, v67
	v_fmac_f32_e32 v235, v161, v71
	v_fmac_f32_e32 v236, v161, v75
	v_fmac_f32_e32 v237, v161, v79
	v_add_f32_dpp v234, v234, v234 quad_perm:[1,0,3,2] row_mask:0xf bank_mask:0xf
	v_add_f32_dpp v235, v235, v235 quad_perm:[1,0,3,2] row_mask:0xf bank_mask:0xf
	v_add_f32_dpp v236, v236, v236 quad_perm:[1,0,3,2] row_mask:0xf bank_mask:0xf
	v_add_f32_dpp v237, v237, v237 quad_perm:[1,0,3,2] row_mask:0xf bank_mask:0xf
	v_add_f32_dpp v234, v234, v234 quad_perm:[2,3,0,1] row_mask:0xf bank_mask:0xf
	v_add_f32_dpp v235, v235, v235 quad_perm:[2,3,0,1] row_mask:0xf bank_mask:0xf
	v_add_f32_dpp v236, v236, v236 quad_perm:[2,3,0,1] row_mask:0xf bank_mask:0xf
	v_add_f32_dpp v237, v237, v237 quad_perm:[2,3,0,1] row_mask:0xf bank_mask:0xf
	v_add_f32_dpp v234, v234, v234 row_half_mirror row_mask:0xf bank_mask:0xf
	v_add_f32_dpp v235, v235, v235 row_half_mirror row_mask:0xf bank_mask:0xf
	v_add_f32_dpp v236, v236, v236 row_half_mirror row_mask:0xf bank_mask:0xf
	v_add_f32_dpp v237, v237, v237 row_half_mirror row_mask:0xf bank_mask:0xf
	s_mov_b32 exec_lo, 0x10001
	s_mov_b32 exec_hi, 0x10001
	ds_write_b32 v155, v234 offset:1216
	ds_write_b32 v155, v235 offset:1232
	ds_write_b32 v155, v236 offset:1248
	ds_write_b32 v155, v237 offset:1264
	s_mov_b64 exec, -1
	s_waitcnt lgkmcnt(0)
; __device__ __forceinline__ void peer_token(const Params& P, int t, int lane, int* sidx, float* sval, const int* sid, const float* sgate, const unsigned* szero) {
;     ...
;         for (int hh = 0; hh < 2; ++hh) off2[hh] = (unsigned)sid[8 * hh + (lr & 7)] * 512u + lofs;
; #pragma unroll
;         for (int hh = 0; hh < 2; ++hh)
; #pragma unroll
;             for (int st = 0; st < 4; ++st) abuf[0][hh][st] = *(const uint4*)(Ub + (off2[hh] + 128 * st));
; #pragma unroll
;         for (int T = 0; T < 8; ++T) {
;             if (T + 1 < 8) {
; #pragma unroll
;                 for (int hh = 0; hh < 2; ++hh) off2[hh] = (unsigned)sid[16 * (T + 1) + 8 * hh + (lr & 7)] * 512u + lofs;
; #pragma unroll
;                 for (int hh = 0; hh < 2; ++hh)
; #pragma unroll
;                     for (int st = 0; st < 4; ++st) abuf[(T + 1) & 1][hh][st] = *(const uint4*)(Ub + (off2[hh] + 128 * st));
;             }
; #pragma unroll
;             for (int hh = 0; hh < 2; ++hh) {
;                 f32x4 au = (f32x4){0.f, 0.f, 0.f, 0.f};
; #pragma unroll
;                 for (int st = 0; st < 4; ++st) {
;                     const uint4 a4 = abuf[T & 1][hh][st];
;                     const v8i Av = {(int)a4.x, (int)a4.y, (int)a4.z, (int)a4.w, 0, 0, 0, 0};
;                     au = __builtin_amdgcn_mfma_scale_f32_16x16x128_f8f6f4(Av, Bv[st], au, 4, 0, 0, 0x7f7f7f7f, 0, 0x7f7f7f7f);
;                 }
;                 if (owner) *(f32x4*)(sact + 16 * T + 8 * hh) = au;
;             }
	v_lshl_add_u32 v230, v230, 9, v144
	v_lshl_add_u32 v231, v231, 9, v144
	v_lshl_add_u32 v232, v232, 9, v144
	v_lshl_add_u32 v233, v233, 9, v144
	global_load_dwordx4 v[32:35], v230, s[10:11]
	global_load_dwordx4 v[36:39], v230, s[10:11] offset:256
	global_load_dwordx4 v[40:43], v231, s[10:11]
	global_load_dwordx4 v[44:47], v231, s[10:11] offset:256
	global_load_dwordx4 v[48:51], v232, s[10:11]
	global_load_dwordx4 v[52:55], v232, s[10:11] offset:256
	global_load_dwordx4 v[56:59], v233, s[10:11]
	global_load_dwordx4 v[60:63], v233, s[10:11] offset:256
	ds_read2_b32 v[96:97], v244 offset0:48 offset1:52
	ds_read2_b32 v[98:99], v244 offset0:56 offset1:60
	s_waitcnt vmcnt(8)
	v_mfma_scale_f32_16x16x128_f8f6f4 v[64:67], v[0:3], v[162:169], 0, v133, v133 op_sel_hi:[0,0,0] cbsz:4
	v_mfma_scale_f32_16x16x128_f8f6f4 v[64:67], v[4:7], v[170:177], v[64:67], v133, v133 op_sel_hi:[0,0,0] cbsz:4
	v_mfma_scale_f32_16x16x128_f8f6f4 v[68:71], v[8:11], v[162:169], 0, v133, v133 op_sel_hi:[0,0,0] cbsz:4
	v_mfma_scale_f32_16x16x128_f8f6f4 v[68:71], v[12:15], v[170:177], v[68:71], v133, v133 op_sel_hi:[0,0,0] cbsz:4
	v_mfma_scale_f32_16x16x128_f8f6f4 v[72:75], v[16:19], v[162:169], 0, v133, v133 op_sel_hi:[0,0,0] cbsz:4
	v_mfma_scale_f32_16x16x128_f8f6f4 v[72:75], v[20:23], v[170:177], v[72:75], v133, v133 op_sel_hi:[0,0,0] cbsz:4
	v_mfma_scale_f32_16x16x128_f8f6f4 v[76:79], v[24:27], v[162:169], 0, v133, v133 op_sel_hi:[0,0,0] cbsz:4
	v_mfma_scale_f32_16x16x128_f8f6f4 v[76:79], v[28:31], v[170:177], v[76:79], v133, v133 op_sel_hi:[0,0,0] cbsz:4
	s_nop 3
	v_mul_f32_e32 v234, v158, v80
	v_mul_f32_e32 v235, v158, v84
	v_mul_f32_e32 v236, v158, v88
	v_mul_f32_e32 v237, v158, v92
	v_fmac_f32_e32 v234, v159, v81
	v_fmac_f32_e32 v235, v159, v85
	v_fmac_f32_e32 v236, v159, v89
	v_fmac_f32_e32 v237, v159, v93
	v_fmac_f32_e32 v234, v160, v82
	v_fmac_f32_e32 v235, v160, v86
	v_fmac_f32_e32 v236, v160, v90
	v_fmac_f32_e32 v237, v160, v94
	v_fmac_f32_e32 v234, v161, v83
	v_fmac_f32_e32 v235, v161, v87
	v_fmac_f32_e32 v236, v161, v91
	v_fmac_f32_e32 v237, v161, v95
	v_add_f32_dpp v234, v234, v234 quad_perm:[1,0,3,2] row_mask:0xf bank_mask:0xf
	v_add_f32_dpp v235, v235, v235 quad_perm:[1,0,3,2] row_mask:0xf bank_mask:0xf
	v_add_f32_dpp v236, v236, v236 quad_perm:[1,0,3,2] row_mask:0xf bank_mask:0xf
	v_add_f32_dpp v237, v237, v237 quad_perm:[1,0,3,2] row_mask:0xf bank_mask:0xf
	v_add_f32_dpp v234, v234, v234 quad_perm:[2,3,0,1] row_mask:0xf bank_mask:0xf
	v_add_f32_dpp v235, v235, v235 quad_perm:[2,3,0,1] row_mask:0xf bank_mask:0xf
	v_add_f32_dpp v236, v236, v236 quad_perm:[2,3,0,1] row_mask:0xf bank_mask:0xf
	v_add_f32_dpp v237, v237, v237 quad_perm:[2,3,0,1] row_mask:0xf bank_mask:0xf
	v_add_f32_dpp v234, v234, v234 row_half_mirror row_mask:0xf bank_mask:0xf
	v_add_f32_dpp v235, v235, v235 row_half_mirror row_mask:0xf bank_mask:0xf
	v_add_f32_dpp v236, v236, v236 row_half_mirror row_mask:0xf bank_mask:0xf
	v_add_f32_dpp v237, v237, v237 row_half_mirror row_mask:0xf bank_mask:0xf
	s_mov_b32 exec_lo, 0x10001
	s_mov_b32 exec_hi, 0x10001
	ds_write_b32 v155, v234 offset:1728
	ds_write_b32 v155, v235 offset:1744
	ds_write_b32 v155, v236 offset:1760
	ds_write_b32 v155, v237 offset:1776
	s_mov_b64 exec, -1
	s_waitcnt lgkmcnt(0)
	v_lshl_add_u32 v96, v96, 9, v144
	v_lshl_add_u32 v97, v97, 9, v144
	v_lshl_add_u32 v98, v98, 9, v144
	v_lshl_add_u32 v99, v99, 9, v144
	global_load_dwordx4 v[0:3], v96, s[10:11]
	global_load_dwordx4 v[4:7], v96, s[10:11] offset:256
	global_load_dwordx4 v[8:11], v97, s[10:11]
	global_load_dwordx4 v[12:15], v97, s[10:11] offset:256
	global_load_dwordx4 v[16:19], v98, s[10:11]
	global_load_dwordx4 v[20:23], v98, s[10:11] offset:256
	global_load_dwordx4 v[24:27], v99, s[10:11]
	global_load_dwordx4 v[28:31], v99, s[10:11] offset:256
	ds_read2_b32 v[230:231], v245 offset0:48 offset1:52
	ds_read2_b32 v[232:233], v245 offset0:56 offset1:60
	s_waitcnt vmcnt(8)
	v_mfma_scale_f32_16x16x128_f8f6f4 v[80:83], v[32:35], v[178:185], 0, v133, v133 op_sel_hi:[0,0,0] cbsz:4
	v_mfma_scale_f32_16x16x128_f8f6f4 v[80:83], v[36:39], v[186:193], v[80:83], v133, v133 op_sel_hi:[0,0,0] cbsz:4
	v_mfma_scale_f32_16x16x128_f8f6f4 v[84:87], v[40:43], v[178:185], 0, v133, v133 op_sel_hi:[0,0,0] cbsz:4
	v_mfma_scale_f32_16x16x128_f8f6f4 v[84:87], v[44:47], v[186:193], v[84:87], v133, v133 op_sel_hi:[0,0,0] cbsz:4
	v_mfma_scale_f32_16x16x128_f8f6f4 v[88:91], v[48:51], v[178:185], 0, v133, v133 op_sel_hi:[0,0,0] cbsz:4
	v_mfma_scale_f32_16x16x128_f8f6f4 v[88:91], v[52:55], v[186:193], v[88:91], v133, v133 op_sel_hi:[0,0,0] cbsz:4
	v_mfma_scale_f32_16x16x128_f8f6f4 v[92:95], v[56:59], v[178:185], 0, v133, v133 op_sel_hi:[0,0,0] cbsz:4
	v_mfma_scale_f32_16x16x128_f8f6f4 v[92:95], v[60:63], v[186:193], v[92:95], v133, v133 op_sel_hi:[0,0,0] cbsz:4
	s_nop 3
	v_mul_f32_e32 v234, v226, v64
	v_mul_f32_e32 v235, v226, v68
	v_mul_f32_e32 v236, v226, v72
	v_mul_f32_e32 v237, v226, v76
	v_fmac_f32_e32 v234, v227, v65
	v_fmac_f32_e32 v235, v227, v69
	v_fmac_f32_e32 v236, v227, v73
	v_fmac_f32_e32 v237, v227, v77
	v_fmac_f32_e32 v234, v228, v66
	v_fmac_f32_e32 v235, v228, v70
	v_fmac_f32_e32 v236, v228, v74
	v_fmac_f32_e32 v237, v228, v78
	v_fmac_f32_e32 v234, v229, v67
	v_fmac_f32_e32 v235, v229, v71
	v_fmac_f32_e32 v236, v229, v75
	v_fmac_f32_e32 v237, v229, v79
	v_add_f32_dpp v234, v234, v234 quad_perm:[1,0,3,2] row_mask:0xf bank_mask:0xf
	v_add_f32_dpp v235, v235, v235 quad_perm:[1,0,3,2] row_mask:0xf bank_mask:0xf
	v_add_f32_dpp v236, v236, v236 quad_perm:[1,0,3,2] row_mask:0xf bank_mask:0xf
	v_add_f32_dpp v237, v237, v237 quad_perm:[1,0,3,2] row_mask:0xf bank_mask:0xf
	v_add_f32_dpp v234, v234, v234 quad_perm:[2,3,0,1] row_mask:0xf bank_mask:0xf
	v_add_f32_dpp v235, v235, v235 quad_perm:[2,3,0,1] row_mask:0xf bank_mask:0xf
	v_add_f32_dpp v236, v236, v236 quad_perm:[2,3,0,1] row_mask:0xf bank_mask:0xf
	v_add_f32_dpp v237, v237, v237 quad_perm:[2,3,0,1] row_mask:0xf bank_mask:0xf
	v_add_f32_dpp v234, v234, v234 row_half_mirror row_mask:0xf bank_mask:0xf
	v_add_f32_dpp v235, v235, v235 row_half_mirror row_mask:0xf bank_mask:0xf
	v_add_f32_dpp v236, v236, v236 row_half_mirror row_mask:0xf bank_mask:0xf
	v_add_f32_dpp v237, v237, v237 row_half_mirror row_mask:0xf bank_mask:0xf
	s_mov_b32 exec_lo, 0x1000100
	s_mov_b32 exec_hi, 0x1000100
	ds_write_b32 v155, v234 offset:2240
	ds_write_b32 v155, v235 offset:2256
	ds_write_b32 v155, v236 offset:2272
	ds_write_b32 v155, v237 offset:2288
	s_mov_b64 exec, -1
	s_waitcnt lgkmcnt(0)
; __device__ __forceinline__ void peer_token(const Params& P, int t, int lane, int* sidx, float* sval, const int* sid, const float* sgate, const unsigned* szero) {
;     ...
;         for (int hh = 0; hh < 2; ++hh) off2[hh] = (unsigned)sid[8 * hh + (lr & 7)] * 512u + lofs;
; #pragma unroll
;         for (int hh = 0; hh < 2; ++hh)
; #pragma unroll
;             for (int st = 0; st < 4; ++st) abuf[0][hh][st] = *(const uint4*)(Ub + (off2[hh] + 128 * st));
; #pragma unroll
;         for (int T = 0; T < 8; ++T) {
;             if (T + 1 < 8) {
; #pragma unroll
;                 for (int hh = 0; hh < 2; ++hh) off2[hh] = (unsigned)sid[16 * (T + 1) + 8 * hh + (lr & 7)] * 512u + lofs;
; #pragma unroll
;                 for (int hh = 0; hh < 2; ++hh)
; #pragma unroll
;                     for (int st = 0; st < 4; ++st) abuf[(T + 1) & 1][hh][st] = *(const uint4*)(Ub + (off2[hh] + 128 * st));
;             }
; #pragma unroll
;             for (int hh = 0; hh < 2; ++hh) {
;                 f32x4 au = (f32x4){0.f, 0.f, 0.f, 0.f};
; #pragma unroll
;                 for (int st = 0; st < 4; ++st) {
;                     const uint4 a4 = abuf[T & 1][hh][st];
;                     const v8i Av = {(int)a4.x, (int)a4.y, (int)a4.z, (int)a4.w, 0, 0, 0, 0};
;                     au = __builtin_amdgcn_mfma_scale_f32_16x16x128_f8f6f4(Av, Bv[st], au, 4, 0, 0, 0x7f7f7f7f, 0, 0x7f7f7f7f);
;                 }
;                 if (owner) *(f32x4*)(sact + 16 * T + 8 * hh) = au;
;             }
	v_lshl_add_u32 v230, v230, 9, v144
	v_lshl_add_u32 v231, v231, 9, v144
	v_lshl_add_u32 v232, v232, 9, v144
	v_lshl_add_u32 v233, v233, 9, v144
	global_load_dwordx4 v[32:35], v230, s[10:11]
	global_load_dwordx4 v[36:39], v230, s[10:11] offset:256
	global_load_dwordx4 v[40:43], v231, s[10:11]
	global_load_dwordx4 v[44:47], v231, s[10:11] offset:256
	global_load_dwordx4 v[48:51], v232, s[10:11]
	global_load_dwordx4 v[52:55], v232, s[10:11] offset:256
	global_load_dwordx4 v[56:59], v233, s[10:11]
	global_load_dwordx4 v[60:63], v233, s[10:11] offset:256
	ds_read2_b32 v[96:97], v238 offset0:64 offset1:68
	ds_read2_b32 v[98:99], v238 offset0:72 offset1:76
	s_waitcnt vmcnt(8)
	v_mfma_scale_f32_16x16x128_f8f6f4 v[64:67], v[0:3], v[194:201], 0, v133, v133 op_sel_hi:[0,0,0] cbsz:4
	v_mfma_scale_f32_16x16x128_f8f6f4 v[64:67], v[4:7], v[202:209], v[64:67], v133, v133 op_sel_hi:[0,0,0] cbsz:4
	v_mfma_scale_f32_16x16x128_f8f6f4 v[68:71], v[8:11], v[194:201], 0, v133, v133 op_sel_hi:[0,0,0] cbsz:4
	v_mfma_scale_f32_16x16x128_f8f6f4 v[68:71], v[12:15], v[202:209], v[68:71], v133, v133 op_sel_hi:[0,0,0] cbsz:4
	v_mfma_scale_f32_16x16x128_f8f6f4 v[72:75], v[16:19], v[194:201], 0, v133, v133 op_sel_hi:[0,0,0] cbsz:4
	v_mfma_scale_f32_16x16x128_f8f6f4 v[72:75], v[20:23], v[202:209], v[72:75], v133, v133 op_sel_hi:[0,0,0] cbsz:4
	v_mfma_scale_f32_16x16x128_f8f6f4 v[76:79], v[24:27], v[194:201], 0, v133, v133 op_sel_hi:[0,0,0] cbsz:4
	v_mfma_scale_f32_16x16x128_f8f6f4 v[76:79], v[28:31], v[202:209], v[76:79], v133, v133 op_sel_hi:[0,0,0] cbsz:4
	s_nop 3
	v_mul_f32_e32 v234, v226, v80
	v_mul_f32_e32 v235, v226, v84
	v_mul_f32_e32 v236, v226, v88
	v_mul_f32_e32 v237, v226, v92
	v_fmac_f32_e32 v234, v227, v81
	v_fmac_f32_e32 v235, v227, v85
	v_fmac_f32_e32 v236, v227, v89
	v_fmac_f32_e32 v237, v227, v93
	v_fmac_f32_e32 v234, v228, v82
	v_fmac_f32_e32 v235, v228, v86
	v_fmac_f32_e32 v236, v228, v90
	v_fmac_f32_e32 v237, v228, v94
	v_fmac_f32_e32 v234, v229, v83
	v_fmac_f32_e32 v235, v229, v87
	v_fmac_f32_e32 v236, v229, v91
	v_fmac_f32_e32 v237, v229, v95
	v_add_f32_dpp v234, v234, v234 quad_perm:[1,0,3,2] row_mask:0xf bank_mask:0xf
	v_add_f32_dpp v235, v235, v235 quad_perm:[1,0,3,2] row_mask:0xf bank_mask:0xf
	v_add_f32_dpp v236, v236, v236 quad_perm:[1,0,3,2] row_mask:0xf bank_mask:0xf
	v_add_f32_dpp v237, v237, v237 quad_perm:[1,0,3,2] row_mask:0xf bank_mask:0xf
	v_add_f32_dpp v234, v234, v234 quad_perm:[2,3,0,1] row_mask:0xf bank_mask:0xf
	v_add_f32_dpp v235, v235, v235 quad_perm:[2,3,0,1] row_mask:0xf bank_mask:0xf
	v_add_f32_dpp v236, v236, v236 quad_perm:[2,3,0,1] row_mask:0xf bank_mask:0xf
	v_add_f32_dpp v237, v237, v237 quad_perm:[2,3,0,1] row_mask:0xf bank_mask:0xf
	v_add_f32_dpp v234, v234, v234 row_half_mirror row_mask:0xf bank_mask:0xf
	v_add_f32_dpp v235, v235, v235 row_half_mirror row_mask:0xf bank_mask:0xf
	v_add_f32_dpp v236, v236, v236 row_half_mirror row_mask:0xf bank_mask:0xf
	v_add_f32_dpp v237, v237, v237 row_half_mirror row_mask:0xf bank_mask:0xf
	s_mov_b32 exec_lo, 0x1000100
	s_mov_b32 exec_hi, 0x1000100
	ds_write_b32 v155, v234 offset:2752
	ds_write_b32 v155, v235 offset:2768
	ds_write_b32 v155, v236 offset:2784
	ds_write_b32 v155, v237 offset:2800
	s_mov_b64 exec, -1
	s_waitcnt lgkmcnt(0)
	v_lshl_add_u32 v96, v96, 9, v144
	v_lshl_add_u32 v97, v97, 9, v144
	v_lshl_add_u32 v98, v98, 9, v144
	v_lshl_add_u32 v99, v99, 9, v144
	global_load_dwordx4 v[0:3], v96, s[10:11]
	global_load_dwordx4 v[4:7], v96, s[10:11] offset:256
	global_load_dwordx4 v[8:11], v97, s[10:11]
	global_load_dwordx4 v[12:15], v97, s[10:11] offset:256
	global_load_dwordx4 v[16:19], v98, s[10:11]
	global_load_dwordx4 v[20:23], v98, s[10:11] offset:256
	global_load_dwordx4 v[24:27], v99, s[10:11]
	global_load_dwordx4 v[28:31], v99, s[10:11] offset:256
	ds_read2_b32 v[230:231], v239 offset0:64 offset1:68
	ds_read2_b32 v[232:233], v239 offset0:72 offset1:76
	s_waitcnt vmcnt(8)
	v_mfma_scale_f32_16x16x128_f8f6f4 v[80:83], v[32:35], v[210:217], 0, v133, v133 op_sel_hi:[0,0,0] cbsz:4
	v_mfma_scale_f32_16x16x128_f8f6f4 v[80:83], v[36:39], v[218:225], v[80:83], v133, v133 op_sel_hi:[0,0,0] cbsz:4
	v_mfma_scale_f32_16x16x128_f8f6f4 v[84:87], v[40:43], v[210:217], 0, v133, v133 op_sel_hi:[0,0,0] cbsz:4
	v_mfma_scale_f32_16x16x128_f8f6f4 v[84:87], v[44:47], v[218:225], v[84:87], v133, v133 op_sel_hi:[0,0,0] cbsz:4
	v_mfma_scale_f32_16x16x128_f8f6f4 v[88:91], v[48:51], v[210:217], 0, v133, v133 op_sel_hi:[0,0,0] cbsz:4
	v_mfma_scale_f32_16x16x128_f8f6f4 v[88:91], v[52:55], v[218:225], v[88:91], v133, v133 op_sel_hi:[0,0,0] cbsz:4
	v_mfma_scale_f32_16x16x128_f8f6f4 v[92:95], v[56:59], v[210:217], 0, v133, v133 op_sel_hi:[0,0,0] cbsz:4
	v_mfma_scale_f32_16x16x128_f8f6f4 v[92:95], v[60:63], v[218:225], v[92:95], v133, v133 op_sel_hi:[0,0,0] cbsz:4
	s_nop 3
	v_mul_f32_e32 v234, v226, v64
	v_mul_f32_e32 v235, v226, v68
	v_mul_f32_e32 v236, v226, v72
	v_mul_f32_e32 v237, v226, v76
	v_fmac_f32_e32 v234, v227, v65
	v_fmac_f32_e32 v235, v227, v69
	v_fmac_f32_e32 v236, v227, v73
	v_fmac_f32_e32 v237, v227, v77
	v_fmac_f32_e32 v234, v228, v66
	v_fmac_f32_e32 v235, v228, v70
	v_fmac_f32_e32 v236, v228, v74
	v_fmac_f32_e32 v237, v228, v78
	v_fmac_f32_e32 v234, v229, v67
	v_fmac_f32_e32 v235, v229, v71
	v_fmac_f32_e32 v236, v229, v75
	v_fmac_f32_e32 v237, v229, v79
	v_add_f32_dpp v234, v234, v234 quad_perm:[1,0,3,2] row_mask:0xf bank_mask:0xf
	v_add_f32_dpp v235, v235, v235 quad_perm:[1,0,3,2] row_mask:0xf bank_mask:0xf
	v_add_f32_dpp v236, v236, v236 quad_perm:[1,0,3,2] row_mask:0xf bank_mask:0xf
	v_add_f32_dpp v237, v237, v237 quad_perm:[1,0,3,2] row_mask:0xf bank_mask:0xf
	v_add_f32_dpp v234, v234, v234 quad_perm:[2,3,0,1] row_mask:0xf bank_mask:0xf
	v_add_f32_dpp v235, v235, v235 quad_perm:[2,3,0,1] row_mask:0xf bank_mask:0xf
	v_add_f32_dpp v236, v236, v236 quad_perm:[2,3,0,1] row_mask:0xf bank_mask:0xf
	v_add_f32_dpp v237, v237, v237 quad_perm:[2,3,0,1] row_mask:0xf bank_mask:0xf
	v_add_f32_dpp v234, v234, v234 row_half_mirror row_mask:0xf bank_mask:0xf
	v_add_f32_dpp v235, v235, v235 row_half_mirror row_mask:0xf bank_mask:0xf
	v_add_f32_dpp v236, v236, v236 row_half_mirror row_mask:0xf bank_mask:0xf
	v_add_f32_dpp v237, v237, v237 row_half_mirror row_mask:0xf bank_mask:0xf
	s_mov_b32 exec_lo, 0x1000100
	s_mov_b32 exec_hi, 0x1000100
	ds_write_b32 v155, v234 offset:3264
	ds_write_b32 v155, v235 offset:3280
	ds_write_b32 v155, v236 offset:3296
	ds_write_b32 v155, v237 offset:3312
	s_mov_b64 exec, -1
	s_waitcnt lgkmcnt(0)
; __device__ __forceinline__ void peer_token(const Params& P, int t, int lane, int* sidx, float* sval, const int* sid, const float* sgate, const unsigned* szero) {
;     ...
;         for (int hh = 0; hh < 2; ++hh) off2[hh] = (unsigned)sid[8 * hh + (lr & 7)] * 512u + lofs;
; #pragma unroll
;         for (int hh = 0; hh < 2; ++hh)
; #pragma unroll
;             for (int st = 0; st < 4; ++st) abuf[0][hh][st] = *(const uint4*)(Ub + (off2[hh] + 128 * st));
; #pragma unroll
;         for (int T = 0; T < 8; ++T) {
;             if (T + 1 < 8) {
; #pragma unroll
;                 for (int hh = 0; hh < 2; ++hh) off2[hh] = (unsigned)sid[16 * (T + 1) + 8 * hh + (lr & 7)] * 512u + lofs;
; #pragma unroll
;                 for (int hh = 0; hh < 2; ++hh)
; #pragma unroll
;                     for (int st = 0; st < 4; ++st) abuf[(T + 1) & 1][hh][st] = *(const uint4*)(Ub + (off2[hh] + 128 * st));
;             }
; #pragma unroll
;             for (int hh = 0; hh < 2; ++hh) {
;                 f32x4 au = (f32x4){0.f, 0.f, 0.f, 0.f};
; #pragma unroll
;                 for (int st = 0; st < 4; ++st) {
;                     const uint4 a4 = abuf[T & 1][hh][st];
;                     const v8i Av = {(int)a4.x, (int)a4.y, (int)a4.z, (int)a4.w, 0, 0, 0, 0};
;                     au = __builtin_amdgcn_mfma_scale_f32_16x16x128_f8f6f4(Av, Bv[st], au, 4, 0, 0, 0x7f7f7f7f, 0, 0x7f7f7f7f);
;                 }
;                 if (owner) *(f32x4*)(sact + 16 * T + 8 * hh) = au;
;             }
	v_lshl_add_u32 v230, v230, 9, v144
	v_lshl_add_u32 v231, v231, 9, v144
	v_lshl_add_u32 v232, v232, 9, v144
	v_lshl_add_u32 v233, v233, 9, v144
	global_load_dwordx4 v[32:35], v230, s[10:11]
	global_load_dwordx4 v[36:39], v230, s[10:11] offset:256
	global_load_dwordx4 v[40:43], v231, s[10:11]
	global_load_dwordx4 v[44:47], v231, s[10:11] offset:256
	global_load_dwordx4 v[48:51], v232, s[10:11]
	global_load_dwordx4 v[52:55], v232, s[10:11] offset:256
	global_load_dwordx4 v[56:59], v233, s[10:11]
	global_load_dwordx4 v[60:63], v233, s[10:11] offset:256
	ds_read2_b32 v[96:97], v240 offset0:64 offset1:68
	ds_read2_b32 v[98:99], v240 offset0:72 offset1:76
	s_waitcnt vmcnt(8)
	v_mfma_scale_f32_16x16x128_f8f6f4 v[64:67], v[0:3], v[162:169], 0, v133, v133 op_sel_hi:[0,0,0] cbsz:4
	v_mfma_scale_f32_16x16x128_f8f6f4 v[64:67], v[4:7], v[170:177], v[64:67], v133, v133 op_sel_hi:[0,0,0] cbsz:4
	v_mfma_scale_f32_16x16x128_f8f6f4 v[68:71], v[8:11], v[162:169], 0, v133, v133 op_sel_hi:[0,0,0] cbsz:4
	v_mfma_scale_f32_16x16x128_f8f6f4 v[68:71], v[12:15], v[170:177], v[68:71], v133, v133 op_sel_hi:[0,0,0] cbsz:4
	v_mfma_scale_f32_16x16x128_f8f6f4 v[72:75], v[16:19], v[162:169], 0, v133, v133 op_sel_hi:[0,0,0] cbsz:4
	v_mfma_scale_f32_16x16x128_f8f6f4 v[72:75], v[20:23], v[170:177], v[72:75], v133, v133 op_sel_hi:[0,0,0] cbsz:4
	v_mfma_scale_f32_16x16x128_f8f6f4 v[76:79], v[24:27], v[162:169], 0, v133, v133 op_sel_hi:[0,0,0] cbsz:4
	v_mfma_scale_f32_16x16x128_f8f6f4 v[76:79], v[28:31], v[170:177], v[76:79], v133, v133 op_sel_hi:[0,0,0] cbsz:4
	s_nop 3
	v_mul_f32_e32 v234, v226, v80
	v_mul_f32_e32 v235, v226, v84
	v_mul_f32_e32 v236, v226, v88
	v_mul_f32_e32 v237, v226, v92
	v_fmac_f32_e32 v234, v227, v81
	v_fmac_f32_e32 v235, v227, v85
	v_fmac_f32_e32 v236, v227, v89
	v_fmac_f32_e32 v237, v227, v93
	v_fmac_f32_e32 v234, v228, v82
	v_fmac_f32_e32 v235, v228, v86
	v_fmac_f32_e32 v236, v228, v90
	v_fmac_f32_e32 v237, v228, v94
	v_fmac_f32_e32 v234, v229, v83
	v_fmac_f32_e32 v235, v229, v87
	v_fmac_f32_e32 v236, v229, v91
	v_fmac_f32_e32 v237, v229, v95
	v_add_f32_dpp v234, v234, v234 quad_perm:[1,0,3,2] row_mask:0xf bank_mask:0xf
	v_add_f32_dpp v235, v235, v235 quad_perm:[1,0,3,2] row_mask:0xf bank_mask:0xf
	v_add_f32_dpp v236, v236, v236 quad_perm:[1,0,3,2] row_mask:0xf bank_mask:0xf
	v_add_f32_dpp v237, v237, v237 quad_perm:[1,0,3,2] row_mask:0xf bank_mask:0xf
	v_add_f32_dpp v234, v234, v234 quad_perm:[2,3,0,1] row_mask:0xf bank_mask:0xf
	v_add_f32_dpp v235, v235, v235 quad_perm:[2,3,0,1] row_mask:0xf bank_mask:0xf
	v_add_f32_dpp v236, v236, v236 quad_perm:[2,3,0,1] row_mask:0xf bank_mask:0xf
	v_add_f32_dpp v237, v237, v237 quad_perm:[2,3,0,1] row_mask:0xf bank_mask:0xf
	v_add_f32_dpp v234, v234, v234 row_half_mirror row_mask:0xf bank_mask:0xf
	v_add_f32_dpp v235, v235, v235 row_half_mirror row_mask:0xf bank_mask:0xf
	v_add_f32_dpp v236, v236, v236 row_half_mirror row_mask:0xf bank_mask:0xf
	v_add_f32_dpp v237, v237, v237 row_half_mirror row_mask:0xf bank_mask:0xf
	s_mov_b32 exec_lo, 0x1000100
	s_mov_b32 exec_hi, 0x1000100
	ds_write_b32 v155, v234 offset:3776
	ds_write_b32 v155, v235 offset:3792
	ds_write_b32 v155, v236 offset:3808
	ds_write_b32 v155, v237 offset:3824
	s_mov_b64 exec, -1
	s_waitcnt lgkmcnt(0)
	v_lshl_add_u32 v96, v96, 9, v144
	v_lshl_add_u32 v97, v97, 9, v144
	v_lshl_add_u32 v98, v98, 9, v144
	v_lshl_add_u32 v99, v99, 9, v144
	global_load_dwordx4 v[0:3], v96, s[10:11]
	global_load_dwordx4 v[4:7], v96, s[10:11] offset:256
	global_load_dwordx4 v[8:11], v97, s[10:11]
	global_load_dwordx4 v[12:15], v97, s[10:11] offset:256
	global_load_dwordx4 v[16:19], v98, s[10:11]
	global_load_dwordx4 v[20:23], v98, s[10:11] offset:256
	global_load_dwordx4 v[24:27], v99, s[10:11]
	global_load_dwordx4 v[28:31], v99, s[10:11] offset:256
	ds_read2_b32 v[230:231], v241 offset0:64 offset1:68
	ds_read2_b32 v[232:233], v241 offset0:72 offset1:76
	s_waitcnt vmcnt(8)
	v_mfma_scale_f32_16x16x128_f8f6f4 v[80:83], v[32:35], v[178:185], 0, v133, v133 op_sel_hi:[0,0,0] cbsz:4
	v_mfma_scale_f32_16x16x128_f8f6f4 v[80:83], v[36:39], v[186:193], v[80:83], v133, v133 op_sel_hi:[0,0,0] cbsz:4
	v_mfma_scale_f32_16x16x128_f8f6f4 v[84:87], v[40:43], v[178:185], 0, v133, v133 op_sel_hi:[0,0,0] cbsz:4
	v_mfma_scale_f32_16x16x128_f8f6f4 v[84:87], v[44:47], v[186:193], v[84:87], v133, v133 op_sel_hi:[0,0,0] cbsz:4
	v_mfma_scale_f32_16x16x128_f8f6f4 v[88:91], v[48:51], v[178:185], 0, v133, v133 op_sel_hi:[0,0,0] cbsz:4
	v_mfma_scale_f32_16x16x128_f8f6f4 v[88:91], v[52:55], v[186:193], v[88:91], v133, v133 op_sel_hi:[0,0,0] cbsz:4
	v_mfma_scale_f32_16x16x128_f8f6f4 v[92:95], v[56:59], v[178:185], 0, v133, v133 op_sel_hi:[0,0,0] cbsz:4
	v_mfma_scale_f32_16x16x128_f8f6f4 v[92:95], v[60:63], v[186:193], v[92:95], v133, v133 op_sel_hi:[0,0,0] cbsz:4
	s_nop 3
	v_mul_f32_e32 v234, v158, v64
	v_mul_f32_e32 v235, v158, v68
	v_mul_f32_e32 v236, v158, v72
	v_mul_f32_e32 v237, v158, v76
	v_fmac_f32_e32 v234, v159, v65
	v_fmac_f32_e32 v235, v159, v69
	v_fmac_f32_e32 v236, v159, v73
	v_fmac_f32_e32 v237, v159, v77
	v_fmac_f32_e32 v234, v160, v66
	v_fmac_f32_e32 v235, v160, v70
	v_fmac_f32_e32 v236, v160, v74
	v_fmac_f32_e32 v237, v160, v78
	v_fmac_f32_e32 v234, v161, v67
	v_fmac_f32_e32 v235, v161, v71
	v_fmac_f32_e32 v236, v161, v75
	v_fmac_f32_e32 v237, v161, v79
	v_add_f32_dpp v234, v234, v234 quad_perm:[1,0,3,2] row_mask:0xf bank_mask:0xf
	v_add_f32_dpp v235, v235, v235 quad_perm:[1,0,3,2] row_mask:0xf bank_mask:0xf
	v_add_f32_dpp v236, v236, v236 quad_perm:[1,0,3,2] row_mask:0xf bank_mask:0xf
	v_add_f32_dpp v237, v237, v237 quad_perm:[1,0,3,2] row_mask:0xf bank_mask:0xf
	v_add_f32_dpp v234, v234, v234 quad_perm:[2,3,0,1] row_mask:0xf bank_mask:0xf
	v_add_f32_dpp v235, v235, v235 quad_perm:[2,3,0,1] row_mask:0xf bank_mask:0xf
	v_add_f32_dpp v236, v236, v236 quad_perm:[2,3,0,1] row_mask:0xf bank_mask:0xf
	v_add_f32_dpp v237, v237, v237 quad_perm:[2,3,0,1] row_mask:0xf bank_mask:0xf
	v_add_f32_dpp v234, v234, v234 row_half_mirror row_mask:0xf bank_mask:0xf
	v_add_f32_dpp v235, v235, v235 row_half_mirror row_mask:0xf bank_mask:0xf
	v_add_f32_dpp v236, v236, v236 row_half_mirror row_mask:0xf bank_mask:0xf
	v_add_f32_dpp v237, v237, v237 row_half_mirror row_mask:0xf bank_mask:0xf
	s_mov_b32 exec_lo, 0x10001
	s_mov_b32 exec_hi, 0x10001
	ds_write_b32 v155, v234 offset:256
	ds_write_b32 v155, v235 offset:272
	ds_write_b32 v155, v236 offset:288
	ds_write_b32 v155, v237 offset:304
	s_mov_b64 exec, -1
	s_waitcnt lgkmcnt(0)
; __device__ __forceinline__ void peer_token(const Params& P, int t, int lane, int* sidx, float* sval, const int* sid, const float* sgate, const unsigned* szero) {
;     ...
;         for (int hh = 0; hh < 2; ++hh) off2[hh] = (unsigned)sid[8 * hh + (lr & 7)] * 512u + lofs;
; #pragma unroll
;         for (int hh = 0; hh < 2; ++hh)
; #pragma unroll
;             for (int st = 0; st < 4; ++st) abuf[0][hh][st] = *(const uint4*)(Ub + (off2[hh] + 128 * st));
; #pragma unroll
;         for (int T = 0; T < 8; ++T) {
;             if (T + 1 < 8) {
; #pragma unroll
;                 for (int hh = 0; hh < 2; ++hh) off2[hh] = (unsigned)sid[16 * (T + 1) + 8 * hh + (lr & 7)] * 512u + lofs;
; #pragma unroll
;                 for (int hh = 0; hh < 2; ++hh)
; #pragma unroll
;                     for (int st = 0; st < 4; ++st) abuf[(T + 1) & 1][hh][st] = *(const uint4*)(Ub + (off2[hh] + 128 * st));
;             }
; #pragma unroll
;             for (int hh = 0; hh < 2; ++hh) {
;                 f32x4 au = (f32x4){0.f, 0.f, 0.f, 0.f};
; #pragma unroll
;                 for (int st = 0; st < 4; ++st) {
;                     const uint4 a4 = abuf[T & 1][hh][st];
;                     const v8i Av = {(int)a4.x, (int)a4.y, (int)a4.z, (int)a4.w, 0, 0, 0, 0};
;                     au = __builtin_amdgcn_mfma_scale_f32_16x16x128_f8f6f4(Av, Bv[st], au, 4, 0, 0, 0x7f7f7f7f, 0, 0x7f7f7f7f);
;                 }
;                 if (owner) *(f32x4*)(sact + 16 * T + 8 * hh) = au;
;             }
	v_lshl_add_u32 v230, v230, 9, v144
	v_lshl_add_u32 v231, v231, 9, v144
	v_lshl_add_u32 v232, v232, 9, v144
	v_lshl_add_u32 v233, v233, 9, v144
	global_load_dwordx4 v[32:35], v230, s[10:11]
	global_load_dwordx4 v[36:39], v230, s[10:11] offset:256
	global_load_dwordx4 v[40:43], v231, s[10:11]
	global_load_dwordx4 v[44:47], v231, s[10:11] offset:256
	global_load_dwordx4 v[48:51], v232, s[10:11]
	global_load_dwordx4 v[52:55], v232, s[10:11] offset:256
	global_load_dwordx4 v[56:59], v233, s[10:11]
	global_load_dwordx4 v[60:63], v233, s[10:11] offset:256
	ds_read2_b32 v[96:97], v242 offset0:64 offset1:68
	ds_read2_b32 v[98:99], v242 offset0:72 offset1:76
	s_waitcnt vmcnt(8)
	v_mfma_scale_f32_16x16x128_f8f6f4 v[64:67], v[0:3], v[194:201], 0, v133, v133 op_sel_hi:[0,0,0] cbsz:4
	v_mfma_scale_f32_16x16x128_f8f6f4 v[64:67], v[4:7], v[202:209], v[64:67], v133, v133 op_sel_hi:[0,0,0] cbsz:4
	v_mfma_scale_f32_16x16x128_f8f6f4 v[68:71], v[8:11], v[194:201], 0, v133, v133 op_sel_hi:[0,0,0] cbsz:4
	v_mfma_scale_f32_16x16x128_f8f6f4 v[68:71], v[12:15], v[202:209], v[68:71], v133, v133 op_sel_hi:[0,0,0] cbsz:4
	v_mfma_scale_f32_16x16x128_f8f6f4 v[72:75], v[16:19], v[194:201], 0, v133, v133 op_sel_hi:[0,0,0] cbsz:4
	v_mfma_scale_f32_16x16x128_f8f6f4 v[72:75], v[20:23], v[202:209], v[72:75], v133, v133 op_sel_hi:[0,0,0] cbsz:4
	v_mfma_scale_f32_16x16x128_f8f6f4 v[76:79], v[24:27], v[194:201], 0, v133, v133 op_sel_hi:[0,0,0] cbsz:4
	v_mfma_scale_f32_16x16x128_f8f6f4 v[76:79], v[28:31], v[202:209], v[76:79], v133, v133 op_sel_hi:[0,0,0] cbsz:4
	s_nop 3
	v_mul_f32_e32 v234, v158, v80
	v_mul_f32_e32 v235, v158, v84
	v_mul_f32_e32 v236, v158, v88
	v_mul_f32_e32 v237, v158, v92
	v_fmac_f32_e32 v234, v159, v81
	v_fmac_f32_e32 v235, v159, v85
	v_fmac_f32_e32 v236, v159, v89
	v_fmac_f32_e32 v237, v159, v93
	v_fmac_f32_e32 v234, v160, v82
	v_fmac_f32_e32 v235, v160, v86
	v_fmac_f32_e32 v236, v160, v90
	v_fmac_f32_e32 v237, v160, v94
	v_fmac_f32_e32 v234, v161, v83
	v_fmac_f32_e32 v235, v161, v87
	v_fmac_f32_e32 v236, v161, v91
	v_fmac_f32_e32 v237, v161, v95
	v_add_f32_dpp v234, v234, v234 quad_perm:[1,0,3,2] row_mask:0xf bank_mask:0xf
	v_add_f32_dpp v235, v235, v235 quad_perm:[1,0,3,2] row_mask:0xf bank_mask:0xf
	v_add_f32_dpp v236, v236, v236 quad_perm:[1,0,3,2] row_mask:0xf bank_mask:0xf
	v_add_f32_dpp v237, v237, v237 quad_perm:[1,0,3,2] row_mask:0xf bank_mask:0xf
	v_add_f32_dpp v234, v234, v234 quad_perm:[2,3,0,1] row_mask:0xf bank_mask:0xf
	v_add_f32_dpp v235, v235, v235 quad_perm:[2,3,0,1] row_mask:0xf bank_mask:0xf
	v_add_f32_dpp v236, v236, v236 quad_perm:[2,3,0,1] row_mask:0xf bank_mask:0xf
	v_add_f32_dpp v237, v237, v237 quad_perm:[2,3,0,1] row_mask:0xf bank_mask:0xf
	v_add_f32_dpp v234, v234, v234 row_half_mirror row_mask:0xf bank_mask:0xf
	v_add_f32_dpp v235, v235, v235 row_half_mirror row_mask:0xf bank_mask:0xf
	v_add_f32_dpp v236, v236, v236 row_half_mirror row_mask:0xf bank_mask:0xf
	v_add_f32_dpp v237, v237, v237 row_half_mirror row_mask:0xf bank_mask:0xf
	s_mov_b32 exec_lo, 0x10001
	s_mov_b32 exec_hi, 0x10001
	ds_write_b32 v155, v234 offset:768
	ds_write_b32 v155, v235 offset:784
	ds_write_b32 v155, v236 offset:800
	ds_write_b32 v155, v237 offset:816
	s_mov_b64 exec, -1
	s_waitcnt lgkmcnt(0)
	v_lshl_add_u32 v96, v96, 9, v144
	v_lshl_add_u32 v97, v97, 9, v144
	v_lshl_add_u32 v98, v98, 9, v144
	v_lshl_add_u32 v99, v99, 9, v144
	global_load_dwordx4 v[0:3], v96, s[10:11]
	global_load_dwordx4 v[4:7], v96, s[10:11] offset:256
	global_load_dwordx4 v[8:11], v97, s[10:11]
	global_load_dwordx4 v[12:15], v97, s[10:11] offset:256
	global_load_dwordx4 v[16:19], v98, s[10:11]
	global_load_dwordx4 v[20:23], v98, s[10:11] offset:256
	global_load_dwordx4 v[24:27], v99, s[10:11]
	global_load_dwordx4 v[28:31], v99, s[10:11] offset:256
	ds_read2_b32 v[230:231], v243 offset0:64 offset1:68
	ds_read2_b32 v[232:233], v243 offset0:72 offset1:76
	s_waitcnt vmcnt(8)
	v_mfma_scale_f32_16x16x128_f8f6f4 v[80:83], v[32:35], v[210:217], 0, v133, v133 op_sel_hi:[0,0,0] cbsz:4
	v_mfma_scale_f32_16x16x128_f8f6f4 v[80:83], v[36:39], v[218:225], v[80:83], v133, v133 op_sel_hi:[0,0,0] cbsz:4
	v_mfma_scale_f32_16x16x128_f8f6f4 v[84:87], v[40:43], v[210:217], 0, v133, v133 op_sel_hi:[0,0,0] cbsz:4
	v_mfma_scale_f32_16x16x128_f8f6f4 v[84:87], v[44:47], v[218:225], v[84:87], v133, v133 op_sel_hi:[0,0,0] cbsz:4
	v_mfma_scale_f32_16x16x128_f8f6f4 v[88:91], v[48:51], v[210:217], 0, v133, v133 op_sel_hi:[0,0,0] cbsz:4
	v_mfma_scale_f32_16x16x128_f8f6f4 v[88:91], v[52:55], v[218:225], v[88:91], v133, v133 op_sel_hi:[0,0,0] cbsz:4
	v_mfma_scale_f32_16x16x128_f8f6f4 v[92:95], v[56:59], v[210:217], 0, v133, v133 op_sel_hi:[0,0,0] cbsz:4
	v_mfma_scale_f32_16x16x128_f8f6f4 v[92:95], v[60:63], v[218:225], v[92:95], v133, v133 op_sel_hi:[0,0,0] cbsz:4
	s_nop 3
	v_mul_f32_e32 v234, v158, v64
	v_mul_f32_e32 v235, v158, v68
	v_mul_f32_e32 v236, v158, v72
	v_mul_f32_e32 v237, v158, v76
	v_fmac_f32_e32 v234, v159, v65
	v_fmac_f32_e32 v235, v159, v69
	v_fmac_f32_e32 v236, v159, v73
	v_fmac_f32_e32 v237, v159, v77
	v_fmac_f32_e32 v234, v160, v66
	v_fmac_f32_e32 v235, v160, v70
	v_fmac_f32_e32 v236, v160, v74
	v_fmac_f32_e32 v237, v160, v78
	v_fmac_f32_e32 v234, v161, v67
	v_fmac_f32_e32 v235, v161, v71
	v_fmac_f32_e32 v236, v161, v75
	v_fmac_f32_e32 v237, v161, v79
	v_add_f32_dpp v234, v234, v234 quad_perm:[1,0,3,2] row_mask:0xf bank_mask:0xf
	v_add_f32_dpp v235, v235, v235 quad_perm:[1,0,3,2] row_mask:0xf bank_mask:0xf
	v_add_f32_dpp v236, v236, v236 quad_perm:[1,0,3,2] row_mask:0xf bank_mask:0xf
	v_add_f32_dpp v237, v237, v237 quad_perm:[1,0,3,2] row_mask:0xf bank_mask:0xf
	v_add_f32_dpp v234, v234, v234 quad_perm:[2,3,0,1] row_mask:0xf bank_mask:0xf
	v_add_f32_dpp v235, v235, v235 quad_perm:[2,3,0,1] row_mask:0xf bank_mask:0xf
	v_add_f32_dpp v236, v236, v236 quad_perm:[2,3,0,1] row_mask:0xf bank_mask:0xf
	v_add_f32_dpp v237, v237, v237 quad_perm:[2,3,0,1] row_mask:0xf bank_mask:0xf
	v_add_f32_dpp v234, v234, v234 row_half_mirror row_mask:0xf bank_mask:0xf
	v_add_f32_dpp v235, v235, v235 row_half_mirror row_mask:0xf bank_mask:0xf
	v_add_f32_dpp v236, v236, v236 row_half_mirror row_mask:0xf bank_mask:0xf
	v_add_f32_dpp v237, v237, v237 row_half_mirror row_mask:0xf bank_mask:0xf
	s_mov_b32 exec_lo, 0x10001
	s_mov_b32 exec_hi, 0x10001
	ds_write_b32 v155, v234 offset:1280
	ds_write_b32 v155, v235 offset:1296
	ds_write_b32 v155, v236 offset:1312
	ds_write_b32 v155, v237 offset:1328
	s_mov_b64 exec, -1
	s_waitcnt lgkmcnt(0)
; __device__ __forceinline__ void peer_token(const Params& P, int t, int lane, int* sidx, float* sval, const int* sid, const float* sgate, const unsigned* szero) {
;     ...
;         for (int hh = 0; hh < 2; ++hh) off2[hh] = (unsigned)sid[8 * hh + (lr & 7)] * 512u + lofs;
; #pragma unroll
;         for (int hh = 0; hh < 2; ++hh)
; #pragma unroll
;             for (int st = 0; st < 4; ++st) abuf[0][hh][st] = *(const uint4*)(Ub + (off2[hh] + 128 * st));
; #pragma unroll
;         for (int T = 0; T < 8; ++T) {
;             if (T + 1 < 8) {
; #pragma unroll
;                 for (int hh = 0; hh < 2; ++hh) off2[hh] = (unsigned)sid[16 * (T + 1) + 8 * hh + (lr & 7)] * 512u + lofs;
; #pragma unroll
;                 for (int hh = 0; hh < 2; ++hh)
; #pragma unroll
;                     for (int st = 0; st < 4; ++st) abuf[(T + 1) & 1][hh][st] = *(const uint4*)(Ub + (off2[hh] + 128 * st));
;             }
; #pragma unroll
;             for (int hh = 0; hh < 2; ++hh) {
;                 f32x4 au = (f32x4){0.f, 0.f, 0.f, 0.f};
; #pragma unroll
;                 for (int st = 0; st < 4; ++st) {
;                     const uint4 a4 = abuf[T & 1][hh][st];
;                     const v8i Av = {(int)a4.x, (int)a4.y, (int)a4.z, (int)a4.w, 0, 0, 0, 0};
;                     au = __builtin_amdgcn_mfma_scale_f32_16x16x128_f8f6f4(Av, Bv[st], au, 4, 0, 0, 0x7f7f7f7f, 0, 0x7f7f7f7f);
;                 }
;                 if (owner) *(f32x4*)(sact + 16 * T + 8 * hh) = au;
;             }
	v_lshl_add_u32 v230, v230, 9, v144
	v_lshl_add_u32 v231, v231, 9, v144
	v_lshl_add_u32 v232, v232, 9, v144
	v_lshl_add_u32 v233, v233, 9, v144
	global_load_dwordx4 v[32:35], v230, s[10:11]
	global_load_dwordx4 v[36:39], v230, s[10:11] offset:256
	global_load_dwordx4 v[40:43], v231, s[10:11]
	global_load_dwordx4 v[44:47], v231, s[10:11] offset:256
	global_load_dwordx4 v[48:51], v232, s[10:11]
	global_load_dwordx4 v[52:55], v232, s[10:11] offset:256
	global_load_dwordx4 v[56:59], v233, s[10:11]
	global_load_dwordx4 v[60:63], v233, s[10:11] offset:256
	ds_read2_b32 v[96:97], v244 offset0:64 offset1:68
	ds_read2_b32 v[98:99], v244 offset0:72 offset1:76
	s_waitcnt vmcnt(8)
	v_mfma_scale_f32_16x16x128_f8f6f4 v[64:67], v[0:3], v[162:169], 0, v133, v133 op_sel_hi:[0,0,0] cbsz:4
	v_mfma_scale_f32_16x16x128_f8f6f4 v[64:67], v[4:7], v[170:177], v[64:67], v133, v133 op_sel_hi:[0,0,0] cbsz:4
	v_mfma_scale_f32_16x16x128_f8f6f4 v[68:71], v[8:11], v[162:169], 0, v133, v133 op_sel_hi:[0,0,0] cbsz:4
	v_mfma_scale_f32_16x16x128_f8f6f4 v[68:71], v[12:15], v[170:177], v[68:71], v133, v133 op_sel_hi:[0,0,0] cbsz:4
	v_mfma_scale_f32_16x16x128_f8f6f4 v[72:75], v[16:19], v[162:169], 0, v133, v133 op_sel_hi:[0,0,0] cbsz:4
	v_mfma_scale_f32_16x16x128_f8f6f4 v[72:75], v[20:23], v[170:177], v[72:75], v133, v133 op_sel_hi:[0,0,0] cbsz:4
	v_mfma_scale_f32_16x16x128_f8f6f4 v[76:79], v[24:27], v[162:169], 0, v133, v133 op_sel_hi:[0,0,0] cbsz:4
	v_mfma_scale_f32_16x16x128_f8f6f4 v[76:79], v[28:31], v[170:177], v[76:79], v133, v133 op_sel_hi:[0,0,0] cbsz:4
	s_nop 3
	v_mul_f32_e32 v234, v158, v80
	v_mul_f32_e32 v235, v158, v84
	v_mul_f32_e32 v236, v158, v88
	v_mul_f32_e32 v237, v158, v92
	v_fmac_f32_e32 v234, v159, v81
	v_fmac_f32_e32 v235, v159, v85
	v_fmac_f32_e32 v236, v159, v89
	v_fmac_f32_e32 v237, v159, v93
	v_fmac_f32_e32 v234, v160, v82
	v_fmac_f32_e32 v235, v160, v86
	v_fmac_f32_e32 v236, v160, v90
	v_fmac_f32_e32 v237, v160, v94
	v_fmac_f32_e32 v234, v161, v83
	v_fmac_f32_e32 v235, v161, v87
	v_fmac_f32_e32 v236, v161, v91
	v_fmac_f32_e32 v237, v161, v95
	v_add_f32_dpp v234, v234, v234 quad_perm:[1,0,3,2] row_mask:0xf bank_mask:0xf
	v_add_f32_dpp v235, v235, v235 quad_perm:[1,0,3,2] row_mask:0xf bank_mask:0xf
	v_add_f32_dpp v236, v236, v236 quad_perm:[1,0,3,2] row_mask:0xf bank_mask:0xf
	v_add_f32_dpp v237, v237, v237 quad_perm:[1,0,3,2] row_mask:0xf bank_mask:0xf
	v_add_f32_dpp v234, v234, v234 quad_perm:[2,3,0,1] row_mask:0xf bank_mask:0xf
	v_add_f32_dpp v235, v235, v235 quad_perm:[2,3,0,1] row_mask:0xf bank_mask:0xf
	v_add_f32_dpp v236, v236, v236 quad_perm:[2,3,0,1] row_mask:0xf bank_mask:0xf
	v_add_f32_dpp v237, v237, v237 quad_perm:[2,3,0,1] row_mask:0xf bank_mask:0xf
	v_add_f32_dpp v234, v234, v234 row_half_mirror row_mask:0xf bank_mask:0xf
	v_add_f32_dpp v235, v235, v235 row_half_mirror row_mask:0xf bank_mask:0xf
	v_add_f32_dpp v236, v236, v236 row_half_mirror row_mask:0xf bank_mask:0xf
	v_add_f32_dpp v237, v237, v237 row_half_mirror row_mask:0xf bank_mask:0xf
	s_mov_b32 exec_lo, 0x10001
	s_mov_b32 exec_hi, 0x10001
	ds_write_b32 v155, v234 offset:1792
	ds_write_b32 v155, v235 offset:1808
	ds_write_b32 v155, v236 offset:1824
	ds_write_b32 v155, v237 offset:1840
	s_mov_b64 exec, -1
	s_waitcnt lgkmcnt(0)
	v_lshl_add_u32 v96, v96, 9, v144
	v_lshl_add_u32 v97, v97, 9, v144
	v_lshl_add_u32 v98, v98, 9, v144
	v_lshl_add_u32 v99, v99, 9, v144
	global_load_dwordx4 v[0:3], v96, s[10:11]
	global_load_dwordx4 v[4:7], v96, s[10:11] offset:256
	global_load_dwordx4 v[8:11], v97, s[10:11]
	global_load_dwordx4 v[12:15], v97, s[10:11] offset:256
	global_load_dwordx4 v[16:19], v98, s[10:11]
	global_load_dwordx4 v[20:23], v98, s[10:11] offset:256
	global_load_dwordx4 v[24:27], v99, s[10:11]
	global_load_dwordx4 v[28:31], v99, s[10:11] offset:256
	ds_read2_b32 v[230:231], v245 offset0:64 offset1:68
	ds_read2_b32 v[232:233], v245 offset0:72 offset1:76
	s_waitcnt vmcnt(8)
	v_mfma_scale_f32_16x16x128_f8f6f4 v[80:83], v[32:35], v[178:185], 0, v133, v133 op_sel_hi:[0,0,0] cbsz:4
	v_mfma_scale_f32_16x16x128_f8f6f4 v[80:83], v[36:39], v[186:193], v[80:83], v133, v133 op_sel_hi:[0,0,0] cbsz:4
	v_mfma_scale_f32_16x16x128_f8f6f4 v[84:87], v[40:43], v[178:185], 0, v133, v133 op_sel_hi:[0,0,0] cbsz:4
	v_mfma_scale_f32_16x16x128_f8f6f4 v[84:87], v[44:47], v[186:193], v[84:87], v133, v133 op_sel_hi:[0,0,0] cbsz:4
	v_mfma_scale_f32_16x16x128_f8f6f4 v[88:91], v[48:51], v[178:185], 0, v133, v133 op_sel_hi:[0,0,0] cbsz:4
	v_mfma_scale_f32_16x16x128_f8f6f4 v[88:91], v[52:55], v[186:193], v[88:91], v133, v133 op_sel_hi:[0,0,0] cbsz:4
	v_mfma_scale_f32_16x16x128_f8f6f4 v[92:95], v[56:59], v[178:185], 0, v133, v133 op_sel_hi:[0,0,0] cbsz:4
	v_mfma_scale_f32_16x16x128_f8f6f4 v[92:95], v[60:63], v[186:193], v[92:95], v133, v133 op_sel_hi:[0,0,0] cbsz:4
	s_nop 3
	v_mul_f32_e32 v234, v226, v64
	v_mul_f32_e32 v235, v226, v68
	v_mul_f32_e32 v236, v226, v72
	v_mul_f32_e32 v237, v226, v76
	v_fmac_f32_e32 v234, v227, v65
	v_fmac_f32_e32 v235, v227, v69
	v_fmac_f32_e32 v236, v227, v73
	v_fmac_f32_e32 v237, v227, v77
	v_fmac_f32_e32 v234, v228, v66
	v_fmac_f32_e32 v235, v228, v70
	v_fmac_f32_e32 v236, v228, v74
	v_fmac_f32_e32 v237, v228, v78
	v_fmac_f32_e32 v234, v229, v67
	v_fmac_f32_e32 v235, v229, v71
	v_fmac_f32_e32 v236, v229, v75
	v_fmac_f32_e32 v237, v229, v79
	v_add_f32_dpp v234, v234, v234 quad_perm:[1,0,3,2] row_mask:0xf bank_mask:0xf
	v_add_f32_dpp v235, v235, v235 quad_perm:[1,0,3,2] row_mask:0xf bank_mask:0xf
	v_add_f32_dpp v236, v236, v236 quad_perm:[1,0,3,2] row_mask:0xf bank_mask:0xf
	v_add_f32_dpp v237, v237, v237 quad_perm:[1,0,3,2] row_mask:0xf bank_mask:0xf
	v_add_f32_dpp v234, v234, v234 quad_perm:[2,3,0,1] row_mask:0xf bank_mask:0xf
	v_add_f32_dpp v235, v235, v235 quad_perm:[2,3,0,1] row_mask:0xf bank_mask:0xf
	v_add_f32_dpp v236, v236, v236 quad_perm:[2,3,0,1] row_mask:0xf bank_mask:0xf
	v_add_f32_dpp v237, v237, v237 quad_perm:[2,3,0,1] row_mask:0xf bank_mask:0xf
	v_add_f32_dpp v234, v234, v234 row_half_mirror row_mask:0xf bank_mask:0xf
	v_add_f32_dpp v235, v235, v235 row_half_mirror row_mask:0xf bank_mask:0xf
	v_add_f32_dpp v236, v236, v236 row_half_mirror row_mask:0xf bank_mask:0xf
	v_add_f32_dpp v237, v237, v237 row_half_mirror row_mask:0xf bank_mask:0xf
	s_mov_b32 exec_lo, 0x1000100
	s_mov_b32 exec_hi, 0x1000100
	ds_write_b32 v155, v234 offset:2304
	ds_write_b32 v155, v235 offset:2320
	ds_write_b32 v155, v236 offset:2336
	ds_write_b32 v155, v237 offset:2352
	s_mov_b64 exec, -1
	s_waitcnt lgkmcnt(0)
; __device__ __forceinline__ void peer_token(const Params& P, int t, int lane, int* sidx, float* sval, const int* sid, const float* sgate, const unsigned* szero) {
;     ...
;         for (int hh = 0; hh < 2; ++hh)
; #pragma unroll
;             for (int st = 0; st < 4; ++st) abuf[0][hh][st] = *(const uint4*)(Ub + (off2[hh] + 128 * st));
; #pragma unroll
;         for (int T = 0; T < 8; ++T) {
;             if (T + 1 < 8) {
; #pragma unroll
;                 for (int hh = 0; hh < 2; ++hh) off2[hh] = (unsigned)sid[16 * (T + 1) + 8 * hh + (lr & 7)] * 512u + lofs;
; #pragma unroll
;                 for (int hh = 0; hh < 2; ++hh)
; #pragma unroll
;                     for (int st = 0; st < 4; ++st) abuf[(T + 1) & 1][hh][st] = *(const uint4*)(Ub + (off2[hh] + 128 * st));
;             }
; #pragma unroll
;             for (int hh = 0; hh < 2; ++hh) {
;                 f32x4 au = (f32x4){0.f, 0.f, 0.f, 0.f};
; #pragma unroll
;                 for (int st = 0; st < 4; ++st) {
;                     const uint4 a4 = abuf[T & 1][hh][st];
;                     const v8i Av = {(int)a4.x, (int)a4.y, (int)a4.z, (int)a4.w, 0, 0, 0, 0};
;                     au = __builtin_amdgcn_mfma_scale_f32_16x16x128_f8f6f4(Av, Bv[st], au, 4, 0, 0, 0x7f7f7f7f, 0, 0x7f7f7f7f);
;                 }
;                 if (owner) *(f32x4*)(sact + 16 * T + 8 * hh) = au;
;             }
;         }
	v_lshl_add_u32 v230, v230, 9, v144
	v_lshl_add_u32 v231, v231, 9, v144
	v_lshl_add_u32 v232, v232, 9, v144
	v_lshl_add_u32 v233, v233, 9, v144
	global_load_dwordx4 v[32:35], v230, s[10:11]
	global_load_dwordx4 v[36:39], v230, s[10:11] offset:256
	global_load_dwordx4 v[40:43], v231, s[10:11]
	global_load_dwordx4 v[44:47], v231, s[10:11] offset:256
	global_load_dwordx4 v[48:51], v232, s[10:11]
	global_load_dwordx4 v[52:55], v232, s[10:11] offset:256
	global_load_dwordx4 v[56:59], v233, s[10:11]
	global_load_dwordx4 v[60:63], v233, s[10:11] offset:256
	ds_read2_b32 v[96:97], v238 offset0:80 offset1:84
	ds_read2_b32 v[98:99], v238 offset0:88 offset1:92
	s_waitcnt vmcnt(8)
	v_mfma_scale_f32_16x16x128_f8f6f4 v[64:67], v[0:3], v[194:201], 0, v133, v133 op_sel_hi:[0,0,0] cbsz:4
	v_mfma_scale_f32_16x16x128_f8f6f4 v[64:67], v[4:7], v[202:209], v[64:67], v133, v133 op_sel_hi:[0,0,0] cbsz:4
	v_mfma_scale_f32_16x16x128_f8f6f4 v[68:71], v[8:11], v[194:201], 0, v133, v133 op_sel_hi:[0,0,0] cbsz:4
	v_mfma_scale_f32_16x16x128_f8f6f4 v[68:71], v[12:15], v[202:209], v[68:71], v133, v133 op_sel_hi:[0,0,0] cbsz:4
	v_mfma_scale_f32_16x16x128_f8f6f4 v[72:75], v[16:19], v[194:201], 0, v133, v133 op_sel_hi:[0,0,0] cbsz:4
	v_mfma_scale_f32_16x16x128_f8f6f4 v[72:75], v[20:23], v[202:209], v[72:75], v133, v133 op_sel_hi:[0,0,0] cbsz:4
	v_mfma_scale_f32_16x16x128_f8f6f4 v[76:79], v[24:27], v[194:201], 0, v133, v133 op_sel_hi:[0,0,0] cbsz:4
	v_mfma_scale_f32_16x16x128_f8f6f4 v[76:79], v[28:31], v[202:209], v[76:79], v133, v133 op_sel_hi:[0,0,0] cbsz:4
	s_nop 3
	v_mul_f32_e32 v234, v226, v80
	v_mul_f32_e32 v235, v226, v84
	v_mul_f32_e32 v236, v226, v88
	v_mul_f32_e32 v237, v226, v92
	v_fmac_f32_e32 v234, v227, v81
	v_fmac_f32_e32 v235, v227, v85
	v_fmac_f32_e32 v236, v227, v89
	v_fmac_f32_e32 v237, v227, v93
	v_fmac_f32_e32 v234, v228, v82
	v_fmac_f32_e32 v235, v228, v86
	v_fmac_f32_e32 v236, v228, v90
	v_fmac_f32_e32 v237, v228, v94
	v_fmac_f32_e32 v234, v229, v83
	v_fmac_f32_e32 v235, v229, v87
	v_fmac_f32_e32 v236, v229, v91
	v_fmac_f32_e32 v237, v229, v95
	v_add_f32_dpp v234, v234, v234 quad_perm:[1,0,3,2] row_mask:0xf bank_mask:0xf
	v_add_f32_dpp v235, v235, v235 quad_perm:[1,0,3,2] row_mask:0xf bank_mask:0xf
	v_add_f32_dpp v236, v236, v236 quad_perm:[1,0,3,2] row_mask:0xf bank_mask:0xf
	v_add_f32_dpp v237, v237, v237 quad_perm:[1,0,3,2] row_mask:0xf bank_mask:0xf
	v_add_f32_dpp v234, v234, v234 quad_perm:[2,3,0,1] row_mask:0xf bank_mask:0xf
	v_add_f32_dpp v235, v235, v235 quad_perm:[2,3,0,1] row_mask:0xf bank_mask:0xf
	v_add_f32_dpp v236, v236, v236 quad_perm:[2,3,0,1] row_mask:0xf bank_mask:0xf
	v_add_f32_dpp v237, v237, v237 quad_perm:[2,3,0,1] row_mask:0xf bank_mask:0xf
	v_add_f32_dpp v234, v234, v234 row_half_mirror row_mask:0xf bank_mask:0xf
	v_add_f32_dpp v235, v235, v235 row_half_mirror row_mask:0xf bank_mask:0xf
	v_add_f32_dpp v236, v236, v236 row_half_mirror row_mask:0xf bank_mask:0xf
	v_add_f32_dpp v237, v237, v237 row_half_mirror row_mask:0xf bank_mask:0xf
	s_mov_b32 exec_lo, 0x1000100
	s_mov_b32 exec_hi, 0x1000100
	ds_write_b32 v155, v234 offset:2816
	ds_write_b32 v155, v235 offset:2832
	ds_write_b32 v155, v236 offset:2848
	ds_write_b32 v155, v237 offset:2864
	s_mov_b64 exec, -1
	s_waitcnt lgkmcnt(0)
	v_lshl_add_u32 v96, v96, 9, v144
	v_lshl_add_u32 v97, v97, 9, v144
	v_lshl_add_u32 v98, v98, 9, v144
	v_lshl_add_u32 v99, v99, 9, v144
	global_load_dwordx4 v[0:3], v96, s[10:11]
	global_load_dwordx4 v[4:7], v96, s[10:11] offset:256
	global_load_dwordx4 v[8:11], v97, s[10:11]
	global_load_dwordx4 v[12:15], v97, s[10:11] offset:256
	global_load_dwordx4 v[16:19], v98, s[10:11]
	global_load_dwordx4 v[20:23], v98, s[10:11] offset:256
	global_load_dwordx4 v[24:27], v99, s[10:11]
	global_load_dwordx4 v[28:31], v99, s[10:11] offset:256
	ds_read2_b32 v[230:231], v239 offset0:80 offset1:84
	ds_read2_b32 v[232:233], v239 offset0:88 offset1:92
	s_waitcnt vmcnt(8)
	v_mfma_scale_f32_16x16x128_f8f6f4 v[80:83], v[32:35], v[210:217], 0, v133, v133 op_sel_hi:[0,0,0] cbsz:4
	v_mfma_scale_f32_16x16x128_f8f6f4 v[80:83], v[36:39], v[218:225], v[80:83], v133, v133 op_sel_hi:[0,0,0] cbsz:4
	v_mfma_scale_f32_16x16x128_f8f6f4 v[84:87], v[40:43], v[210:217], 0, v133, v133 op_sel_hi:[0,0,0] cbsz:4
	v_mfma_scale_f32_16x16x128_f8f6f4 v[84:87], v[44:47], v[218:225], v[84:87], v133, v133 op_sel_hi:[0,0,0] cbsz:4
	v_mfma_scale_f32_16x16x128_f8f6f4 v[88:91], v[48:51], v[210:217], 0, v133, v133 op_sel_hi:[0,0,0] cbsz:4
	v_mfma_scale_f32_16x16x128_f8f6f4 v[88:91], v[52:55], v[218:225], v[88:91], v133, v133 op_sel_hi:[0,0,0] cbsz:4
	v_mfma_scale_f32_16x16x128_f8f6f4 v[92:95], v[56:59], v[210:217], 0, v133, v133 op_sel_hi:[0,0,0] cbsz:4
	v_mfma_scale_f32_16x16x128_f8f6f4 v[92:95], v[60:63], v[218:225], v[92:95], v133, v133 op_sel_hi:[0,0,0] cbsz:4
	s_nop 3
	v_mul_f32_e32 v234, v226, v64
	v_mul_f32_e32 v235, v226, v68
	v_mul_f32_e32 v236, v226, v72
	v_mul_f32_e32 v237, v226, v76
	v_fmac_f32_e32 v234, v227, v65
	v_fmac_f32_e32 v235, v227, v69
	v_fmac_f32_e32 v236, v227, v73
	v_fmac_f32_e32 v237, v227, v77
	v_fmac_f32_e32 v234, v228, v66
	v_fmac_f32_e32 v235, v228, v70
	v_fmac_f32_e32 v236, v228, v74
	v_fmac_f32_e32 v237, v228, v78
	v_fmac_f32_e32 v234, v229, v67
	v_fmac_f32_e32 v235, v229, v71
	v_fmac_f32_e32 v236, v229, v75
	v_fmac_f32_e32 v237, v229, v79
	v_add_f32_dpp v234, v234, v234 quad_perm:[1,0,3,2] row_mask:0xf bank_mask:0xf
	v_add_f32_dpp v235, v235, v235 quad_perm:[1,0,3,2] row_mask:0xf bank_mask:0xf
	v_add_f32_dpp v236, v236, v236 quad_perm:[1,0,3,2] row_mask:0xf bank_mask:0xf
	v_add_f32_dpp v237, v237, v237 quad_perm:[1,0,3,2] row_mask:0xf bank_mask:0xf
	v_add_f32_dpp v234, v234, v234 quad_perm:[2,3,0,1] row_mask:0xf bank_mask:0xf
	v_add_f32_dpp v235, v235, v235 quad_perm:[2,3,0,1] row_mask:0xf bank_mask:0xf
	v_add_f32_dpp v236, v236, v236 quad_perm:[2,3,0,1] row_mask:0xf bank_mask:0xf
	v_add_f32_dpp v237, v237, v237 quad_perm:[2,3,0,1] row_mask:0xf bank_mask:0xf
	v_add_f32_dpp v234, v234, v234 row_half_mirror row_mask:0xf bank_mask:0xf
	v_add_f32_dpp v235, v235, v235 row_half_mirror row_mask:0xf bank_mask:0xf
	v_add_f32_dpp v236, v236, v236 row_half_mirror row_mask:0xf bank_mask:0xf
	v_add_f32_dpp v237, v237, v237 row_half_mirror row_mask:0xf bank_mask:0xf
	s_mov_b32 exec_lo, 0x1000100
	s_mov_b32 exec_hi, 0x1000100
	ds_write_b32 v155, v234 offset:3328
	ds_write_b32 v155, v235 offset:3344
	ds_write_b32 v155, v236 offset:3360
	ds_write_b32 v155, v237 offset:3376
	s_mov_b64 exec, -1
	s_waitcnt lgkmcnt(0)
; __device__ __forceinline__ void peer_token(const Params& P, int t, int lane, int* sidx, float* sval, const int* sid, const float* sgate, const unsigned* szero) {
;     ...
;         for (int hh = 0; hh < 2; ++hh)
; #pragma unroll
;             for (int st = 0; st < 4; ++st) abuf[0][hh][st] = *(const uint4*)(Ub + (off2[hh] + 128 * st));
; #pragma unroll
;         for (int T = 0; T < 8; ++T) {
;             if (T + 1 < 8) {
; #pragma unroll
;                 for (int hh = 0; hh < 2; ++hh) off2[hh] = (unsigned)sid[16 * (T + 1) + 8 * hh + (lr & 7)] * 512u + lofs;
; #pragma unroll
;                 for (int hh = 0; hh < 2; ++hh)
; #pragma unroll
;                     for (int st = 0; st < 4; ++st) abuf[(T + 1) & 1][hh][st] = *(const uint4*)(Ub + (off2[hh] + 128 * st));
;             }
; #pragma unroll
;             for (int hh = 0; hh < 2; ++hh) {
;                 f32x4 au = (f32x4){0.f, 0.f, 0.f, 0.f};
; #pragma unroll
;                 for (int st = 0; st < 4; ++st) {
;                     const uint4 a4 = abuf[T & 1][hh][st];
;                     const v8i Av = {(int)a4.x, (int)a4.y, (int)a4.z, (int)a4.w, 0, 0, 0, 0};
;                     au = __builtin_amdgcn_mfma_scale_f32_16x16x128_f8f6f4(Av, Bv[st], au, 4, 0, 0, 0x7f7f7f7f, 0, 0x7f7f7f7f);
;                 }
;                 if (owner) *(f32x4*)(sact + 16 * T + 8 * hh) = au;
;             }
;         }
	v_lshl_add_u32 v230, v230, 9, v144
	v_lshl_add_u32 v231, v231, 9, v144
	v_lshl_add_u32 v232, v232, 9, v144
	v_lshl_add_u32 v233, v233, 9, v144
	global_load_dwordx4 v[32:35], v230, s[10:11]
	global_load_dwordx4 v[36:39], v230, s[10:11] offset:256
	global_load_dwordx4 v[40:43], v231, s[10:11]
	global_load_dwordx4 v[44:47], v231, s[10:11] offset:256
	global_load_dwordx4 v[48:51], v232, s[10:11]
	global_load_dwordx4 v[52:55], v232, s[10:11] offset:256
	global_load_dwordx4 v[56:59], v233, s[10:11]
	global_load_dwordx4 v[60:63], v233, s[10:11] offset:256
	ds_read2_b32 v[96:97], v240 offset0:80 offset1:84
	ds_read2_b32 v[98:99], v240 offset0:88 offset1:92
	s_waitcnt vmcnt(8)
	v_mfma_scale_f32_16x16x128_f8f6f4 v[64:67], v[0:3], v[162:169], 0, v133, v133 op_sel_hi:[0,0,0] cbsz:4
	v_mfma_scale_f32_16x16x128_f8f6f4 v[64:67], v[4:7], v[170:177], v[64:67], v133, v133 op_sel_hi:[0,0,0] cbsz:4
	v_mfma_scale_f32_16x16x128_f8f6f4 v[68:71], v[8:11], v[162:169], 0, v133, v133 op_sel_hi:[0,0,0] cbsz:4
	v_mfma_scale_f32_16x16x128_f8f6f4 v[68:71], v[12:15], v[170:177], v[68:71], v133, v133 op_sel_hi:[0,0,0] cbsz:4
	v_mfma_scale_f32_16x16x128_f8f6f4 v[72:75], v[16:19], v[162:169], 0, v133, v133 op_sel_hi:[0,0,0] cbsz:4
	v_mfma_scale_f32_16x16x128_f8f6f4 v[72:75], v[20:23], v[170:177], v[72:75], v133, v133 op_sel_hi:[0,0,0] cbsz:4
	v_mfma_scale_f32_16x16x128_f8f6f4 v[76:79], v[24:27], v[162:169], 0, v133, v133 op_sel_hi:[0,0,0] cbsz:4
	v_mfma_scale_f32_16x16x128_f8f6f4 v[76:79], v[28:31], v[170:177], v[76:79], v133, v133 op_sel_hi:[0,0,0] cbsz:4
	s_nop 3
	v_mul_f32_e32 v234, v226, v80
	v_mul_f32_e32 v235, v226, v84
	v_mul_f32_e32 v236, v226, v88
	v_mul_f32_e32 v237, v226, v92
	v_fmac_f32_e32 v234, v227, v81
	v_fmac_f32_e32 v235, v227, v85
	v_fmac_f32_e32 v236, v227, v89
	v_fmac_f32_e32 v237, v227, v93
	v_fmac_f32_e32 v234, v228, v82
	v_fmac_f32_e32 v235, v228, v86
	v_fmac_f32_e32 v236, v228, v90
	v_fmac_f32_e32 v237, v228, v94
	v_fmac_f32_e32 v234, v229, v83
	v_fmac_f32_e32 v235, v229, v87
	v_fmac_f32_e32 v236, v229, v91
	v_fmac_f32_e32 v237, v229, v95
	v_add_f32_dpp v234, v234, v234 quad_perm:[1,0,3,2] row_mask:0xf bank_mask:0xf
	v_add_f32_dpp v235, v235, v235 quad_perm:[1,0,3,2] row_mask:0xf bank_mask:0xf
	v_add_f32_dpp v236, v236, v236 quad_perm:[1,0,3,2] row_mask:0xf bank_mask:0xf
	v_add_f32_dpp v237, v237, v237 quad_perm:[1,0,3,2] row_mask:0xf bank_mask:0xf
	v_add_f32_dpp v234, v234, v234 quad_perm:[2,3,0,1] row_mask:0xf bank_mask:0xf
	v_add_f32_dpp v235, v235, v235 quad_perm:[2,3,0,1] row_mask:0xf bank_mask:0xf
	v_add_f32_dpp v236, v236, v236 quad_perm:[2,3,0,1] row_mask:0xf bank_mask:0xf
	v_add_f32_dpp v237, v237, v237 quad_perm:[2,3,0,1] row_mask:0xf bank_mask:0xf
	v_add_f32_dpp v234, v234, v234 row_half_mirror row_mask:0xf bank_mask:0xf
	v_add_f32_dpp v235, v235, v235 row_half_mirror row_mask:0xf bank_mask:0xf
	v_add_f32_dpp v236, v236, v236 row_half_mirror row_mask:0xf bank_mask:0xf
	v_add_f32_dpp v237, v237, v237 row_half_mirror row_mask:0xf bank_mask:0xf
	s_mov_b32 exec_lo, 0x1000100
	s_mov_b32 exec_hi, 0x1000100
	ds_write_b32 v155, v234 offset:3840
	ds_write_b32 v155, v235 offset:3856
	ds_write_b32 v155, v236 offset:3872
	ds_write_b32 v155, v237 offset:3888
	s_mov_b64 exec, -1
	s_waitcnt lgkmcnt(0)
	v_lshl_add_u32 v96, v96, 9, v144
	v_lshl_add_u32 v97, v97, 9, v144
	v_lshl_add_u32 v98, v98, 9, v144
	v_lshl_add_u32 v99, v99, 9, v144
	global_load_dwordx4 v[0:3], v96, s[10:11]
	global_load_dwordx4 v[4:7], v96, s[10:11] offset:256
	global_load_dwordx4 v[8:11], v97, s[10:11]
	global_load_dwordx4 v[12:15], v97, s[10:11] offset:256
	global_load_dwordx4 v[16:19], v98, s[10:11]
	global_load_dwordx4 v[20:23], v98, s[10:11] offset:256
	global_load_dwordx4 v[24:27], v99, s[10:11]
	global_load_dwordx4 v[28:31], v99, s[10:11] offset:256
	ds_read2_b32 v[230:231], v241 offset0:80 offset1:84
	ds_read2_b32 v[232:233], v241 offset0:88 offset1:92
	s_waitcnt vmcnt(8)
	v_mfma_scale_f32_16x16x128_f8f6f4 v[80:83], v[32:35], v[178:185], 0, v133, v133 op_sel_hi:[0,0,0] cbsz:4
	v_mfma_scale_f32_16x16x128_f8f6f4 v[80:83], v[36:39], v[186:193], v[80:83], v133, v133 op_sel_hi:[0,0,0] cbsz:4
	v_mfma_scale_f32_16x16x128_f8f6f4 v[84:87], v[40:43], v[178:185], 0, v133, v133 op_sel_hi:[0,0,0] cbsz:4
	v_mfma_scale_f32_16x16x128_f8f6f4 v[84:87], v[44:47], v[186:193], v[84:87], v133, v133 op_sel_hi:[0,0,0] cbsz:4
	v_mfma_scale_f32_16x16x128_f8f6f4 v[88:91], v[48:51], v[178:185], 0, v133, v133 op_sel_hi:[0,0,0] cbsz:4
	v_mfma_scale_f32_16x16x128_f8f6f4 v[88:91], v[52:55], v[186:193], v[88:91], v133, v133 op_sel_hi:[0,0,0] cbsz:4
	v_mfma_scale_f32_16x16x128_f8f6f4 v[92:95], v[56:59], v[178:185], 0, v133, v133 op_sel_hi:[0,0,0] cbsz:4
	v_mfma_scale_f32_16x16x128_f8f6f4 v[92:95], v[60:63], v[186:193], v[92:95], v133, v133 op_sel_hi:[0,0,0] cbsz:4
	s_nop 3
	v_mul_f32_e32 v234, v158, v64
	v_mul_f32_e32 v235, v158, v68
	v_mul_f32_e32 v236, v158, v72
	v_mul_f32_e32 v237, v158, v76
	v_fmac_f32_e32 v234, v159, v65
	v_fmac_f32_e32 v235, v159, v69
	v_fmac_f32_e32 v236, v159, v73
	v_fmac_f32_e32 v237, v159, v77
	v_fmac_f32_e32 v234, v160, v66
	v_fmac_f32_e32 v235, v160, v70
	v_fmac_f32_e32 v236, v160, v74
	v_fmac_f32_e32 v237, v160, v78
	v_fmac_f32_e32 v234, v161, v67
	v_fmac_f32_e32 v235, v161, v71
	v_fmac_f32_e32 v236, v161, v75
	v_fmac_f32_e32 v237, v161, v79
	v_add_f32_dpp v234, v234, v234 quad_perm:[1,0,3,2] row_mask:0xf bank_mask:0xf
	v_add_f32_dpp v235, v235, v235 quad_perm:[1,0,3,2] row_mask:0xf bank_mask:0xf
	v_add_f32_dpp v236, v236, v236 quad_perm:[1,0,3,2] row_mask:0xf bank_mask:0xf
	v_add_f32_dpp v237, v237, v237 quad_perm:[1,0,3,2] row_mask:0xf bank_mask:0xf
	v_add_f32_dpp v234, v234, v234 quad_perm:[2,3,0,1] row_mask:0xf bank_mask:0xf
	v_add_f32_dpp v235, v235, v235 quad_perm:[2,3,0,1] row_mask:0xf bank_mask:0xf
	v_add_f32_dpp v236, v236, v236 quad_perm:[2,3,0,1] row_mask:0xf bank_mask:0xf
	v_add_f32_dpp v237, v237, v237 quad_perm:[2,3,0,1] row_mask:0xf bank_mask:0xf
	v_add_f32_dpp v234, v234, v234 row_half_mirror row_mask:0xf bank_mask:0xf
	v_add_f32_dpp v235, v235, v235 row_half_mirror row_mask:0xf bank_mask:0xf
	v_add_f32_dpp v236, v236, v236 row_half_mirror row_mask:0xf bank_mask:0xf
	v_add_f32_dpp v237, v237, v237 row_half_mirror row_mask:0xf bank_mask:0xf
	s_mov_b32 exec_lo, 0x10001
	s_mov_b32 exec_hi, 0x10001
	ds_write_b32 v155, v234 offset:320
	ds_write_b32 v155, v235 offset:336
	ds_write_b32 v155, v236 offset:352
	ds_write_b32 v155, v237 offset:368
	s_mov_b64 exec, -1
	s_waitcnt lgkmcnt(0)
; __device__ __forceinline__ void peer_token(const Params& P, int t, int lane, int* sidx, float* sval, const int* sid, const float* sgate, const unsigned* szero) {
;     ...
;         for (int hh = 0; hh < 2; ++hh)
; #pragma unroll
;             for (int st = 0; st < 4; ++st) abuf[0][hh][st] = *(const uint4*)(Ub + (off2[hh] + 128 * st));
; #pragma unroll
;         for (int T = 0; T < 8; ++T) {
;             if (T + 1 < 8) {
; #pragma unroll
;                 for (int hh = 0; hh < 2; ++hh) off2[hh] = (unsigned)sid[16 * (T + 1) + 8 * hh + (lr & 7)] * 512u + lofs;
; #pragma unroll
;                 for (int hh = 0; hh < 2; ++hh)
; #pragma unroll
;                     for (int st = 0; st < 4; ++st) abuf[(T + 1) & 1][hh][st] = *(const uint4*)(Ub + (off2[hh] + 128 * st));
;             }
; #pragma unroll
;             for (int hh = 0; hh < 2; ++hh) {
;                 f32x4 au = (f32x4){0.f, 0.f, 0.f, 0.f};
; #pragma unroll
;                 for (int st = 0; st < 4; ++st) {
;                     const uint4 a4 = abuf[T & 1][hh][st];
;                     const v8i Av = {(int)a4.x, (int)a4.y, (int)a4.z, (int)a4.w, 0, 0, 0, 0};
;                     au = __builtin_amdgcn_mfma_scale_f32_16x16x128_f8f6f4(Av, Bv[st], au, 4, 0, 0, 0x7f7f7f7f, 0, 0x7f7f7f7f);
;                 }
;                 if (owner) *(f32x4*)(sact + 16 * T + 8 * hh) = au;
;             }
;         }
	v_lshl_add_u32 v230, v230, 9, v144
	v_lshl_add_u32 v231, v231, 9, v144
	v_lshl_add_u32 v232, v232, 9, v144
	v_lshl_add_u32 v233, v233, 9, v144
	global_load_dwordx4 v[32:35], v230, s[10:11]
	global_load_dwordx4 v[36:39], v230, s[10:11] offset:256
	global_load_dwordx4 v[40:43], v231, s[10:11]
	global_load_dwordx4 v[44:47], v231, s[10:11] offset:256
	global_load_dwordx4 v[48:51], v232, s[10:11]
	global_load_dwordx4 v[52:55], v232, s[10:11] offset:256
	global_load_dwordx4 v[56:59], v233, s[10:11]
	global_load_dwordx4 v[60:63], v233, s[10:11] offset:256
	ds_read2_b32 v[96:97], v242 offset0:80 offset1:84
	ds_read2_b32 v[98:99], v242 offset0:88 offset1:92
	s_waitcnt vmcnt(8)
	v_mfma_scale_f32_16x16x128_f8f6f4 v[64:67], v[0:3], v[194:201], 0, v133, v133 op_sel_hi:[0,0,0] cbsz:4
	v_mfma_scale_f32_16x16x128_f8f6f4 v[64:67], v[4:7], v[202:209], v[64:67], v133, v133 op_sel_hi:[0,0,0] cbsz:4
	v_mfma_scale_f32_16x16x128_f8f6f4 v[68:71], v[8:11], v[194:201], 0, v133, v133 op_sel_hi:[0,0,0] cbsz:4
	v_mfma_scale_f32_16x16x128_f8f6f4 v[68:71], v[12:15], v[202:209], v[68:71], v133, v133 op_sel_hi:[0,0,0] cbsz:4
	v_mfma_scale_f32_16x16x128_f8f6f4 v[72:75], v[16:19], v[194:201], 0, v133, v133 op_sel_hi:[0,0,0] cbsz:4
	v_mfma_scale_f32_16x16x128_f8f6f4 v[72:75], v[20:23], v[202:209], v[72:75], v133, v133 op_sel_hi:[0,0,0] cbsz:4
	v_mfma_scale_f32_16x16x128_f8f6f4 v[76:79], v[24:27], v[194:201], 0, v133, v133 op_sel_hi:[0,0,0] cbsz:4
	v_mfma_scale_f32_16x16x128_f8f6f4 v[76:79], v[28:31], v[202:209], v[76:79], v133, v133 op_sel_hi:[0,0,0] cbsz:4
	s_nop 3
	v_mul_f32_e32 v234, v158, v80
	v_mul_f32_e32 v235, v158, v84
	v_mul_f32_e32 v236, v158, v88
	v_mul_f32_e32 v237, v158, v92
	v_fmac_f32_e32 v234, v159, v81
	v_fmac_f32_e32 v235, v159, v85
	v_fmac_f32_e32 v236, v159, v89
	v_fmac_f32_e32 v237, v159, v93
	v_fmac_f32_e32 v234, v160, v82
	v_fmac_f32_e32 v235, v160, v86
	v_fmac_f32_e32 v236, v160, v90
	v_fmac_f32_e32 v237, v160, v94
	v_fmac_f32_e32 v234, v161, v83
	v_fmac_f32_e32 v235, v161, v87
	v_fmac_f32_e32 v236, v161, v91
	v_fmac_f32_e32 v237, v161, v95
	v_add_f32_dpp v234, v234, v234 quad_perm:[1,0,3,2] row_mask:0xf bank_mask:0xf
	v_add_f32_dpp v235, v235, v235 quad_perm:[1,0,3,2] row_mask:0xf bank_mask:0xf
	v_add_f32_dpp v236, v236, v236 quad_perm:[1,0,3,2] row_mask:0xf bank_mask:0xf
	v_add_f32_dpp v237, v237, v237 quad_perm:[1,0,3,2] row_mask:0xf bank_mask:0xf
	v_add_f32_dpp v234, v234, v234 quad_perm:[2,3,0,1] row_mask:0xf bank_mask:0xf
	v_add_f32_dpp v235, v235, v235 quad_perm:[2,3,0,1] row_mask:0xf bank_mask:0xf
	v_add_f32_dpp v236, v236, v236 quad_perm:[2,3,0,1] row_mask:0xf bank_mask:0xf
	v_add_f32_dpp v237, v237, v237 quad_perm:[2,3,0,1] row_mask:0xf bank_mask:0xf
	v_add_f32_dpp v234, v234, v234 row_half_mirror row_mask:0xf bank_mask:0xf
	v_add_f32_dpp v235, v235, v235 row_half_mirror row_mask:0xf bank_mask:0xf
	v_add_f32_dpp v236, v236, v236 row_half_mirror row_mask:0xf bank_mask:0xf
	v_add_f32_dpp v237, v237, v237 row_half_mirror row_mask:0xf bank_mask:0xf
	s_mov_b32 exec_lo, 0x10001
	s_mov_b32 exec_hi, 0x10001
	ds_write_b32 v155, v234 offset:832
	ds_write_b32 v155, v235 offset:848
	ds_write_b32 v155, v236 offset:864
	ds_write_b32 v155, v237 offset:880
	s_mov_b64 exec, -1
	s_waitcnt lgkmcnt(0)
	v_lshl_add_u32 v96, v96, 9, v144
	v_lshl_add_u32 v97, v97, 9, v144
	v_lshl_add_u32 v98, v98, 9, v144
	v_lshl_add_u32 v99, v99, 9, v144
	global_load_dwordx4 v[0:3], v96, s[10:11]
	global_load_dwordx4 v[4:7], v96, s[10:11] offset:256
	global_load_dwordx4 v[8:11], v97, s[10:11]
	global_load_dwordx4 v[12:15], v97, s[10:11] offset:256
	global_load_dwordx4 v[16:19], v98, s[10:11]
	global_load_dwordx4 v[20:23], v98, s[10:11] offset:256
	global_load_dwordx4 v[24:27], v99, s[10:11]
	global_load_dwordx4 v[28:31], v99, s[10:11] offset:256
	ds_read2_b32 v[230:231], v243 offset0:80 offset1:84
	ds_read2_b32 v[232:233], v243 offset0:88 offset1:92
	s_waitcnt vmcnt(8)
	v_mfma_scale_f32_16x16x128_f8f6f4 v[80:83], v[32:35], v[210:217], 0, v133, v133 op_sel_hi:[0,0,0] cbsz:4
	v_mfma_scale_f32_16x16x128_f8f6f4 v[80:83], v[36:39], v[218:225], v[80:83], v133, v133 op_sel_hi:[0,0,0] cbsz:4
	v_mfma_scale_f32_16x16x128_f8f6f4 v[84:87], v[40:43], v[210:217], 0, v133, v133 op_sel_hi:[0,0,0] cbsz:4
	v_mfma_scale_f32_16x16x128_f8f6f4 v[84:87], v[44:47], v[218:225], v[84:87], v133, v133 op_sel_hi:[0,0,0] cbsz:4
	v_mfma_scale_f32_16x16x128_f8f6f4 v[88:91], v[48:51], v[210:217], 0, v133, v133 op_sel_hi:[0,0,0] cbsz:4
	v_mfma_scale_f32_16x16x128_f8f6f4 v[88:91], v[52:55], v[218:225], v[88:91], v133, v133 op_sel_hi:[0,0,0] cbsz:4
	v_mfma_scale_f32_16x16x128_f8f6f4 v[92:95], v[56:59], v[210:217], 0, v133, v133 op_sel_hi:[0,0,0] cbsz:4
	v_mfma_scale_f32_16x16x128_f8f6f4 v[92:95], v[60:63], v[218:225], v[92:95], v133, v133 op_sel_hi:[0,0,0] cbsz:4
	s_nop 3
	v_mul_f32_e32 v234, v158, v64
	v_mul_f32_e32 v235, v158, v68
	v_mul_f32_e32 v236, v158, v72
	v_mul_f32_e32 v237, v158, v76
	v_fmac_f32_e32 v234, v159, v65
	v_fmac_f32_e32 v235, v159, v69
	v_fmac_f32_e32 v236, v159, v73
	v_fmac_f32_e32 v237, v159, v77
	v_fmac_f32_e32 v234, v160, v66
	v_fmac_f32_e32 v235, v160, v70
	v_fmac_f32_e32 v236, v160, v74
	v_fmac_f32_e32 v237, v160, v78
	v_fmac_f32_e32 v234, v161, v67
	v_fmac_f32_e32 v235, v161, v71
	v_fmac_f32_e32 v236, v161, v75
	v_fmac_f32_e32 v237, v161, v79
	v_add_f32_dpp v234, v234, v234 quad_perm:[1,0,3,2] row_mask:0xf bank_mask:0xf
	v_add_f32_dpp v235, v235, v235 quad_perm:[1,0,3,2] row_mask:0xf bank_mask:0xf
	v_add_f32_dpp v236, v236, v236 quad_perm:[1,0,3,2] row_mask:0xf bank_mask:0xf
	v_add_f32_dpp v237, v237, v237 quad_perm:[1,0,3,2] row_mask:0xf bank_mask:0xf
	v_add_f32_dpp v234, v234, v234 quad_perm:[2,3,0,1] row_mask:0xf bank_mask:0xf
	v_add_f32_dpp v235, v235, v235 quad_perm:[2,3,0,1] row_mask:0xf bank_mask:0xf
	v_add_f32_dpp v236, v236, v236 quad_perm:[2,3,0,1] row_mask:0xf bank_mask:0xf
	v_add_f32_dpp v237, v237, v237 quad_perm:[2,3,0,1] row_mask:0xf bank_mask:0xf
	v_add_f32_dpp v234, v234, v234 row_half_mirror row_mask:0xf bank_mask:0xf
	v_add_f32_dpp v235, v235, v235 row_half_mirror row_mask:0xf bank_mask:0xf
	v_add_f32_dpp v236, v236, v236 row_half_mirror row_mask:0xf bank_mask:0xf
	v_add_f32_dpp v237, v237, v237 row_half_mirror row_mask:0xf bank_mask:0xf
	s_mov_b32 exec_lo, 0x10001
	s_mov_b32 exec_hi, 0x10001
	ds_write_b32 v155, v234 offset:1344
	ds_write_b32 v155, v235 offset:1360
	ds_write_b32 v155, v236 offset:1376
	ds_write_b32 v155, v237 offset:1392
	s_mov_b64 exec, -1
	s_waitcnt lgkmcnt(0)
; __device__ __forceinline__ void peer_token(const Params& P, int t, int lane, int* sidx, float* sval, const int* sid, const float* sgate, const unsigned* szero) {
;     ...
;         for (int hh = 0; hh < 2; ++hh)
; #pragma unroll
;             for (int st = 0; st < 4; ++st) abuf[0][hh][st] = *(const uint4*)(Ub + (off2[hh] + 128 * st));
; #pragma unroll
;         for (int T = 0; T < 8; ++T) {
;             if (T + 1 < 8) {
; #pragma unroll
;                 for (int hh = 0; hh < 2; ++hh) off2[hh] = (unsigned)sid[16 * (T + 1) + 8 * hh + (lr & 7)] * 512u + lofs;
; #pragma unroll
;                 for (int hh = 0; hh < 2; ++hh)
; #pragma unroll
;                     for (int st = 0; st < 4; ++st) abuf[(T + 1) & 1][hh][st] = *(const uint4*)(Ub + (off2[hh] + 128 * st));
;             }
; #pragma unroll
;             for (int hh = 0; hh < 2; ++hh) {
;                 f32x4 au = (f32x4){0.f, 0.f, 0.f, 0.f};
; #pragma unroll
;                 for (int st = 0; st < 4; ++st) {
;                     const uint4 a4 = abuf[T & 1][hh][st];
;                     const v8i Av = {(int)a4.x, (int)a4.y, (int)a4.z, (int)a4.w, 0, 0, 0, 0};
;                     au = __builtin_amdgcn_mfma_scale_f32_16x16x128_f8f6f4(Av, Bv[st], au, 4, 0, 0, 0x7f7f7f7f, 0, 0x7f7f7f7f);
;                 }
;                 if (owner) *(f32x4*)(sact + 16 * T + 8 * hh) = au;
;             }
;         }
	v_lshl_add_u32 v230, v230, 9, v144
	v_lshl_add_u32 v231, v231, 9, v144
	v_lshl_add_u32 v232, v232, 9, v144
	v_lshl_add_u32 v233, v233, 9, v144
	global_load_dwordx4 v[32:35], v230, s[10:11]
	global_load_dwordx4 v[36:39], v230, s[10:11] offset:256
	global_load_dwordx4 v[40:43], v231, s[10:11]
	global_load_dwordx4 v[44:47], v231, s[10:11] offset:256
	global_load_dwordx4 v[48:51], v232, s[10:11]
	global_load_dwordx4 v[52:55], v232, s[10:11] offset:256
	global_load_dwordx4 v[56:59], v233, s[10:11]
	global_load_dwordx4 v[60:63], v233, s[10:11] offset:256
	ds_read2_b32 v[96:97], v244 offset0:80 offset1:84
	ds_read2_b32 v[98:99], v244 offset0:88 offset1:92
	s_waitcnt vmcnt(8)
	v_mfma_scale_f32_16x16x128_f8f6f4 v[64:67], v[0:3], v[162:169], 0, v133, v133 op_sel_hi:[0,0,0] cbsz:4
	v_mfma_scale_f32_16x16x128_f8f6f4 v[64:67], v[4:7], v[170:177], v[64:67], v133, v133 op_sel_hi:[0,0,0] cbsz:4
	v_mfma_scale_f32_16x16x128_f8f6f4 v[68:71], v[8:11], v[162:169], 0, v133, v133 op_sel_hi:[0,0,0] cbsz:4
	v_mfma_scale_f32_16x16x128_f8f6f4 v[68:71], v[12:15], v[170:177], v[68:71], v133, v133 op_sel_hi:[0,0,0] cbsz:4
	v_mfma_scale_f32_16x16x128_f8f6f4 v[72:75], v[16:19], v[162:169], 0, v133, v133 op_sel_hi:[0,0,0] cbsz:4
	v_mfma_scale_f32_16x16x128_f8f6f4 v[72:75], v[20:23], v[170:177], v[72:75], v133, v133 op_sel_hi:[0,0,0] cbsz:4
	v_mfma_scale_f32_16x16x128_f8f6f4 v[76:79], v[24:27], v[162:169], 0, v133, v133 op_sel_hi:[0,0,0] cbsz:4
	v_mfma_scale_f32_16x16x128_f8f6f4 v[76:79], v[28:31], v[170:177], v[76:79], v133, v133 op_sel_hi:[0,0,0] cbsz:4
	s_nop 3
	v_mul_f32_e32 v234, v158, v80
	v_mul_f32_e32 v235, v158, v84
	v_mul_f32_e32 v236, v158, v88
	v_mul_f32_e32 v237, v158, v92
	v_fmac_f32_e32 v234, v159, v81
	v_fmac_f32_e32 v235, v159, v85
	v_fmac_f32_e32 v236, v159, v89
	v_fmac_f32_e32 v237, v159, v93
	v_fmac_f32_e32 v234, v160, v82
	v_fmac_f32_e32 v235, v160, v86
	v_fmac_f32_e32 v236, v160, v90
	v_fmac_f32_e32 v237, v160, v94
	v_fmac_f32_e32 v234, v161, v83
	v_fmac_f32_e32 v235, v161, v87
	v_fmac_f32_e32 v236, v161, v91
	v_fmac_f32_e32 v237, v161, v95
	v_add_f32_dpp v234, v234, v234 quad_perm:[1,0,3,2] row_mask:0xf bank_mask:0xf
	v_add_f32_dpp v235, v235, v235 quad_perm:[1,0,3,2] row_mask:0xf bank_mask:0xf
	v_add_f32_dpp v236, v236, v236 quad_perm:[1,0,3,2] row_mask:0xf bank_mask:0xf
	v_add_f32_dpp v237, v237, v237 quad_perm:[1,0,3,2] row_mask:0xf bank_mask:0xf
	v_add_f32_dpp v234, v234, v234 quad_perm:[2,3,0,1] row_mask:0xf bank_mask:0xf
	v_add_f32_dpp v235, v235, v235 quad_perm:[2,3,0,1] row_mask:0xf bank_mask:0xf
	v_add_f32_dpp v236, v236, v236 quad_perm:[2,3,0,1] row_mask:0xf bank_mask:0xf
	v_add_f32_dpp v237, v237, v237 quad_perm:[2,3,0,1] row_mask:0xf bank_mask:0xf
	v_add_f32_dpp v234, v234, v234 row_half_mirror row_mask:0xf bank_mask:0xf
	v_add_f32_dpp v235, v235, v235 row_half_mirror row_mask:0xf bank_mask:0xf
	v_add_f32_dpp v236, v236, v236 row_half_mirror row_mask:0xf bank_mask:0xf
	v_add_f32_dpp v237, v237, v237 row_half_mirror row_mask:0xf bank_mask:0xf
	s_mov_b32 exec_lo, 0x10001
	s_mov_b32 exec_hi, 0x10001
	ds_write_b32 v155, v234 offset:1856
	ds_write_b32 v155, v235 offset:1872
	ds_write_b32 v155, v236 offset:1888
	ds_write_b32 v155, v237 offset:1904
	s_mov_b64 exec, -1
	s_waitcnt lgkmcnt(0)
	v_lshl_add_u32 v96, v96, 9, v144
	v_lshl_add_u32 v97, v97, 9, v144
	v_lshl_add_u32 v98, v98, 9, v144
	v_lshl_add_u32 v99, v99, 9, v144
	global_load_dwordx4 v[0:3], v96, s[10:11]
	global_load_dwordx4 v[4:7], v96, s[10:11] offset:256
	global_load_dwordx4 v[8:11], v97, s[10:11]
	global_load_dwordx4 v[12:15], v97, s[10:11] offset:256
	global_load_dwordx4 v[16:19], v98, s[10:11]
	global_load_dwordx4 v[20:23], v98, s[10:11] offset:256
	global_load_dwordx4 v[24:27], v99, s[10:11]
	global_load_dwordx4 v[28:31], v99, s[10:11] offset:256
	ds_read2_b32 v[230:231], v245 offset0:80 offset1:84
	ds_read2_b32 v[232:233], v245 offset0:88 offset1:92
	s_waitcnt vmcnt(8)
	v_mfma_scale_f32_16x16x128_f8f6f4 v[80:83], v[32:35], v[178:185], 0, v133, v133 op_sel_hi:[0,0,0] cbsz:4
	v_mfma_scale_f32_16x16x128_f8f6f4 v[80:83], v[36:39], v[186:193], v[80:83], v133, v133 op_sel_hi:[0,0,0] cbsz:4
	v_mfma_scale_f32_16x16x128_f8f6f4 v[84:87], v[40:43], v[178:185], 0, v133, v133 op_sel_hi:[0,0,0] cbsz:4
	v_mfma_scale_f32_16x16x128_f8f6f4 v[84:87], v[44:47], v[186:193], v[84:87], v133, v133 op_sel_hi:[0,0,0] cbsz:4
	v_mfma_scale_f32_16x16x128_f8f6f4 v[88:91], v[48:51], v[178:185], 0, v133, v133 op_sel_hi:[0,0,0] cbsz:4
	v_mfma_scale_f32_16x16x128_f8f6f4 v[88:91], v[52:55], v[186:193], v[88:91], v133, v133 op_sel_hi:[0,0,0] cbsz:4
	v_mfma_scale_f32_16x16x128_f8f6f4 v[92:95], v[56:59], v[178:185], 0, v133, v133 op_sel_hi:[0,0,0] cbsz:4
	v_mfma_scale_f32_16x16x128_f8f6f4 v[92:95], v[60:63], v[186:193], v[92:95], v133, v133 op_sel_hi:[0,0,0] cbsz:4
	s_nop 3
	v_mul_f32_e32 v234, v226, v64
	v_mul_f32_e32 v235, v226, v68
	v_mul_f32_e32 v236, v226, v72
	v_mul_f32_e32 v237, v226, v76
	v_fmac_f32_e32 v234, v227, v65
	v_fmac_f32_e32 v235, v227, v69
	v_fmac_f32_e32 v236, v227, v73
	v_fmac_f32_e32 v237, v227, v77
	v_fmac_f32_e32 v234, v228, v66
	v_fmac_f32_e32 v235, v228, v70
	v_fmac_f32_e32 v236, v228, v74
	v_fmac_f32_e32 v237, v228, v78
	v_fmac_f32_e32 v234, v229, v67
	v_fmac_f32_e32 v235, v229, v71
	v_fmac_f32_e32 v236, v229, v75
	v_fmac_f32_e32 v237, v229, v79
	v_add_f32_dpp v234, v234, v234 quad_perm:[1,0,3,2] row_mask:0xf bank_mask:0xf
	v_add_f32_dpp v235, v235, v235 quad_perm:[1,0,3,2] row_mask:0xf bank_mask:0xf
	v_add_f32_dpp v236, v236, v236 quad_perm:[1,0,3,2] row_mask:0xf bank_mask:0xf
	v_add_f32_dpp v237, v237, v237 quad_perm:[1,0,3,2] row_mask:0xf bank_mask:0xf
	v_add_f32_dpp v234, v234, v234 quad_perm:[2,3,0,1] row_mask:0xf bank_mask:0xf
	v_add_f32_dpp v235, v235, v235 quad_perm:[2,3,0,1] row_mask:0xf bank_mask:0xf
	v_add_f32_dpp v236, v236, v236 quad_perm:[2,3,0,1] row_mask:0xf bank_mask:0xf
	v_add_f32_dpp v237, v237, v237 quad_perm:[2,3,0,1] row_mask:0xf bank_mask:0xf
	v_add_f32_dpp v234, v234, v234 row_half_mirror row_mask:0xf bank_mask:0xf
	v_add_f32_dpp v235, v235, v235 row_half_mirror row_mask:0xf bank_mask:0xf
	v_add_f32_dpp v236, v236, v236 row_half_mirror row_mask:0xf bank_mask:0xf
	v_add_f32_dpp v237, v237, v237 row_half_mirror row_mask:0xf bank_mask:0xf
	s_mov_b32 exec_lo, 0x1000100
	s_mov_b32 exec_hi, 0x1000100
	ds_write_b32 v155, v234 offset:2368
	ds_write_b32 v155, v235 offset:2384
	ds_write_b32 v155, v236 offset:2400
	ds_write_b32 v155, v237 offset:2416
	s_mov_b64 exec, -1
	s_waitcnt lgkmcnt(0)
; __device__ __forceinline__ void peer_token(const Params& P, int t, int lane, int* sidx, float* sval, const int* sid, const float* sgate, const unsigned* szero) {
;     ...
;         for (int hh = 0; hh < 2; ++hh)
; #pragma unroll
;             for (int st = 0; st < 4; ++st) abuf[0][hh][st] = *(const uint4*)(Ub + (off2[hh] + 128 * st));
; #pragma unroll
;         for (int T = 0; T < 8; ++T) {
;             if (T + 1 < 8) {
; #pragma unroll
;                 for (int hh = 0; hh < 2; ++hh) off2[hh] = (unsigned)sid[16 * (T + 1) + 8 * hh + (lr & 7)] * 512u + lofs;
; #pragma unroll
;                 for (int hh = 0; hh < 2; ++hh)
; #pragma unroll
;                     for (int st = 0; st < 4; ++st) abuf[(T + 1) & 1][hh][st] = *(const uint4*)(Ub + (off2[hh] + 128 * st));
;             }
; #pragma unroll
;             for (int hh = 0; hh < 2; ++hh) {
;                 f32x4 au = (f32x4){0.f, 0.f, 0.f, 0.f};
; #pragma unroll
;                 for (int st = 0; st < 4; ++st) {
;                     const uint4 a4 = abuf[T & 1][hh][st];
;                     const v8i Av = {(int)a4.x, (int)a4.y, (int)a4.z, (int)a4.w, 0, 0, 0, 0};
;                     au = __builtin_amdgcn_mfma_scale_f32_16x16x128_f8f6f4(Av, Bv[st], au, 4, 0, 0, 0x7f7f7f7f, 0, 0x7f7f7f7f);
;                 }
;                 if (owner) *(f32x4*)(sact + 16 * T + 8 * hh) = au;
;             }
;         }
	v_lshl_add_u32 v230, v230, 9, v144
	v_lshl_add_u32 v231, v231, 9, v144
	v_lshl_add_u32 v232, v232, 9, v144
	v_lshl_add_u32 v233, v233, 9, v144
	global_load_dwordx4 v[32:35], v230, s[10:11]
	global_load_dwordx4 v[36:39], v230, s[10:11] offset:256
	global_load_dwordx4 v[40:43], v231, s[10:11]
	global_load_dwordx4 v[44:47], v231, s[10:11] offset:256
	global_load_dwordx4 v[48:51], v232, s[10:11]
	global_load_dwordx4 v[52:55], v232, s[10:11] offset:256
	global_load_dwordx4 v[56:59], v233, s[10:11]
	global_load_dwordx4 v[60:63], v233, s[10:11] offset:256
	ds_read2_b32 v[96:97], v238 offset0:96 offset1:100
	ds_read2_b32 v[98:99], v238 offset0:104 offset1:108
	s_waitcnt vmcnt(8)
	v_mfma_scale_f32_16x16x128_f8f6f4 v[64:67], v[0:3], v[194:201], 0, v133, v133 op_sel_hi:[0,0,0] cbsz:4
	v_mfma_scale_f32_16x16x128_f8f6f4 v[64:67], v[4:7], v[202:209], v[64:67], v133, v133 op_sel_hi:[0,0,0] cbsz:4
	v_mfma_scale_f32_16x16x128_f8f6f4 v[68:71], v[8:11], v[194:201], 0, v133, v133 op_sel_hi:[0,0,0] cbsz:4
	v_mfma_scale_f32_16x16x128_f8f6f4 v[68:71], v[12:15], v[202:209], v[68:71], v133, v133 op_sel_hi:[0,0,0] cbsz:4
	v_mfma_scale_f32_16x16x128_f8f6f4 v[72:75], v[16:19], v[194:201], 0, v133, v133 op_sel_hi:[0,0,0] cbsz:4
	v_mfma_scale_f32_16x16x128_f8f6f4 v[72:75], v[20:23], v[202:209], v[72:75], v133, v133 op_sel_hi:[0,0,0] cbsz:4
	v_mfma_scale_f32_16x16x128_f8f6f4 v[76:79], v[24:27], v[194:201], 0, v133, v133 op_sel_hi:[0,0,0] cbsz:4
	v_mfma_scale_f32_16x16x128_f8f6f4 v[76:79], v[28:31], v[202:209], v[76:79], v133, v133 op_sel_hi:[0,0,0] cbsz:4
	s_nop 3
	v_mul_f32_e32 v234, v226, v80
	v_mul_f32_e32 v235, v226, v84
	v_mul_f32_e32 v236, v226, v88
	v_mul_f32_e32 v237, v226, v92
	v_fmac_f32_e32 v234, v227, v81
	v_fmac_f32_e32 v235, v227, v85
	v_fmac_f32_e32 v236, v227, v89
	v_fmac_f32_e32 v237, v227, v93
	v_fmac_f32_e32 v234, v228, v82
	v_fmac_f32_e32 v235, v228, v86
	v_fmac_f32_e32 v236, v228, v90
	v_fmac_f32_e32 v237, v228, v94
	v_fmac_f32_e32 v234, v229, v83
	v_fmac_f32_e32 v235, v229, v87
	v_fmac_f32_e32 v236, v229, v91
	v_fmac_f32_e32 v237, v229, v95
	v_add_f32_dpp v234, v234, v234 quad_perm:[1,0,3,2] row_mask:0xf bank_mask:0xf
	v_add_f32_dpp v235, v235, v235 quad_perm:[1,0,3,2] row_mask:0xf bank_mask:0xf
	v_add_f32_dpp v236, v236, v236 quad_perm:[1,0,3,2] row_mask:0xf bank_mask:0xf
	v_add_f32_dpp v237, v237, v237 quad_perm:[1,0,3,2] row_mask:0xf bank_mask:0xf
	v_add_f32_dpp v234, v234, v234 quad_perm:[2,3,0,1] row_mask:0xf bank_mask:0xf
	v_add_f32_dpp v235, v235, v235 quad_perm:[2,3,0,1] row_mask:0xf bank_mask:0xf
	v_add_f32_dpp v236, v236, v236 quad_perm:[2,3,0,1] row_mask:0xf bank_mask:0xf
	v_add_f32_dpp v237, v237, v237 quad_perm:[2,3,0,1] row_mask:0xf bank_mask:0xf
	v_add_f32_dpp v234, v234, v234 row_half_mirror row_mask:0xf bank_mask:0xf
	v_add_f32_dpp v235, v235, v235 row_half_mirror row_mask:0xf bank_mask:0xf
	v_add_f32_dpp v236, v236, v236 row_half_mirror row_mask:0xf bank_mask:0xf
	v_add_f32_dpp v237, v237, v237 row_half_mirror row_mask:0xf bank_mask:0xf
	s_mov_b32 exec_lo, 0x1000100
	s_mov_b32 exec_hi, 0x1000100
	ds_write_b32 v155, v234 offset:2880
	ds_write_b32 v155, v235 offset:2896
	ds_write_b32 v155, v236 offset:2912
	ds_write_b32 v155, v237 offset:2928
	s_mov_b64 exec, -1
	s_waitcnt lgkmcnt(0)
	v_lshl_add_u32 v96, v96, 9, v144
	v_lshl_add_u32 v97, v97, 9, v144
	v_lshl_add_u32 v98, v98, 9, v144
	v_lshl_add_u32 v99, v99, 9, v144
	global_load_dwordx4 v[0:3], v96, s[10:11]
	global_load_dwordx4 v[4:7], v96, s[10:11] offset:256
	global_load_dwordx4 v[8:11], v97, s[10:11]
	global_load_dwordx4 v[12:15], v97, s[10:11] offset:256
	global_load_dwordx4 v[16:19], v98, s[10:11]
	global_load_dwordx4 v[20:23], v98, s[10:11] offset:256
	global_load_dwordx4 v[24:27], v99, s[10:11]
	global_load_dwordx4 v[28:31], v99, s[10:11] offset:256
	ds_read2_b32 v[230:231], v239 offset0:96 offset1:100
	ds_read2_b32 v[232:233], v239 offset0:104 offset1:108
	s_waitcnt vmcnt(8)
	v_mfma_scale_f32_16x16x128_f8f6f4 v[80:83], v[32:35], v[210:217], 0, v133, v133 op_sel_hi:[0,0,0] cbsz:4
	v_mfma_scale_f32_16x16x128_f8f6f4 v[80:83], v[36:39], v[218:225], v[80:83], v133, v133 op_sel_hi:[0,0,0] cbsz:4
	v_mfma_scale_f32_16x16x128_f8f6f4 v[84:87], v[40:43], v[210:217], 0, v133, v133 op_sel_hi:[0,0,0] cbsz:4
	v_mfma_scale_f32_16x16x128_f8f6f4 v[84:87], v[44:47], v[218:225], v[84:87], v133, v133 op_sel_hi:[0,0,0] cbsz:4
	v_mfma_scale_f32_16x16x128_f8f6f4 v[88:91], v[48:51], v[210:217], 0, v133, v133 op_sel_hi:[0,0,0] cbsz:4
	v_mfma_scale_f32_16x16x128_f8f6f4 v[88:91], v[52:55], v[218:225], v[88:91], v133, v133 op_sel_hi:[0,0,0] cbsz:4
	v_mfma_scale_f32_16x16x128_f8f6f4 v[92:95], v[56:59], v[210:217], 0, v133, v133 op_sel_hi:[0,0,0] cbsz:4
	v_mfma_scale_f32_16x16x128_f8f6f4 v[92:95], v[60:63], v[218:225], v[92:95], v133, v133 op_sel_hi:[0,0,0] cbsz:4
	s_nop 3
	v_mul_f32_e32 v234, v226, v64
	v_mul_f32_e32 v235, v226, v68
	v_mul_f32_e32 v236, v226, v72
	v_mul_f32_e32 v237, v226, v76
	v_fmac_f32_e32 v234, v227, v65
	v_fmac_f32_e32 v235, v227, v69
	v_fmac_f32_e32 v236, v227, v73
	v_fmac_f32_e32 v237, v227, v77
	v_fmac_f32_e32 v234, v228, v66
	v_fmac_f32_e32 v235, v228, v70
	v_fmac_f32_e32 v236, v228, v74
	v_fmac_f32_e32 v237, v228, v78
	v_fmac_f32_e32 v234, v229, v67
	v_fmac_f32_e32 v235, v229, v71
	v_fmac_f32_e32 v236, v229, v75
	v_fmac_f32_e32 v237, v229, v79
	v_add_f32_dpp v234, v234, v234 quad_perm:[1,0,3,2] row_mask:0xf bank_mask:0xf
	v_add_f32_dpp v235, v235, v235 quad_perm:[1,0,3,2] row_mask:0xf bank_mask:0xf
	v_add_f32_dpp v236, v236, v236 quad_perm:[1,0,3,2] row_mask:0xf bank_mask:0xf
	v_add_f32_dpp v237, v237, v237 quad_perm:[1,0,3,2] row_mask:0xf bank_mask:0xf
	v_add_f32_dpp v234, v234, v234 quad_perm:[2,3,0,1] row_mask:0xf bank_mask:0xf
	v_add_f32_dpp v235, v235, v235 quad_perm:[2,3,0,1] row_mask:0xf bank_mask:0xf
	v_add_f32_dpp v236, v236, v236 quad_perm:[2,3,0,1] row_mask:0xf bank_mask:0xf
	v_add_f32_dpp v237, v237, v237 quad_perm:[2,3,0,1] row_mask:0xf bank_mask:0xf
	v_add_f32_dpp v234, v234, v234 row_half_mirror row_mask:0xf bank_mask:0xf
	v_add_f32_dpp v235, v235, v235 row_half_mirror row_mask:0xf bank_mask:0xf
	v_add_f32_dpp v236, v236, v236 row_half_mirror row_mask:0xf bank_mask:0xf
	v_add_f32_dpp v237, v237, v237 row_half_mirror row_mask:0xf bank_mask:0xf
	s_mov_b32 exec_lo, 0x1000100
	s_mov_b32 exec_hi, 0x1000100
	ds_write_b32 v155, v234 offset:3392
	ds_write_b32 v155, v235 offset:3408
	ds_write_b32 v155, v236 offset:3424
	ds_write_b32 v155, v237 offset:3440
	s_mov_b64 exec, -1
	s_waitcnt lgkmcnt(0)
; __device__ __forceinline__ void peer_token(const Params& P, int t, int lane, int* sidx, float* sval, const int* sid, const float* sgate, const unsigned* szero) {
;     ...
;         for (int hh = 0; hh < 2; ++hh)
; #pragma unroll
;             for (int st = 0; st < 4; ++st) abuf[0][hh][st] = *(const uint4*)(Ub + (off2[hh] + 128 * st));
; #pragma unroll
;         for (int T = 0; T < 8; ++T) {
;             if (T + 1 < 8) {
; #pragma unroll
;                 for (int hh = 0; hh < 2; ++hh) off2[hh] = (unsigned)sid[16 * (T + 1) + 8 * hh + (lr & 7)] * 512u + lofs;
; #pragma unroll
;                 for (int hh = 0; hh < 2; ++hh)
; #pragma unroll
;                     for (int st = 0; st < 4; ++st) abuf[(T + 1) & 1][hh][st] = *(const uint4*)(Ub + (off2[hh] + 128 * st));
;             }
; #pragma unroll
;             for (int hh = 0; hh < 2; ++hh) {
;                 f32x4 au = (f32x4){0.f, 0.f, 0.f, 0.f};
; #pragma unroll
;                 for (int st = 0; st < 4; ++st) {
;                     const uint4 a4 = abuf[T & 1][hh][st];
;                     const v8i Av = {(int)a4.x, (int)a4.y, (int)a4.z, (int)a4.w, 0, 0, 0, 0};
;                     au = __builtin_amdgcn_mfma_scale_f32_16x16x128_f8f6f4(Av, Bv[st], au, 4, 0, 0, 0x7f7f7f7f, 0, 0x7f7f7f7f);
;                 }
;                 if (owner) *(f32x4*)(sact + 16 * T + 8 * hh) = au;
;             }
;         }
	v_lshl_add_u32 v230, v230, 9, v144
	v_lshl_add_u32 v231, v231, 9, v144
	v_lshl_add_u32 v232, v232, 9, v144
	v_lshl_add_u32 v233, v233, 9, v144
	global_load_dwordx4 v[32:35], v230, s[10:11]
	global_load_dwordx4 v[36:39], v230, s[10:11] offset:256
	global_load_dwordx4 v[40:43], v231, s[10:11]
	global_load_dwordx4 v[44:47], v231, s[10:11] offset:256
	global_load_dwordx4 v[48:51], v232, s[10:11]
	global_load_dwordx4 v[52:55], v232, s[10:11] offset:256
	global_load_dwordx4 v[56:59], v233, s[10:11]
	global_load_dwordx4 v[60:63], v233, s[10:11] offset:256
	ds_read2_b32 v[96:97], v240 offset0:96 offset1:100
	ds_read2_b32 v[98:99], v240 offset0:104 offset1:108
	s_waitcnt vmcnt(8)
	v_mfma_scale_f32_16x16x128_f8f6f4 v[64:67], v[0:3], v[162:169], 0, v133, v133 op_sel_hi:[0,0,0] cbsz:4
	v_mfma_scale_f32_16x16x128_f8f6f4 v[64:67], v[4:7], v[170:177], v[64:67], v133, v133 op_sel_hi:[0,0,0] cbsz:4
	v_mfma_scale_f32_16x16x128_f8f6f4 v[68:71], v[8:11], v[162:169], 0, v133, v133 op_sel_hi:[0,0,0] cbsz:4
	v_mfma_scale_f32_16x16x128_f8f6f4 v[68:71], v[12:15], v[170:177], v[68:71], v133, v133 op_sel_hi:[0,0,0] cbsz:4
	v_mfma_scale_f32_16x16x128_f8f6f4 v[72:75], v[16:19], v[162:169], 0, v133, v133 op_sel_hi:[0,0,0] cbsz:4
	v_mfma_scale_f32_16x16x128_f8f6f4 v[72:75], v[20:23], v[170:177], v[72:75], v133, v133 op_sel_hi:[0,0,0] cbsz:4
	v_mfma_scale_f32_16x16x128_f8f6f4 v[76:79], v[24:27], v[162:169], 0, v133, v133 op_sel_hi:[0,0,0] cbsz:4
	v_mfma_scale_f32_16x16x128_f8f6f4 v[76:79], v[28:31], v[170:177], v[76:79], v133, v133 op_sel_hi:[0,0,0] cbsz:4
	s_nop 3
	v_mul_f32_e32 v234, v226, v80
	v_mul_f32_e32 v235, v226, v84
	v_mul_f32_e32 v236, v226, v88
	v_mul_f32_e32 v237, v226, v92
	v_fmac_f32_e32 v234, v227, v81
	v_fmac_f32_e32 v235, v227, v85
	v_fmac_f32_e32 v236, v227, v89
	v_fmac_f32_e32 v237, v227, v93
	v_fmac_f32_e32 v234, v228, v82
	v_fmac_f32_e32 v235, v228, v86
	v_fmac_f32_e32 v236, v228, v90
	v_fmac_f32_e32 v237, v228, v94
	v_fmac_f32_e32 v234, v229, v83
	v_fmac_f32_e32 v235, v229, v87
	v_fmac_f32_e32 v236, v229, v91
	v_fmac_f32_e32 v237, v229, v95
	v_add_f32_dpp v234, v234, v234 quad_perm:[1,0,3,2] row_mask:0xf bank_mask:0xf
	v_add_f32_dpp v235, v235, v235 quad_perm:[1,0,3,2] row_mask:0xf bank_mask:0xf
	v_add_f32_dpp v236, v236, v236 quad_perm:[1,0,3,2] row_mask:0xf bank_mask:0xf
	v_add_f32_dpp v237, v237, v237 quad_perm:[1,0,3,2] row_mask:0xf bank_mask:0xf
	v_add_f32_dpp v234, v234, v234 quad_perm:[2,3,0,1] row_mask:0xf bank_mask:0xf
	v_add_f32_dpp v235, v235, v235 quad_perm:[2,3,0,1] row_mask:0xf bank_mask:0xf
	v_add_f32_dpp v236, v236, v236 quad_perm:[2,3,0,1] row_mask:0xf bank_mask:0xf
	v_add_f32_dpp v237, v237, v237 quad_perm:[2,3,0,1] row_mask:0xf bank_mask:0xf
	v_add_f32_dpp v234, v234, v234 row_half_mirror row_mask:0xf bank_mask:0xf
	v_add_f32_dpp v235, v235, v235 row_half_mirror row_mask:0xf bank_mask:0xf
	v_add_f32_dpp v236, v236, v236 row_half_mirror row_mask:0xf bank_mask:0xf
	v_add_f32_dpp v237, v237, v237 row_half_mirror row_mask:0xf bank_mask:0xf
	s_mov_b32 exec_lo, 0x1000100
	s_mov_b32 exec_hi, 0x1000100
	ds_write_b32 v155, v234 offset:3904
	ds_write_b32 v155, v235 offset:3920
	ds_write_b32 v155, v236 offset:3936
	ds_write_b32 v155, v237 offset:3952
	s_mov_b64 exec, -1
	s_waitcnt lgkmcnt(0)
	v_lshl_add_u32 v96, v96, 9, v144
	v_lshl_add_u32 v97, v97, 9, v144
	v_lshl_add_u32 v98, v98, 9, v144
	v_lshl_add_u32 v99, v99, 9, v144
	global_load_dwordx4 v[0:3], v96, s[10:11]
	global_load_dwordx4 v[4:7], v96, s[10:11] offset:256
	global_load_dwordx4 v[8:11], v97, s[10:11]
	global_load_dwordx4 v[12:15], v97, s[10:11] offset:256
	global_load_dwordx4 v[16:19], v98, s[10:11]
	global_load_dwordx4 v[20:23], v98, s[10:11] offset:256
	global_load_dwordx4 v[24:27], v99, s[10:11]
	global_load_dwordx4 v[28:31], v99, s[10:11] offset:256
	ds_read2_b32 v[230:231], v241 offset0:96 offset1:100
	ds_read2_b32 v[232:233], v241 offset0:104 offset1:108
	s_waitcnt vmcnt(8)
	v_mfma_scale_f32_16x16x128_f8f6f4 v[80:83], v[32:35], v[178:185], 0, v133, v133 op_sel_hi:[0,0,0] cbsz:4
	v_mfma_scale_f32_16x16x128_f8f6f4 v[80:83], v[36:39], v[186:193], v[80:83], v133, v133 op_sel_hi:[0,0,0] cbsz:4
	v_mfma_scale_f32_16x16x128_f8f6f4 v[84:87], v[40:43], v[178:185], 0, v133, v133 op_sel_hi:[0,0,0] cbsz:4
	v_mfma_scale_f32_16x16x128_f8f6f4 v[84:87], v[44:47], v[186:193], v[84:87], v133, v133 op_sel_hi:[0,0,0] cbsz:4
	v_mfma_scale_f32_16x16x128_f8f6f4 v[88:91], v[48:51], v[178:185], 0, v133, v133 op_sel_hi:[0,0,0] cbsz:4
	v_mfma_scale_f32_16x16x128_f8f6f4 v[88:91], v[52:55], v[186:193], v[88:91], v133, v133 op_sel_hi:[0,0,0] cbsz:4
	v_mfma_scale_f32_16x16x128_f8f6f4 v[92:95], v[56:59], v[178:185], 0, v133, v133 op_sel_hi:[0,0,0] cbsz:4
	v_mfma_scale_f32_16x16x128_f8f6f4 v[92:95], v[60:63], v[186:193], v[92:95], v133, v133 op_sel_hi:[0,0,0] cbsz:4
	s_nop 3
	v_mul_f32_e32 v234, v158, v64
	v_mul_f32_e32 v235, v158, v68
	v_mul_f32_e32 v236, v158, v72
	v_mul_f32_e32 v237, v158, v76
	v_fmac_f32_e32 v234, v159, v65
	v_fmac_f32_e32 v235, v159, v69
	v_fmac_f32_e32 v236, v159, v73
	v_fmac_f32_e32 v237, v159, v77
	v_fmac_f32_e32 v234, v160, v66
	v_fmac_f32_e32 v235, v160, v70
	v_fmac_f32_e32 v236, v160, v74
	v_fmac_f32_e32 v237, v160, v78
	v_fmac_f32_e32 v234, v161, v67
	v_fmac_f32_e32 v235, v161, v71
	v_fmac_f32_e32 v236, v161, v75
	v_fmac_f32_e32 v237, v161, v79
	v_add_f32_dpp v234, v234, v234 quad_perm:[1,0,3,2] row_mask:0xf bank_mask:0xf
	v_add_f32_dpp v235, v235, v235 quad_perm:[1,0,3,2] row_mask:0xf bank_mask:0xf
	v_add_f32_dpp v236, v236, v236 quad_perm:[1,0,3,2] row_mask:0xf bank_mask:0xf
	v_add_f32_dpp v237, v237, v237 quad_perm:[1,0,3,2] row_mask:0xf bank_mask:0xf
	v_add_f32_dpp v234, v234, v234 quad_perm:[2,3,0,1] row_mask:0xf bank_mask:0xf
	v_add_f32_dpp v235, v235, v235 quad_perm:[2,3,0,1] row_mask:0xf bank_mask:0xf
	v_add_f32_dpp v236, v236, v236 quad_perm:[2,3,0,1] row_mask:0xf bank_mask:0xf
	v_add_f32_dpp v237, v237, v237 quad_perm:[2,3,0,1] row_mask:0xf bank_mask:0xf
	v_add_f32_dpp v234, v234, v234 row_half_mirror row_mask:0xf bank_mask:0xf
	v_add_f32_dpp v235, v235, v235 row_half_mirror row_mask:0xf bank_mask:0xf
	v_add_f32_dpp v236, v236, v236 row_half_mirror row_mask:0xf bank_mask:0xf
	v_add_f32_dpp v237, v237, v237 row_half_mirror row_mask:0xf bank_mask:0xf
	s_mov_b32 exec_lo, 0x10001
	s_mov_b32 exec_hi, 0x10001
	ds_write_b32 v155, v234 offset:384
	ds_write_b32 v155, v235 offset:400
	ds_write_b32 v155, v236 offset:416
	ds_write_b32 v155, v237 offset:432
	s_mov_b64 exec, -1
	s_waitcnt lgkmcnt(0)
; __device__ __forceinline__ void peer_token(const Params& P, int t, int lane, int* sidx, float* sval, const int* sid, const float* sgate, const unsigned* szero) {
;     ...
;         for (int hh = 0; hh < 2; ++hh)
; #pragma unroll
;             for (int st = 0; st < 4; ++st) abuf[0][hh][st] = *(const uint4*)(Ub + (off2[hh] + 128 * st));
; #pragma unroll
;         for (int T = 0; T < 8; ++T) {
;             if (T + 1 < 8) {
; #pragma unroll
;                 for (int hh = 0; hh < 2; ++hh) off2[hh] = (unsigned)sid[16 * (T + 1) + 8 * hh + (lr & 7)] * 512u + lofs;
; #pragma unroll
;                 for (int hh = 0; hh < 2; ++hh)
; #pragma unroll
;                     for (int st = 0; st < 4; ++st) abuf[(T + 1) & 1][hh][st] = *(const uint4*)(Ub + (off2[hh] + 128 * st));
;             }
; #pragma unroll
;             for (int hh = 0; hh < 2; ++hh) {
;                 f32x4 au = (f32x4){0.f, 0.f, 0.f, 0.f};
; #pragma unroll
;                 for (int st = 0; st < 4; ++st) {
;                     const uint4 a4 = abuf[T & 1][hh][st];
;                     const v8i Av = {(int)a4.x, (int)a4.y, (int)a4.z, (int)a4.w, 0, 0, 0, 0};
;                     au = __builtin_amdgcn_mfma_scale_f32_16x16x128_f8f6f4(Av, Bv[st], au, 4, 0, 0, 0x7f7f7f7f, 0, 0x7f7f7f7f);
;                 }
;                 if (owner) *(f32x4*)(sact + 16 * T + 8 * hh) = au;
;             }
;         }
	v_lshl_add_u32 v230, v230, 9, v144
	v_lshl_add_u32 v231, v231, 9, v144
	v_lshl_add_u32 v232, v232, 9, v144
	v_lshl_add_u32 v233, v233, 9, v144
	global_load_dwordx4 v[32:35], v230, s[10:11]
	global_load_dwordx4 v[36:39], v230, s[10:11] offset:256
	global_load_dwordx4 v[40:43], v231, s[10:11]
	global_load_dwordx4 v[44:47], v231, s[10:11] offset:256
	global_load_dwordx4 v[48:51], v232, s[10:11]
	global_load_dwordx4 v[52:55], v232, s[10:11] offset:256
	global_load_dwordx4 v[56:59], v233, s[10:11]
	global_load_dwordx4 v[60:63], v233, s[10:11] offset:256
	ds_read2_b32 v[96:97], v242 offset0:96 offset1:100
	ds_read2_b32 v[98:99], v242 offset0:104 offset1:108
	s_waitcnt vmcnt(8)
	v_mfma_scale_f32_16x16x128_f8f6f4 v[64:67], v[0:3], v[194:201], 0, v133, v133 op_sel_hi:[0,0,0] cbsz:4
	v_mfma_scale_f32_16x16x128_f8f6f4 v[64:67], v[4:7], v[202:209], v[64:67], v133, v133 op_sel_hi:[0,0,0] cbsz:4
	v_mfma_scale_f32_16x16x128_f8f6f4 v[68:71], v[8:11], v[194:201], 0, v133, v133 op_sel_hi:[0,0,0] cbsz:4
	v_mfma_scale_f32_16x16x128_f8f6f4 v[68:71], v[12:15], v[202:209], v[68:71], v133, v133 op_sel_hi:[0,0,0] cbsz:4
	v_mfma_scale_f32_16x16x128_f8f6f4 v[72:75], v[16:19], v[194:201], 0, v133, v133 op_sel_hi:[0,0,0] cbsz:4
	v_mfma_scale_f32_16x16x128_f8f6f4 v[72:75], v[20:23], v[202:209], v[72:75], v133, v133 op_sel_hi:[0,0,0] cbsz:4
	v_mfma_scale_f32_16x16x128_f8f6f4 v[76:79], v[24:27], v[194:201], 0, v133, v133 op_sel_hi:[0,0,0] cbsz:4
	v_mfma_scale_f32_16x16x128_f8f6f4 v[76:79], v[28:31], v[202:209], v[76:79], v133, v133 op_sel_hi:[0,0,0] cbsz:4
	s_nop 3
	v_mul_f32_e32 v234, v158, v80
	v_mul_f32_e32 v235, v158, v84
	v_mul_f32_e32 v236, v158, v88
	v_mul_f32_e32 v237, v158, v92
	v_fmac_f32_e32 v234, v159, v81
	v_fmac_f32_e32 v235, v159, v85
	v_fmac_f32_e32 v236, v159, v89
	v_fmac_f32_e32 v237, v159, v93
	v_fmac_f32_e32 v234, v160, v82
	v_fmac_f32_e32 v235, v160, v86
	v_fmac_f32_e32 v236, v160, v90
	v_fmac_f32_e32 v237, v160, v94
	v_fmac_f32_e32 v234, v161, v83
	v_fmac_f32_e32 v235, v161, v87
	v_fmac_f32_e32 v236, v161, v91
	v_fmac_f32_e32 v237, v161, v95
	v_add_f32_dpp v234, v234, v234 quad_perm:[1,0,3,2] row_mask:0xf bank_mask:0xf
	v_add_f32_dpp v235, v235, v235 quad_perm:[1,0,3,2] row_mask:0xf bank_mask:0xf
	v_add_f32_dpp v236, v236, v236 quad_perm:[1,0,3,2] row_mask:0xf bank_mask:0xf
	v_add_f32_dpp v237, v237, v237 quad_perm:[1,0,3,2] row_mask:0xf bank_mask:0xf
	v_add_f32_dpp v234, v234, v234 quad_perm:[2,3,0,1] row_mask:0xf bank_mask:0xf
	v_add_f32_dpp v235, v235, v235 quad_perm:[2,3,0,1] row_mask:0xf bank_mask:0xf
	v_add_f32_dpp v236, v236, v236 quad_perm:[2,3,0,1] row_mask:0xf bank_mask:0xf
	v_add_f32_dpp v237, v237, v237 quad_perm:[2,3,0,1] row_mask:0xf bank_mask:0xf
	v_add_f32_dpp v234, v234, v234 row_half_mirror row_mask:0xf bank_mask:0xf
	v_add_f32_dpp v235, v235, v235 row_half_mirror row_mask:0xf bank_mask:0xf
	v_add_f32_dpp v236, v236, v236 row_half_mirror row_mask:0xf bank_mask:0xf
	v_add_f32_dpp v237, v237, v237 row_half_mirror row_mask:0xf bank_mask:0xf
	s_mov_b32 exec_lo, 0x10001
	s_mov_b32 exec_hi, 0x10001
	ds_write_b32 v155, v234 offset:896
	ds_write_b32 v155, v235 offset:912
	ds_write_b32 v155, v236 offset:928
	ds_write_b32 v155, v237 offset:944
	s_mov_b64 exec, -1
	s_waitcnt lgkmcnt(0)
	v_lshl_add_u32 v96, v96, 9, v144
	v_lshl_add_u32 v97, v97, 9, v144
	v_lshl_add_u32 v98, v98, 9, v144
	v_lshl_add_u32 v99, v99, 9, v144
	global_load_dwordx4 v[0:3], v96, s[10:11]
	global_load_dwordx4 v[4:7], v96, s[10:11] offset:256
	global_load_dwordx4 v[8:11], v97, s[10:11]
	global_load_dwordx4 v[12:15], v97, s[10:11] offset:256
	global_load_dwordx4 v[16:19], v98, s[10:11]
	global_load_dwordx4 v[20:23], v98, s[10:11] offset:256
	global_load_dwordx4 v[24:27], v99, s[10:11]
	global_load_dwordx4 v[28:31], v99, s[10:11] offset:256
	ds_read2_b32 v[230:231], v243 offset0:96 offset1:100
	ds_read2_b32 v[232:233], v243 offset0:104 offset1:108
	s_waitcnt vmcnt(8)
	v_mfma_scale_f32_16x16x128_f8f6f4 v[80:83], v[32:35], v[210:217], 0, v133, v133 op_sel_hi:[0,0,0] cbsz:4
	v_mfma_scale_f32_16x16x128_f8f6f4 v[80:83], v[36:39], v[218:225], v[80:83], v133, v133 op_sel_hi:[0,0,0] cbsz:4
	v_mfma_scale_f32_16x16x128_f8f6f4 v[84:87], v[40:43], v[210:217], 0, v133, v133 op_sel_hi:[0,0,0] cbsz:4
	v_mfma_scale_f32_16x16x128_f8f6f4 v[84:87], v[44:47], v[218:225], v[84:87], v133, v133 op_sel_hi:[0,0,0] cbsz:4
	v_mfma_scale_f32_16x16x128_f8f6f4 v[88:91], v[48:51], v[210:217], 0, v133, v133 op_sel_hi:[0,0,0] cbsz:4
	v_mfma_scale_f32_16x16x128_f8f6f4 v[88:91], v[52:55], v[218:225], v[88:91], v133, v133 op_sel_hi:[0,0,0] cbsz:4
	v_mfma_scale_f32_16x16x128_f8f6f4 v[92:95], v[56:59], v[210:217], 0, v133, v133 op_sel_hi:[0,0,0] cbsz:4
	v_mfma_scale_f32_16x16x128_f8f6f4 v[92:95], v[60:63], v[218:225], v[92:95], v133, v133 op_sel_hi:[0,0,0] cbsz:4
	s_nop 3
	v_mul_f32_e32 v234, v158, v64
	v_mul_f32_e32 v235, v158, v68
	v_mul_f32_e32 v236, v158, v72
	v_mul_f32_e32 v237, v158, v76
	v_fmac_f32_e32 v234, v159, v65
	v_fmac_f32_e32 v235, v159, v69
	v_fmac_f32_e32 v236, v159, v73
	v_fmac_f32_e32 v237, v159, v77
	v_fmac_f32_e32 v234, v160, v66
	v_fmac_f32_e32 v235, v160, v70
	v_fmac_f32_e32 v236, v160, v74
	v_fmac_f32_e32 v237, v160, v78
	v_fmac_f32_e32 v234, v161, v67
	v_fmac_f32_e32 v235, v161, v71
	v_fmac_f32_e32 v236, v161, v75
	v_fmac_f32_e32 v237, v161, v79
	v_add_f32_dpp v234, v234, v234 quad_perm:[1,0,3,2] row_mask:0xf bank_mask:0xf
	v_add_f32_dpp v235, v235, v235 quad_perm:[1,0,3,2] row_mask:0xf bank_mask:0xf
	v_add_f32_dpp v236, v236, v236 quad_perm:[1,0,3,2] row_mask:0xf bank_mask:0xf
	v_add_f32_dpp v237, v237, v237 quad_perm:[1,0,3,2] row_mask:0xf bank_mask:0xf
	v_add_f32_dpp v234, v234, v234 quad_perm:[2,3,0,1] row_mask:0xf bank_mask:0xf
	v_add_f32_dpp v235, v235, v235 quad_perm:[2,3,0,1] row_mask:0xf bank_mask:0xf
	v_add_f32_dpp v236, v236, v236 quad_perm:[2,3,0,1] row_mask:0xf bank_mask:0xf
	v_add_f32_dpp v237, v237, v237 quad_perm:[2,3,0,1] row_mask:0xf bank_mask:0xf
	v_add_f32_dpp v234, v234, v234 row_half_mirror row_mask:0xf bank_mask:0xf
	v_add_f32_dpp v235, v235, v235 row_half_mirror row_mask:0xf bank_mask:0xf
	v_add_f32_dpp v236, v236, v236 row_half_mirror row_mask:0xf bank_mask:0xf
	v_add_f32_dpp v237, v237, v237 row_half_mirror row_mask:0xf bank_mask:0xf
	s_mov_b32 exec_lo, 0x10001
	s_mov_b32 exec_hi, 0x10001
	ds_write_b32 v155, v234 offset:1408
	ds_write_b32 v155, v235 offset:1424
	ds_write_b32 v155, v236 offset:1440
	ds_write_b32 v155, v237 offset:1456
	s_mov_b64 exec, -1
	s_waitcnt lgkmcnt(0)
; __device__ __forceinline__ void peer_token(const Params& P, int t, int lane, int* sidx, float* sval, const int* sid, const float* sgate, const unsigned* szero) {
;     ...
;         for (int hh = 0; hh < 2; ++hh)
; #pragma unroll
;             for (int st = 0; st < 4; ++st) abuf[0][hh][st] = *(const uint4*)(Ub + (off2[hh] + 128 * st));
; #pragma unroll
;         for (int T = 0; T < 8; ++T) {
;             if (T + 1 < 8) {
; #pragma unroll
;                 for (int hh = 0; hh < 2; ++hh) off2[hh] = (unsigned)sid[16 * (T + 1) + 8 * hh + (lr & 7)] * 512u + lofs;
; #pragma unroll
;                 for (int hh = 0; hh < 2; ++hh)
; #pragma unroll
;                     for (int st = 0; st < 4; ++st) abuf[(T + 1) & 1][hh][st] = *(const uint4*)(Ub + (off2[hh] + 128 * st));
;             }
; #pragma unroll
;             for (int hh = 0; hh < 2; ++hh) {
;                 f32x4 au = (f32x4){0.f, 0.f, 0.f, 0.f};
; #pragma unroll
;                 for (int st = 0; st < 4; ++st) {
;                     const uint4 a4 = abuf[T & 1][hh][st];
;                     const v8i Av = {(int)a4.x, (int)a4.y, (int)a4.z, (int)a4.w, 0, 0, 0, 0};
;                     au = __builtin_amdgcn_mfma_scale_f32_16x16x128_f8f6f4(Av, Bv[st], au, 4, 0, 0, 0x7f7f7f7f, 0, 0x7f7f7f7f);
;                 }
;                 if (owner) *(f32x4*)(sact + 16 * T + 8 * hh) = au;
;             }
;         }
	v_lshl_add_u32 v230, v230, 9, v144
	v_lshl_add_u32 v231, v231, 9, v144
	v_lshl_add_u32 v232, v232, 9, v144
	v_lshl_add_u32 v233, v233, 9, v144
	global_load_dwordx4 v[32:35], v230, s[10:11]
	global_load_dwordx4 v[36:39], v230, s[10:11] offset:256
	global_load_dwordx4 v[40:43], v231, s[10:11]
	global_load_dwordx4 v[44:47], v231, s[10:11] offset:256
	global_load_dwordx4 v[48:51], v232, s[10:11]
	global_load_dwordx4 v[52:55], v232, s[10:11] offset:256
	global_load_dwordx4 v[56:59], v233, s[10:11]
	global_load_dwordx4 v[60:63], v233, s[10:11] offset:256
	ds_read2_b32 v[96:97], v244 offset0:96 offset1:100
	ds_read2_b32 v[98:99], v244 offset0:104 offset1:108
	s_waitcnt vmcnt(8)
	v_mfma_scale_f32_16x16x128_f8f6f4 v[64:67], v[0:3], v[162:169], 0, v133, v133 op_sel_hi:[0,0,0] cbsz:4
	v_mfma_scale_f32_16x16x128_f8f6f4 v[64:67], v[4:7], v[170:177], v[64:67], v133, v133 op_sel_hi:[0,0,0] cbsz:4
	v_mfma_scale_f32_16x16x128_f8f6f4 v[68:71], v[8:11], v[162:169], 0, v133, v133 op_sel_hi:[0,0,0] cbsz:4
	v_mfma_scale_f32_16x16x128_f8f6f4 v[68:71], v[12:15], v[170:177], v[68:71], v133, v133 op_sel_hi:[0,0,0] cbsz:4
	v_mfma_scale_f32_16x16x128_f8f6f4 v[72:75], v[16:19], v[162:169], 0, v133, v133 op_sel_hi:[0,0,0] cbsz:4
	v_mfma_scale_f32_16x16x128_f8f6f4 v[72:75], v[20:23], v[170:177], v[72:75], v133, v133 op_sel_hi:[0,0,0] cbsz:4
	v_mfma_scale_f32_16x16x128_f8f6f4 v[76:79], v[24:27], v[162:169], 0, v133, v133 op_sel_hi:[0,0,0] cbsz:4
	v_mfma_scale_f32_16x16x128_f8f6f4 v[76:79], v[28:31], v[170:177], v[76:79], v133, v133 op_sel_hi:[0,0,0] cbsz:4
	s_nop 3
	v_mul_f32_e32 v234, v158, v80
	v_mul_f32_e32 v235, v158, v84
	v_mul_f32_e32 v236, v158, v88
	v_mul_f32_e32 v237, v158, v92
	v_fmac_f32_e32 v234, v159, v81
	v_fmac_f32_e32 v235, v159, v85
	v_fmac_f32_e32 v236, v159, v89
	v_fmac_f32_e32 v237, v159, v93
	v_fmac_f32_e32 v234, v160, v82
	v_fmac_f32_e32 v235, v160, v86
	v_fmac_f32_e32 v236, v160, v90
	v_fmac_f32_e32 v237, v160, v94
	v_fmac_f32_e32 v234, v161, v83
	v_fmac_f32_e32 v235, v161, v87
	v_fmac_f32_e32 v236, v161, v91
	v_fmac_f32_e32 v237, v161, v95
	v_add_f32_dpp v234, v234, v234 quad_perm:[1,0,3,2] row_mask:0xf bank_mask:0xf
	v_add_f32_dpp v235, v235, v235 quad_perm:[1,0,3,2] row_mask:0xf bank_mask:0xf
	v_add_f32_dpp v236, v236, v236 quad_perm:[1,0,3,2] row_mask:0xf bank_mask:0xf
	v_add_f32_dpp v237, v237, v237 quad_perm:[1,0,3,2] row_mask:0xf bank_mask:0xf
	v_add_f32_dpp v234, v234, v234 quad_perm:[2,3,0,1] row_mask:0xf bank_mask:0xf
	v_add_f32_dpp v235, v235, v235 quad_perm:[2,3,0,1] row_mask:0xf bank_mask:0xf
	v_add_f32_dpp v236, v236, v236 quad_perm:[2,3,0,1] row_mask:0xf bank_mask:0xf
	v_add_f32_dpp v237, v237, v237 quad_perm:[2,3,0,1] row_mask:0xf bank_mask:0xf
	v_add_f32_dpp v234, v234, v234 row_half_mirror row_mask:0xf bank_mask:0xf
	v_add_f32_dpp v235, v235, v235 row_half_mirror row_mask:0xf bank_mask:0xf
	v_add_f32_dpp v236, v236, v236 row_half_mirror row_mask:0xf bank_mask:0xf
	v_add_f32_dpp v237, v237, v237 row_half_mirror row_mask:0xf bank_mask:0xf
	s_mov_b32 exec_lo, 0x10001
	s_mov_b32 exec_hi, 0x10001
	ds_write_b32 v155, v234 offset:1920
	ds_write_b32 v155, v235 offset:1936
	ds_write_b32 v155, v236 offset:1952
	ds_write_b32 v155, v237 offset:1968
	s_mov_b64 exec, -1
	s_waitcnt lgkmcnt(0)
	v_lshl_add_u32 v96, v96, 9, v144
	v_lshl_add_u32 v97, v97, 9, v144
	v_lshl_add_u32 v98, v98, 9, v144
	v_lshl_add_u32 v99, v99, 9, v144
	global_load_dwordx4 v[0:3], v96, s[10:11]
	global_load_dwordx4 v[4:7], v96, s[10:11] offset:256
	global_load_dwordx4 v[8:11], v97, s[10:11]
	global_load_dwordx4 v[12:15], v97, s[10:11] offset:256
	global_load_dwordx4 v[16:19], v98, s[10:11]
	global_load_dwordx4 v[20:23], v98, s[10:11] offset:256
	global_load_dwordx4 v[24:27], v99, s[10:11]
	global_load_dwordx4 v[28:31], v99, s[10:11] offset:256
	ds_read2_b32 v[230:231], v245 offset0:96 offset1:100
	ds_read2_b32 v[232:233], v245 offset0:104 offset1:108
	s_waitcnt vmcnt(8)
	v_mfma_scale_f32_16x16x128_f8f6f4 v[80:83], v[32:35], v[178:185], 0, v133, v133 op_sel_hi:[0,0,0] cbsz:4
	v_mfma_scale_f32_16x16x128_f8f6f4 v[80:83], v[36:39], v[186:193], v[80:83], v133, v133 op_sel_hi:[0,0,0] cbsz:4
	v_mfma_scale_f32_16x16x128_f8f6f4 v[84:87], v[40:43], v[178:185], 0, v133, v133 op_sel_hi:[0,0,0] cbsz:4
	v_mfma_scale_f32_16x16x128_f8f6f4 v[84:87], v[44:47], v[186:193], v[84:87], v133, v133 op_sel_hi:[0,0,0] cbsz:4
	v_mfma_scale_f32_16x16x128_f8f6f4 v[88:91], v[48:51], v[178:185], 0, v133, v133 op_sel_hi:[0,0,0] cbsz:4
	v_mfma_scale_f32_16x16x128_f8f6f4 v[88:91], v[52:55], v[186:193], v[88:91], v133, v133 op_sel_hi:[0,0,0] cbsz:4
	v_mfma_scale_f32_16x16x128_f8f6f4 v[92:95], v[56:59], v[178:185], 0, v133, v133 op_sel_hi:[0,0,0] cbsz:4
	v_mfma_scale_f32_16x16x128_f8f6f4 v[92:95], v[60:63], v[186:193], v[92:95], v133, v133 op_sel_hi:[0,0,0] cbsz:4
	s_nop 3
	v_mul_f32_e32 v234, v226, v64
	v_mul_f32_e32 v235, v226, v68
	v_mul_f32_e32 v236, v226, v72
	v_mul_f32_e32 v237, v226, v76
	v_fmac_f32_e32 v234, v227, v65
	v_fmac_f32_e32 v235, v227, v69
	v_fmac_f32_e32 v236, v227, v73
	v_fmac_f32_e32 v237, v227, v77
	v_fmac_f32_e32 v234, v228, v66
	v_fmac_f32_e32 v235, v228, v70
	v_fmac_f32_e32 v236, v228, v74
	v_fmac_f32_e32 v237, v228, v78
	v_fmac_f32_e32 v234, v229, v67
	v_fmac_f32_e32 v235, v229, v71
	v_fmac_f32_e32 v236, v229, v75
	v_fmac_f32_e32 v237, v229, v79
	v_add_f32_dpp v234, v234, v234 quad_perm:[1,0,3,2] row_mask:0xf bank_mask:0xf
	v_add_f32_dpp v235, v235, v235 quad_perm:[1,0,3,2] row_mask:0xf bank_mask:0xf
	v_add_f32_dpp v236, v236, v236 quad_perm:[1,0,3,2] row_mask:0xf bank_mask:0xf
	v_add_f32_dpp v237, v237, v237 quad_perm:[1,0,3,2] row_mask:0xf bank_mask:0xf
	v_add_f32_dpp v234, v234, v234 quad_perm:[2,3,0,1] row_mask:0xf bank_mask:0xf
	v_add_f32_dpp v235, v235, v235 quad_perm:[2,3,0,1] row_mask:0xf bank_mask:0xf
	v_add_f32_dpp v236, v236, v236 quad_perm:[2,3,0,1] row_mask:0xf bank_mask:0xf
	v_add_f32_dpp v237, v237, v237 quad_perm:[2,3,0,1] row_mask:0xf bank_mask:0xf
	v_add_f32_dpp v234, v234, v234 row_half_mirror row_mask:0xf bank_mask:0xf
	v_add_f32_dpp v235, v235, v235 row_half_mirror row_mask:0xf bank_mask:0xf
	v_add_f32_dpp v236, v236, v236 row_half_mirror row_mask:0xf bank_mask:0xf
	v_add_f32_dpp v237, v237, v237 row_half_mirror row_mask:0xf bank_mask:0xf
	s_mov_b32 exec_lo, 0x1000100
	s_mov_b32 exec_hi, 0x1000100
	ds_write_b32 v155, v234 offset:2432
	ds_write_b32 v155, v235 offset:2448
	ds_write_b32 v155, v236 offset:2464
	ds_write_b32 v155, v237 offset:2480
	s_mov_b64 exec, -1
	s_waitcnt lgkmcnt(0)
; __device__ __forceinline__ void peer_token(const Params& P, int t, int lane, int* sidx, float* sval, const int* sid, const float* sgate, const unsigned* szero) {
;     ...
;         for (int hh = 0; hh < 2; ++hh)
; #pragma unroll
;             for (int st = 0; st < 4; ++st) abuf[0][hh][st] = *(const uint4*)(Ub + (off2[hh] + 128 * st));
; #pragma unroll
;         for (int T = 0; T < 8; ++T) {
;             if (T + 1 < 8) {
; #pragma unroll
;                 for (int hh = 0; hh < 2; ++hh) off2[hh] = (unsigned)sid[16 * (T + 1) + 8 * hh + (lr & 7)] * 512u + lofs;
; #pragma unroll
;                 for (int hh = 0; hh < 2; ++hh)
; #pragma unroll
;                     for (int st = 0; st < 4; ++st) abuf[(T + 1) & 1][hh][st] = *(const uint4*)(Ub + (off2[hh] + 128 * st));
;             }
; #pragma unroll
;             for (int hh = 0; hh < 2; ++hh) {
;                 f32x4 au = (f32x4){0.f, 0.f, 0.f, 0.f};
; #pragma unroll
;                 for (int st = 0; st < 4; ++st) {
;                     const uint4 a4 = abuf[T & 1][hh][st];
;                     const v8i Av = {(int)a4.x, (int)a4.y, (int)a4.z, (int)a4.w, 0, 0, 0, 0};
;                     au = __builtin_amdgcn_mfma_scale_f32_16x16x128_f8f6f4(Av, Bv[st], au, 4, 0, 0, 0x7f7f7f7f, 0, 0x7f7f7f7f);
;                 }
;                 if (owner) *(f32x4*)(sact + 16 * T + 8 * hh) = au;
;             }
;         }
	v_lshl_add_u32 v230, v230, 9, v144
	v_lshl_add_u32 v231, v231, 9, v144
	v_lshl_add_u32 v232, v232, 9, v144
	v_lshl_add_u32 v233, v233, 9, v144
	global_load_dwordx4 v[32:35], v230, s[10:11]
	global_load_dwordx4 v[36:39], v230, s[10:11] offset:256
	global_load_dwordx4 v[40:43], v231, s[10:11]
	global_load_dwordx4 v[44:47], v231, s[10:11] offset:256
	global_load_dwordx4 v[48:51], v232, s[10:11]
	global_load_dwordx4 v[52:55], v232, s[10:11] offset:256
	global_load_dwordx4 v[56:59], v233, s[10:11]
	global_load_dwordx4 v[60:63], v233, s[10:11] offset:256
	ds_read2_b32 v[96:97], v238 offset0:112 offset1:116
	ds_read2_b32 v[98:99], v238 offset0:120 offset1:124
	s_waitcnt vmcnt(8)
	v_mfma_scale_f32_16x16x128_f8f6f4 v[64:67], v[0:3], v[194:201], 0, v133, v133 op_sel_hi:[0,0,0] cbsz:4
	v_mfma_scale_f32_16x16x128_f8f6f4 v[64:67], v[4:7], v[202:209], v[64:67], v133, v133 op_sel_hi:[0,0,0] cbsz:4
	v_mfma_scale_f32_16x16x128_f8f6f4 v[68:71], v[8:11], v[194:201], 0, v133, v133 op_sel_hi:[0,0,0] cbsz:4
	v_mfma_scale_f32_16x16x128_f8f6f4 v[68:71], v[12:15], v[202:209], v[68:71], v133, v133 op_sel_hi:[0,0,0] cbsz:4
	v_mfma_scale_f32_16x16x128_f8f6f4 v[72:75], v[16:19], v[194:201], 0, v133, v133 op_sel_hi:[0,0,0] cbsz:4
	v_mfma_scale_f32_16x16x128_f8f6f4 v[72:75], v[20:23], v[202:209], v[72:75], v133, v133 op_sel_hi:[0,0,0] cbsz:4
	v_mfma_scale_f32_16x16x128_f8f6f4 v[76:79], v[24:27], v[194:201], 0, v133, v133 op_sel_hi:[0,0,0] cbsz:4
	v_mfma_scale_f32_16x16x128_f8f6f4 v[76:79], v[28:31], v[202:209], v[76:79], v133, v133 op_sel_hi:[0,0,0] cbsz:4
	s_nop 3
	v_mul_f32_e32 v234, v226, v80
	v_mul_f32_e32 v235, v226, v84
	v_mul_f32_e32 v236, v226, v88
	v_mul_f32_e32 v237, v226, v92
	v_fmac_f32_e32 v234, v227, v81
	v_fmac_f32_e32 v235, v227, v85
	v_fmac_f32_e32 v236, v227, v89
	v_fmac_f32_e32 v237, v227, v93
	v_fmac_f32_e32 v234, v228, v82
	v_fmac_f32_e32 v235, v228, v86
	v_fmac_f32_e32 v236, v228, v90
	v_fmac_f32_e32 v237, v228, v94
	v_fmac_f32_e32 v234, v229, v83
	v_fmac_f32_e32 v235, v229, v87
	v_fmac_f32_e32 v236, v229, v91
	v_fmac_f32_e32 v237, v229, v95
	v_add_f32_dpp v234, v234, v234 quad_perm:[1,0,3,2] row_mask:0xf bank_mask:0xf
	v_add_f32_dpp v235, v235, v235 quad_perm:[1,0,3,2] row_mask:0xf bank_mask:0xf
	v_add_f32_dpp v236, v236, v236 quad_perm:[1,0,3,2] row_mask:0xf bank_mask:0xf
	v_add_f32_dpp v237, v237, v237 quad_perm:[1,0,3,2] row_mask:0xf bank_mask:0xf
	v_add_f32_dpp v234, v234, v234 quad_perm:[2,3,0,1] row_mask:0xf bank_mask:0xf
	v_add_f32_dpp v235, v235, v235 quad_perm:[2,3,0,1] row_mask:0xf bank_mask:0xf
	v_add_f32_dpp v236, v236, v236 quad_perm:[2,3,0,1] row_mask:0xf bank_mask:0xf
	v_add_f32_dpp v237, v237, v237 quad_perm:[2,3,0,1] row_mask:0xf bank_mask:0xf
	v_add_f32_dpp v234, v234, v234 row_half_mirror row_mask:0xf bank_mask:0xf
	v_add_f32_dpp v235, v235, v235 row_half_mirror row_mask:0xf bank_mask:0xf
	v_add_f32_dpp v236, v236, v236 row_half_mirror row_mask:0xf bank_mask:0xf
	v_add_f32_dpp v237, v237, v237 row_half_mirror row_mask:0xf bank_mask:0xf
	s_mov_b32 exec_lo, 0x1000100
	s_mov_b32 exec_hi, 0x1000100
	ds_write_b32 v155, v234 offset:2944
	ds_write_b32 v155, v235 offset:2960
	ds_write_b32 v155, v236 offset:2976
	ds_write_b32 v155, v237 offset:2992
	s_mov_b64 exec, -1
	s_waitcnt lgkmcnt(0)
	v_lshl_add_u32 v96, v96, 9, v144
	v_lshl_add_u32 v97, v97, 9, v144
	v_lshl_add_u32 v98, v98, 9, v144
	v_lshl_add_u32 v99, v99, 9, v144
	global_load_dwordx4 v[0:3], v96, s[10:11]
	global_load_dwordx4 v[4:7], v96, s[10:11] offset:256
	global_load_dwordx4 v[8:11], v97, s[10:11]
	global_load_dwordx4 v[12:15], v97, s[10:11] offset:256
	global_load_dwordx4 v[16:19], v98, s[10:11]
	global_load_dwordx4 v[20:23], v98, s[10:11] offset:256
	global_load_dwordx4 v[24:27], v99, s[10:11]
	global_load_dwordx4 v[28:31], v99, s[10:11] offset:256
	ds_read2_b32 v[230:231], v239 offset0:112 offset1:116
	ds_read2_b32 v[232:233], v239 offset0:120 offset1:124
	s_waitcnt vmcnt(8)
	v_mfma_scale_f32_16x16x128_f8f6f4 v[80:83], v[32:35], v[210:217], 0, v133, v133 op_sel_hi:[0,0,0] cbsz:4
	v_mfma_scale_f32_16x16x128_f8f6f4 v[80:83], v[36:39], v[218:225], v[80:83], v133, v133 op_sel_hi:[0,0,0] cbsz:4
	v_mfma_scale_f32_16x16x128_f8f6f4 v[84:87], v[40:43], v[210:217], 0, v133, v133 op_sel_hi:[0,0,0] cbsz:4
	v_mfma_scale_f32_16x16x128_f8f6f4 v[84:87], v[44:47], v[218:225], v[84:87], v133, v133 op_sel_hi:[0,0,0] cbsz:4
	v_mfma_scale_f32_16x16x128_f8f6f4 v[88:91], v[48:51], v[210:217], 0, v133, v133 op_sel_hi:[0,0,0] cbsz:4
	v_mfma_scale_f32_16x16x128_f8f6f4 v[88:91], v[52:55], v[218:225], v[88:91], v133, v133 op_sel_hi:[0,0,0] cbsz:4
	v_mfma_scale_f32_16x16x128_f8f6f4 v[92:95], v[56:59], v[210:217], 0, v133, v133 op_sel_hi:[0,0,0] cbsz:4
	v_mfma_scale_f32_16x16x128_f8f6f4 v[92:95], v[60:63], v[218:225], v[92:95], v133, v133 op_sel_hi:[0,0,0] cbsz:4
	s_nop 3
	v_mul_f32_e32 v234, v226, v64
	v_mul_f32_e32 v235, v226, v68
	v_mul_f32_e32 v236, v226, v72
	v_mul_f32_e32 v237, v226, v76
	v_fmac_f32_e32 v234, v227, v65
	v_fmac_f32_e32 v235, v227, v69
	v_fmac_f32_e32 v236, v227, v73
	v_fmac_f32_e32 v237, v227, v77
	v_fmac_f32_e32 v234, v228, v66
	v_fmac_f32_e32 v235, v228, v70
	v_fmac_f32_e32 v236, v228, v74
	v_fmac_f32_e32 v237, v228, v78
	v_fmac_f32_e32 v234, v229, v67
	v_fmac_f32_e32 v235, v229, v71
	v_fmac_f32_e32 v236, v229, v75
	v_fmac_f32_e32 v237, v229, v79
	v_add_f32_dpp v234, v234, v234 quad_perm:[1,0,3,2] row_mask:0xf bank_mask:0xf
	v_add_f32_dpp v235, v235, v235 quad_perm:[1,0,3,2] row_mask:0xf bank_mask:0xf
	v_add_f32_dpp v236, v236, v236 quad_perm:[1,0,3,2] row_mask:0xf bank_mask:0xf
	v_add_f32_dpp v237, v237, v237 quad_perm:[1,0,3,2] row_mask:0xf bank_mask:0xf
	v_add_f32_dpp v234, v234, v234 quad_perm:[2,3,0,1] row_mask:0xf bank_mask:0xf
	v_add_f32_dpp v235, v235, v235 quad_perm:[2,3,0,1] row_mask:0xf bank_mask:0xf
	v_add_f32_dpp v236, v236, v236 quad_perm:[2,3,0,1] row_mask:0xf bank_mask:0xf
	v_add_f32_dpp v237, v237, v237 quad_perm:[2,3,0,1] row_mask:0xf bank_mask:0xf
	v_add_f32_dpp v234, v234, v234 row_half_mirror row_mask:0xf bank_mask:0xf
	v_add_f32_dpp v235, v235, v235 row_half_mirror row_mask:0xf bank_mask:0xf
	v_add_f32_dpp v236, v236, v236 row_half_mirror row_mask:0xf bank_mask:0xf
	v_add_f32_dpp v237, v237, v237 row_half_mirror row_mask:0xf bank_mask:0xf
	s_mov_b32 exec_lo, 0x1000100
	s_mov_b32 exec_hi, 0x1000100
	ds_write_b32 v155, v234 offset:3456
	ds_write_b32 v155, v235 offset:3472
	ds_write_b32 v155, v236 offset:3488
	ds_write_b32 v155, v237 offset:3504
	s_mov_b64 exec, -1
	s_waitcnt lgkmcnt(0)
; __device__ __forceinline__ void peer_token(const Params& P, int t, int lane, int* sidx, float* sval, const int* sid, const float* sgate, const unsigned* szero) {
;     ...
;         for (int hh = 0; hh < 2; ++hh)
; #pragma unroll
;             for (int st = 0; st < 4; ++st) abuf[0][hh][st] = *(const uint4*)(Ub + (off2[hh] + 128 * st));
; #pragma unroll
;         for (int T = 0; T < 8; ++T) {
;             if (T + 1 < 8) {
; #pragma unroll
;                 for (int hh = 0; hh < 2; ++hh) off2[hh] = (unsigned)sid[16 * (T + 1) + 8 * hh + (lr & 7)] * 512u + lofs;
; #pragma unroll
;                 for (int hh = 0; hh < 2; ++hh)
; #pragma unroll
;                     for (int st = 0; st < 4; ++st) abuf[(T + 1) & 1][hh][st] = *(const uint4*)(Ub + (off2[hh] + 128 * st));
;             }
; #pragma unroll
;             for (int hh = 0; hh < 2; ++hh) {
;                 f32x4 au = (f32x4){0.f, 0.f, 0.f, 0.f};
; #pragma unroll
;                 for (int st = 0; st < 4; ++st) {
;                     const uint4 a4 = abuf[T & 1][hh][st];
;                     const v8i Av = {(int)a4.x, (int)a4.y, (int)a4.z, (int)a4.w, 0, 0, 0, 0};
;                     au = __builtin_amdgcn_mfma_scale_f32_16x16x128_f8f6f4(Av, Bv[st], au, 4, 0, 0, 0x7f7f7f7f, 0, 0x7f7f7f7f);
;                 }
;                 if (owner) *(f32x4*)(sact + 16 * T + 8 * hh) = au;
;             }
;         }
	v_lshl_add_u32 v230, v230, 9, v144
	v_lshl_add_u32 v231, v231, 9, v144
	v_lshl_add_u32 v232, v232, 9, v144
	v_lshl_add_u32 v233, v233, 9, v144
	global_load_dwordx4 v[32:35], v230, s[10:11]
	global_load_dwordx4 v[36:39], v230, s[10:11] offset:256
	global_load_dwordx4 v[40:43], v231, s[10:11]
	global_load_dwordx4 v[44:47], v231, s[10:11] offset:256
	global_load_dwordx4 v[48:51], v232, s[10:11]
	global_load_dwordx4 v[52:55], v232, s[10:11] offset:256
	global_load_dwordx4 v[56:59], v233, s[10:11]
	global_load_dwordx4 v[60:63], v233, s[10:11] offset:256
	ds_read2_b32 v[96:97], v240 offset0:112 offset1:116
	ds_read2_b32 v[98:99], v240 offset0:120 offset1:124
	s_waitcnt vmcnt(8)
	v_mfma_scale_f32_16x16x128_f8f6f4 v[64:67], v[0:3], v[162:169], 0, v133, v133 op_sel_hi:[0,0,0] cbsz:4
	v_mfma_scale_f32_16x16x128_f8f6f4 v[64:67], v[4:7], v[170:177], v[64:67], v133, v133 op_sel_hi:[0,0,0] cbsz:4
	v_mfma_scale_f32_16x16x128_f8f6f4 v[68:71], v[8:11], v[162:169], 0, v133, v133 op_sel_hi:[0,0,0] cbsz:4
	v_mfma_scale_f32_16x16x128_f8f6f4 v[68:71], v[12:15], v[170:177], v[68:71], v133, v133 op_sel_hi:[0,0,0] cbsz:4
	v_mfma_scale_f32_16x16x128_f8f6f4 v[72:75], v[16:19], v[162:169], 0, v133, v133 op_sel_hi:[0,0,0] cbsz:4
	v_mfma_scale_f32_16x16x128_f8f6f4 v[72:75], v[20:23], v[170:177], v[72:75], v133, v133 op_sel_hi:[0,0,0] cbsz:4
	v_mfma_scale_f32_16x16x128_f8f6f4 v[76:79], v[24:27], v[162:169], 0, v133, v133 op_sel_hi:[0,0,0] cbsz:4
	v_mfma_scale_f32_16x16x128_f8f6f4 v[76:79], v[28:31], v[170:177], v[76:79], v133, v133 op_sel_hi:[0,0,0] cbsz:4
	s_nop 3
	v_mul_f32_e32 v234, v226, v80
	v_mul_f32_e32 v235, v226, v84
	v_mul_f32_e32 v236, v226, v88
	v_mul_f32_e32 v237, v226, v92
	v_fmac_f32_e32 v234, v227, v81
	v_fmac_f32_e32 v235, v227, v85
	v_fmac_f32_e32 v236, v227, v89
	v_fmac_f32_e32 v237, v227, v93
	v_fmac_f32_e32 v234, v228, v82
	v_fmac_f32_e32 v235, v228, v86
	v_fmac_f32_e32 v236, v228, v90
	v_fmac_f32_e32 v237, v228, v94
	v_fmac_f32_e32 v234, v229, v83
	v_fmac_f32_e32 v235, v229, v87
	v_fmac_f32_e32 v236, v229, v91
	v_fmac_f32_e32 v237, v229, v95
	v_add_f32_dpp v234, v234, v234 quad_perm:[1,0,3,2] row_mask:0xf bank_mask:0xf
	v_add_f32_dpp v235, v235, v235 quad_perm:[1,0,3,2] row_mask:0xf bank_mask:0xf
	v_add_f32_dpp v236, v236, v236 quad_perm:[1,0,3,2] row_mask:0xf bank_mask:0xf
	v_add_f32_dpp v237, v237, v237 quad_perm:[1,0,3,2] row_mask:0xf bank_mask:0xf
	v_add_f32_dpp v234, v234, v234 quad_perm:[2,3,0,1] row_mask:0xf bank_mask:0xf
	v_add_f32_dpp v235, v235, v235 quad_perm:[2,3,0,1] row_mask:0xf bank_mask:0xf
	v_add_f32_dpp v236, v236, v236 quad_perm:[2,3,0,1] row_mask:0xf bank_mask:0xf
	v_add_f32_dpp v237, v237, v237 quad_perm:[2,3,0,1] row_mask:0xf bank_mask:0xf
	v_add_f32_dpp v234, v234, v234 row_half_mirror row_mask:0xf bank_mask:0xf
	v_add_f32_dpp v235, v235, v235 row_half_mirror row_mask:0xf bank_mask:0xf
	v_add_f32_dpp v236, v236, v236 row_half_mirror row_mask:0xf bank_mask:0xf
	v_add_f32_dpp v237, v237, v237 row_half_mirror row_mask:0xf bank_mask:0xf
	s_mov_b32 exec_lo, 0x1000100
	s_mov_b32 exec_hi, 0x1000100
	ds_write_b32 v155, v234 offset:3968
	ds_write_b32 v155, v235 offset:3984
	ds_write_b32 v155, v236 offset:4000
	ds_write_b32 v155, v237 offset:4016
	s_mov_b64 exec, -1
	s_waitcnt lgkmcnt(0)
	v_lshl_add_u32 v96, v96, 9, v144
	v_lshl_add_u32 v97, v97, 9, v144
	v_lshl_add_u32 v98, v98, 9, v144
	v_lshl_add_u32 v99, v99, 9, v144
	global_load_dwordx4 v[0:3], v96, s[10:11]
	global_load_dwordx4 v[4:7], v96, s[10:11] offset:256
	global_load_dwordx4 v[8:11], v97, s[10:11]
	global_load_dwordx4 v[12:15], v97, s[10:11] offset:256
	global_load_dwordx4 v[16:19], v98, s[10:11]
	global_load_dwordx4 v[20:23], v98, s[10:11] offset:256
	global_load_dwordx4 v[24:27], v99, s[10:11]
	global_load_dwordx4 v[28:31], v99, s[10:11] offset:256
	ds_read2_b32 v[230:231], v241 offset0:112 offset1:116
	ds_read2_b32 v[232:233], v241 offset0:120 offset1:124
	s_waitcnt vmcnt(8)
	v_mfma_scale_f32_16x16x128_f8f6f4 v[80:83], v[32:35], v[178:185], 0, v133, v133 op_sel_hi:[0,0,0] cbsz:4
	v_mfma_scale_f32_16x16x128_f8f6f4 v[80:83], v[36:39], v[186:193], v[80:83], v133, v133 op_sel_hi:[0,0,0] cbsz:4
	v_mfma_scale_f32_16x16x128_f8f6f4 v[84:87], v[40:43], v[178:185], 0, v133, v133 op_sel_hi:[0,0,0] cbsz:4
	v_mfma_scale_f32_16x16x128_f8f6f4 v[84:87], v[44:47], v[186:193], v[84:87], v133, v133 op_sel_hi:[0,0,0] cbsz:4
	v_mfma_scale_f32_16x16x128_f8f6f4 v[88:91], v[48:51], v[178:185], 0, v133, v133 op_sel_hi:[0,0,0] cbsz:4
	v_mfma_scale_f32_16x16x128_f8f6f4 v[88:91], v[52:55], v[186:193], v[88:91], v133, v133 op_sel_hi:[0,0,0] cbsz:4
	v_mfma_scale_f32_16x16x128_f8f6f4 v[92:95], v[56:59], v[178:185], 0, v133, v133 op_sel_hi:[0,0,0] cbsz:4
	v_mfma_scale_f32_16x16x128_f8f6f4 v[92:95], v[60:63], v[186:193], v[92:95], v133, v133 op_sel_hi:[0,0,0] cbsz:4
	s_nop 3
	v_mul_f32_e32 v234, v158, v64
	v_mul_f32_e32 v235, v158, v68
	v_mul_f32_e32 v236, v158, v72
	v_mul_f32_e32 v237, v158, v76
	v_fmac_f32_e32 v234, v159, v65
	v_fmac_f32_e32 v235, v159, v69
	v_fmac_f32_e32 v236, v159, v73
	v_fmac_f32_e32 v237, v159, v77
	v_fmac_f32_e32 v234, v160, v66
	v_fmac_f32_e32 v235, v160, v70
	v_fmac_f32_e32 v236, v160, v74
	v_fmac_f32_e32 v237, v160, v78
	v_fmac_f32_e32 v234, v161, v67
	v_fmac_f32_e32 v235, v161, v71
	v_fmac_f32_e32 v236, v161, v75
	v_fmac_f32_e32 v237, v161, v79
	v_add_f32_dpp v234, v234, v234 quad_perm:[1,0,3,2] row_mask:0xf bank_mask:0xf
	v_add_f32_dpp v235, v235, v235 quad_perm:[1,0,3,2] row_mask:0xf bank_mask:0xf
	v_add_f32_dpp v236, v236, v236 quad_perm:[1,0,3,2] row_mask:0xf bank_mask:0xf
	v_add_f32_dpp v237, v237, v237 quad_perm:[1,0,3,2] row_mask:0xf bank_mask:0xf
	v_add_f32_dpp v234, v234, v234 quad_perm:[2,3,0,1] row_mask:0xf bank_mask:0xf
	v_add_f32_dpp v235, v235, v235 quad_perm:[2,3,0,1] row_mask:0xf bank_mask:0xf
	v_add_f32_dpp v236, v236, v236 quad_perm:[2,3,0,1] row_mask:0xf bank_mask:0xf
	v_add_f32_dpp v237, v237, v237 quad_perm:[2,3,0,1] row_mask:0xf bank_mask:0xf
	v_add_f32_dpp v234, v234, v234 row_half_mirror row_mask:0xf bank_mask:0xf
	v_add_f32_dpp v235, v235, v235 row_half_mirror row_mask:0xf bank_mask:0xf
	v_add_f32_dpp v236, v236, v236 row_half_mirror row_mask:0xf bank_mask:0xf
	v_add_f32_dpp v237, v237, v237 row_half_mirror row_mask:0xf bank_mask:0xf
	s_mov_b32 exec_lo, 0x10001
	s_mov_b32 exec_hi, 0x10001
	ds_write_b32 v155, v234 offset:448
	ds_write_b32 v155, v235 offset:464
	ds_write_b32 v155, v236 offset:480
	ds_write_b32 v155, v237 offset:496
	s_mov_b64 exec, -1
	s_waitcnt lgkmcnt(0)
; __device__ __forceinline__ void peer_token(const Params& P, int t, int lane, int* sidx, float* sval, const int* sid, const float* sgate, const unsigned* szero) {
;     ...
;         for (int hh = 0; hh < 2; ++hh)
; #pragma unroll
;             for (int st = 0; st < 4; ++st) abuf[0][hh][st] = *(const uint4*)(Ub + (off2[hh] + 128 * st));
; #pragma unroll
;         for (int T = 0; T < 8; ++T) {
;             if (T + 1 < 8) {
; #pragma unroll
;                 for (int hh = 0; hh < 2; ++hh) off2[hh] = (unsigned)sid[16 * (T + 1) + 8 * hh + (lr & 7)] * 512u + lofs;
; #pragma unroll
;                 for (int hh = 0; hh < 2; ++hh)
; #pragma unroll
;                     for (int st = 0; st < 4; ++st) abuf[(T + 1) & 1][hh][st] = *(const uint4*)(Ub + (off2[hh] + 128 * st));
;             }
; #pragma unroll
;             for (int hh = 0; hh < 2; ++hh) {
;                 f32x4 au = (f32x4){0.f, 0.f, 0.f, 0.f};
; #pragma unroll
;                 for (int st = 0; st < 4; ++st) {
;                     const uint4 a4 = abuf[T & 1][hh][st];
;                     const v8i Av = {(int)a4.x, (int)a4.y, (int)a4.z, (int)a4.w, 0, 0, 0, 0};
;                     au = __builtin_amdgcn_mfma_scale_f32_16x16x128_f8f6f4(Av, Bv[st], au, 4, 0, 0, 0x7f7f7f7f, 0, 0x7f7f7f7f);
;                 }
;                 if (owner) *(f32x4*)(sact + 16 * T + 8 * hh) = au;
;             }
;         }
	v_lshl_add_u32 v230, v230, 9, v144
	v_lshl_add_u32 v231, v231, 9, v144
	v_lshl_add_u32 v232, v232, 9, v144
	v_lshl_add_u32 v233, v233, 9, v144
	global_load_dwordx4 v[32:35], v230, s[10:11]
	global_load_dwordx4 v[36:39], v230, s[10:11] offset:256
	global_load_dwordx4 v[40:43], v231, s[10:11]
	global_load_dwordx4 v[44:47], v231, s[10:11] offset:256
	global_load_dwordx4 v[48:51], v232, s[10:11]
	global_load_dwordx4 v[52:55], v232, s[10:11] offset:256
	global_load_dwordx4 v[56:59], v233, s[10:11]
	global_load_dwordx4 v[60:63], v233, s[10:11] offset:256
	ds_read2_b32 v[96:97], v242 offset0:112 offset1:116
	ds_read2_b32 v[98:99], v242 offset0:120 offset1:124
	s_waitcnt vmcnt(8)
	v_mfma_scale_f32_16x16x128_f8f6f4 v[64:67], v[0:3], v[194:201], 0, v133, v133 op_sel_hi:[0,0,0] cbsz:4
	v_mfma_scale_f32_16x16x128_f8f6f4 v[64:67], v[4:7], v[202:209], v[64:67], v133, v133 op_sel_hi:[0,0,0] cbsz:4
	v_mfma_scale_f32_16x16x128_f8f6f4 v[68:71], v[8:11], v[194:201], 0, v133, v133 op_sel_hi:[0,0,0] cbsz:4
	v_mfma_scale_f32_16x16x128_f8f6f4 v[68:71], v[12:15], v[202:209], v[68:71], v133, v133 op_sel_hi:[0,0,0] cbsz:4
	v_mfma_scale_f32_16x16x128_f8f6f4 v[72:75], v[16:19], v[194:201], 0, v133, v133 op_sel_hi:[0,0,0] cbsz:4
	v_mfma_scale_f32_16x16x128_f8f6f4 v[72:75], v[20:23], v[202:209], v[72:75], v133, v133 op_sel_hi:[0,0,0] cbsz:4
	v_mfma_scale_f32_16x16x128_f8f6f4 v[76:79], v[24:27], v[194:201], 0, v133, v133 op_sel_hi:[0,0,0] cbsz:4
	v_mfma_scale_f32_16x16x128_f8f6f4 v[76:79], v[28:31], v[202:209], v[76:79], v133, v133 op_sel_hi:[0,0,0] cbsz:4
	s_nop 3
	v_mul_f32_e32 v234, v158, v80
	v_mul_f32_e32 v235, v158, v84
	v_mul_f32_e32 v236, v158, v88
	v_mul_f32_e32 v237, v158, v92
	v_fmac_f32_e32 v234, v159, v81
	v_fmac_f32_e32 v235, v159, v85
	v_fmac_f32_e32 v236, v159, v89
	v_fmac_f32_e32 v237, v159, v93
	v_fmac_f32_e32 v234, v160, v82
	v_fmac_f32_e32 v235, v160, v86
	v_fmac_f32_e32 v236, v160, v90
	v_fmac_f32_e32 v237, v160, v94
	v_fmac_f32_e32 v234, v161, v83
	v_fmac_f32_e32 v235, v161, v87
	v_fmac_f32_e32 v236, v161, v91
	v_fmac_f32_e32 v237, v161, v95
	v_add_f32_dpp v234, v234, v234 quad_perm:[1,0,3,2] row_mask:0xf bank_mask:0xf
	v_add_f32_dpp v235, v235, v235 quad_perm:[1,0,3,2] row_mask:0xf bank_mask:0xf
	v_add_f32_dpp v236, v236, v236 quad_perm:[1,0,3,2] row_mask:0xf bank_mask:0xf
	v_add_f32_dpp v237, v237, v237 quad_perm:[1,0,3,2] row_mask:0xf bank_mask:0xf
	v_add_f32_dpp v234, v234, v234 quad_perm:[2,3,0,1] row_mask:0xf bank_mask:0xf
	v_add_f32_dpp v235, v235, v235 quad_perm:[2,3,0,1] row_mask:0xf bank_mask:0xf
	v_add_f32_dpp v236, v236, v236 quad_perm:[2,3,0,1] row_mask:0xf bank_mask:0xf
	v_add_f32_dpp v237, v237, v237 quad_perm:[2,3,0,1] row_mask:0xf bank_mask:0xf
	v_add_f32_dpp v234, v234, v234 row_half_mirror row_mask:0xf bank_mask:0xf
	v_add_f32_dpp v235, v235, v235 row_half_mirror row_mask:0xf bank_mask:0xf
	v_add_f32_dpp v236, v236, v236 row_half_mirror row_mask:0xf bank_mask:0xf
	v_add_f32_dpp v237, v237, v237 row_half_mirror row_mask:0xf bank_mask:0xf
	s_mov_b32 exec_lo, 0x10001
	s_mov_b32 exec_hi, 0x10001
	ds_write_b32 v155, v234 offset:960
	ds_write_b32 v155, v235 offset:976
	ds_write_b32 v155, v236 offset:992
	ds_write_b32 v155, v237 offset:1008
	s_mov_b64 exec, -1
	s_waitcnt lgkmcnt(0)
	v_lshl_add_u32 v96, v96, 9, v144
	v_lshl_add_u32 v97, v97, 9, v144
	v_lshl_add_u32 v98, v98, 9, v144
	v_lshl_add_u32 v99, v99, 9, v144
	global_load_dwordx4 v[0:3], v96, s[10:11]
	global_load_dwordx4 v[4:7], v96, s[10:11] offset:256
	global_load_dwordx4 v[8:11], v97, s[10:11]
	global_load_dwordx4 v[12:15], v97, s[10:11] offset:256
	global_load_dwordx4 v[16:19], v98, s[10:11]
	global_load_dwordx4 v[20:23], v98, s[10:11] offset:256
	global_load_dwordx4 v[24:27], v99, s[10:11]
	global_load_dwordx4 v[28:31], v99, s[10:11] offset:256
	ds_read2_b32 v[230:231], v243 offset0:112 offset1:116
	ds_read2_b32 v[232:233], v243 offset0:120 offset1:124
	s_waitcnt vmcnt(8)
	v_mfma_scale_f32_16x16x128_f8f6f4 v[80:83], v[32:35], v[210:217], 0, v133, v133 op_sel_hi:[0,0,0] cbsz:4
	v_mfma_scale_f32_16x16x128_f8f6f4 v[80:83], v[36:39], v[218:225], v[80:83], v133, v133 op_sel_hi:[0,0,0] cbsz:4
	v_mfma_scale_f32_16x16x128_f8f6f4 v[84:87], v[40:43], v[210:217], 0, v133, v133 op_sel_hi:[0,0,0] cbsz:4
	v_mfma_scale_f32_16x16x128_f8f6f4 v[84:87], v[44:47], v[218:225], v[84:87], v133, v133 op_sel_hi:[0,0,0] cbsz:4
	v_mfma_scale_f32_16x16x128_f8f6f4 v[88:91], v[48:51], v[210:217], 0, v133, v133 op_sel_hi:[0,0,0] cbsz:4
	v_mfma_scale_f32_16x16x128_f8f6f4 v[88:91], v[52:55], v[218:225], v[88:91], v133, v133 op_sel_hi:[0,0,0] cbsz:4
	v_mfma_scale_f32_16x16x128_f8f6f4 v[92:95], v[56:59], v[210:217], 0, v133, v133 op_sel_hi:[0,0,0] cbsz:4
	v_mfma_scale_f32_16x16x128_f8f6f4 v[92:95], v[60:63], v[218:225], v[92:95], v133, v133 op_sel_hi:[0,0,0] cbsz:4
	s_nop 3
	v_mul_f32_e32 v234, v158, v64
	v_mul_f32_e32 v235, v158, v68
	v_mul_f32_e32 v236, v158, v72
	v_mul_f32_e32 v237, v158, v76
	v_fmac_f32_e32 v234, v159, v65
	v_fmac_f32_e32 v235, v159, v69
	v_fmac_f32_e32 v236, v159, v73
	v_fmac_f32_e32 v237, v159, v77
	v_fmac_f32_e32 v234, v160, v66
	v_fmac_f32_e32 v235, v160, v70
	v_fmac_f32_e32 v236, v160, v74
	v_fmac_f32_e32 v237, v160, v78
	v_fmac_f32_e32 v234, v161, v67
	v_fmac_f32_e32 v235, v161, v71
	v_fmac_f32_e32 v236, v161, v75
	v_fmac_f32_e32 v237, v161, v79
	v_add_f32_dpp v234, v234, v234 quad_perm:[1,0,3,2] row_mask:0xf bank_mask:0xf
	v_add_f32_dpp v235, v235, v235 quad_perm:[1,0,3,2] row_mask:0xf bank_mask:0xf
	v_add_f32_dpp v236, v236, v236 quad_perm:[1,0,3,2] row_mask:0xf bank_mask:0xf
	v_add_f32_dpp v237, v237, v237 quad_perm:[1,0,3,2] row_mask:0xf bank_mask:0xf
	v_add_f32_dpp v234, v234, v234 quad_perm:[2,3,0,1] row_mask:0xf bank_mask:0xf
	v_add_f32_dpp v235, v235, v235 quad_perm:[2,3,0,1] row_mask:0xf bank_mask:0xf
	v_add_f32_dpp v236, v236, v236 quad_perm:[2,3,0,1] row_mask:0xf bank_mask:0xf
	v_add_f32_dpp v237, v237, v237 quad_perm:[2,3,0,1] row_mask:0xf bank_mask:0xf
	v_add_f32_dpp v234, v234, v234 row_half_mirror row_mask:0xf bank_mask:0xf
	v_add_f32_dpp v235, v235, v235 row_half_mirror row_mask:0xf bank_mask:0xf
	v_add_f32_dpp v236, v236, v236 row_half_mirror row_mask:0xf bank_mask:0xf
	v_add_f32_dpp v237, v237, v237 row_half_mirror row_mask:0xf bank_mask:0xf
	s_mov_b32 exec_lo, 0x10001
	s_mov_b32 exec_hi, 0x10001
	ds_write_b32 v155, v234 offset:1472
	ds_write_b32 v155, v235 offset:1488
	ds_write_b32 v155, v236 offset:1504
	ds_write_b32 v155, v237 offset:1520
	s_mov_b64 exec, -1
	s_waitcnt lgkmcnt(0)
; __device__ __forceinline__ void peer_token(const Params& P, int t, int lane, int* sidx, float* sval, const int* sid, const float* sgate, const unsigned* szero) {
;     ...
;         for (int hh = 0; hh < 2; ++hh)
; #pragma unroll
;             for (int st = 0; st < 4; ++st) abuf[0][hh][st] = *(const uint4*)(Ub + (off2[hh] + 128 * st));
; #pragma unroll
;         for (int T = 0; T < 8; ++T) {
;             if (T + 1 < 8) {
; #pragma unroll
;                 for (int hh = 0; hh < 2; ++hh) off2[hh] = (unsigned)sid[16 * (T + 1) + 8 * hh + (lr & 7)] * 512u + lofs;
; #pragma unroll
;                 for (int hh = 0; hh < 2; ++hh)
; #pragma unroll
;                     for (int st = 0; st < 4; ++st) abuf[(T + 1) & 1][hh][st] = *(const uint4*)(Ub + (off2[hh] + 128 * st));
;             }
; #pragma unroll
;             for (int hh = 0; hh < 2; ++hh) {
;                 f32x4 au = (f32x4){0.f, 0.f, 0.f, 0.f};
; #pragma unroll
;                 for (int st = 0; st < 4; ++st) {
;                     const uint4 a4 = abuf[T & 1][hh][st];
;                     const v8i Av = {(int)a4.x, (int)a4.y, (int)a4.z, (int)a4.w, 0, 0, 0, 0};
;                     au = __builtin_amdgcn_mfma_scale_f32_16x16x128_f8f6f4(Av, Bv[st], au, 4, 0, 0, 0x7f7f7f7f, 0, 0x7f7f7f7f);
;                 }
;                 if (owner) *(f32x4*)(sact + 16 * T + 8 * hh) = au;
;             }
;         }
	v_lshl_add_u32 v230, v230, 9, v144
	v_lshl_add_u32 v231, v231, 9, v144
	v_lshl_add_u32 v232, v232, 9, v144
	v_lshl_add_u32 v233, v233, 9, v144
	global_load_dwordx4 v[32:35], v230, s[10:11]
	global_load_dwordx4 v[36:39], v230, s[10:11] offset:256
	global_load_dwordx4 v[40:43], v231, s[10:11]
	global_load_dwordx4 v[44:47], v231, s[10:11] offset:256
	global_load_dwordx4 v[48:51], v232, s[10:11]
	global_load_dwordx4 v[52:55], v232, s[10:11] offset:256
	global_load_dwordx4 v[56:59], v233, s[10:11]
	global_load_dwordx4 v[60:63], v233, s[10:11] offset:256
	ds_read2_b32 v[96:97], v244 offset0:112 offset1:116
	ds_read2_b32 v[98:99], v244 offset0:120 offset1:124
	s_waitcnt vmcnt(8)
	v_mfma_scale_f32_16x16x128_f8f6f4 v[64:67], v[0:3], v[162:169], 0, v133, v133 op_sel_hi:[0,0,0] cbsz:4
	v_mfma_scale_f32_16x16x128_f8f6f4 v[64:67], v[4:7], v[170:177], v[64:67], v133, v133 op_sel_hi:[0,0,0] cbsz:4
	v_mfma_scale_f32_16x16x128_f8f6f4 v[68:71], v[8:11], v[162:169], 0, v133, v133 op_sel_hi:[0,0,0] cbsz:4
	v_mfma_scale_f32_16x16x128_f8f6f4 v[68:71], v[12:15], v[170:177], v[68:71], v133, v133 op_sel_hi:[0,0,0] cbsz:4
	v_mfma_scale_f32_16x16x128_f8f6f4 v[72:75], v[16:19], v[162:169], 0, v133, v133 op_sel_hi:[0,0,0] cbsz:4
	v_mfma_scale_f32_16x16x128_f8f6f4 v[72:75], v[20:23], v[170:177], v[72:75], v133, v133 op_sel_hi:[0,0,0] cbsz:4
	v_mfma_scale_f32_16x16x128_f8f6f4 v[76:79], v[24:27], v[162:169], 0, v133, v133 op_sel_hi:[0,0,0] cbsz:4
	v_mfma_scale_f32_16x16x128_f8f6f4 v[76:79], v[28:31], v[170:177], v[76:79], v133, v133 op_sel_hi:[0,0,0] cbsz:4
	s_nop 3
	v_mul_f32_e32 v234, v158, v80
	v_mul_f32_e32 v235, v158, v84
	v_mul_f32_e32 v236, v158, v88
	v_mul_f32_e32 v237, v158, v92
	v_fmac_f32_e32 v234, v159, v81
	v_fmac_f32_e32 v235, v159, v85
	v_fmac_f32_e32 v236, v159, v89
	v_fmac_f32_e32 v237, v159, v93
	v_fmac_f32_e32 v234, v160, v82
	v_fmac_f32_e32 v235, v160, v86
	v_fmac_f32_e32 v236, v160, v90
	v_fmac_f32_e32 v237, v160, v94
	v_fmac_f32_e32 v234, v161, v83
	v_fmac_f32_e32 v235, v161, v87
	v_fmac_f32_e32 v236, v161, v91
	v_fmac_f32_e32 v237, v161, v95
	v_add_f32_dpp v234, v234, v234 quad_perm:[1,0,3,2] row_mask:0xf bank_mask:0xf
	v_add_f32_dpp v235, v235, v235 quad_perm:[1,0,3,2] row_mask:0xf bank_mask:0xf
	v_add_f32_dpp v236, v236, v236 quad_perm:[1,0,3,2] row_mask:0xf bank_mask:0xf
	v_add_f32_dpp v237, v237, v237 quad_perm:[1,0,3,2] row_mask:0xf bank_mask:0xf
	v_add_f32_dpp v234, v234, v234 quad_perm:[2,3,0,1] row_mask:0xf bank_mask:0xf
	v_add_f32_dpp v235, v235, v235 quad_perm:[2,3,0,1] row_mask:0xf bank_mask:0xf
	v_add_f32_dpp v236, v236, v236 quad_perm:[2,3,0,1] row_mask:0xf bank_mask:0xf
	v_add_f32_dpp v237, v237, v237 quad_perm:[2,3,0,1] row_mask:0xf bank_mask:0xf
	v_add_f32_dpp v234, v234, v234 row_half_mirror row_mask:0xf bank_mask:0xf
	v_add_f32_dpp v235, v235, v235 row_half_mirror row_mask:0xf bank_mask:0xf
	v_add_f32_dpp v236, v236, v236 row_half_mirror row_mask:0xf bank_mask:0xf
	v_add_f32_dpp v237, v237, v237 row_half_mirror row_mask:0xf bank_mask:0xf
	s_mov_b32 exec_lo, 0x10001
	s_mov_b32 exec_hi, 0x10001
	ds_write_b32 v155, v234 offset:1984
	ds_write_b32 v155, v235 offset:2000
	ds_write_b32 v155, v236 offset:2016
	ds_write_b32 v155, v237 offset:2032
	s_mov_b64 exec, -1
	s_waitcnt lgkmcnt(0)
	v_lshl_add_u32 v96, v96, 9, v144
	v_lshl_add_u32 v97, v97, 9, v144
	v_lshl_add_u32 v98, v98, 9, v144
	v_lshl_add_u32 v99, v99, 9, v144
	global_load_dwordx4 v[0:3], v96, s[10:11]
	global_load_dwordx4 v[4:7], v96, s[10:11] offset:256
	global_load_dwordx4 v[8:11], v97, s[10:11]
	global_load_dwordx4 v[12:15], v97, s[10:11] offset:256
	global_load_dwordx4 v[16:19], v98, s[10:11]
	global_load_dwordx4 v[20:23], v98, s[10:11] offset:256
	global_load_dwordx4 v[24:27], v99, s[10:11]
	global_load_dwordx4 v[28:31], v99, s[10:11] offset:256
	ds_read2_b32 v[230:231], v245 offset0:112 offset1:116
	ds_read2_b32 v[232:233], v245 offset0:120 offset1:124
	s_waitcnt vmcnt(8)
	v_mfma_scale_f32_16x16x128_f8f6f4 v[80:83], v[32:35], v[178:185], 0, v133, v133 op_sel_hi:[0,0,0] cbsz:4
	v_mfma_scale_f32_16x16x128_f8f6f4 v[80:83], v[36:39], v[186:193], v[80:83], v133, v133 op_sel_hi:[0,0,0] cbsz:4
	v_mfma_scale_f32_16x16x128_f8f6f4 v[84:87], v[40:43], v[178:185], 0, v133, v133 op_sel_hi:[0,0,0] cbsz:4
	v_mfma_scale_f32_16x16x128_f8f6f4 v[84:87], v[44:47], v[186:193], v[84:87], v133, v133 op_sel_hi:[0,0,0] cbsz:4
	v_mfma_scale_f32_16x16x128_f8f6f4 v[88:91], v[48:51], v[178:185], 0, v133, v133 op_sel_hi:[0,0,0] cbsz:4
	v_mfma_scale_f32_16x16x128_f8f6f4 v[88:91], v[52:55], v[186:193], v[88:91], v133, v133 op_sel_hi:[0,0,0] cbsz:4
	v_mfma_scale_f32_16x16x128_f8f6f4 v[92:95], v[56:59], v[178:185], 0, v133, v133 op_sel_hi:[0,0,0] cbsz:4
	v_mfma_scale_f32_16x16x128_f8f6f4 v[92:95], v[60:63], v[186:193], v[92:95], v133, v133 op_sel_hi:[0,0,0] cbsz:4
	s_nop 3
	v_mul_f32_e32 v234, v226, v64
	v_mul_f32_e32 v235, v226, v68
	v_mul_f32_e32 v236, v226, v72
	v_mul_f32_e32 v237, v226, v76
	v_fmac_f32_e32 v234, v227, v65
	v_fmac_f32_e32 v235, v227, v69
	v_fmac_f32_e32 v236, v227, v73
	v_fmac_f32_e32 v237, v227, v77
	v_fmac_f32_e32 v234, v228, v66
	v_fmac_f32_e32 v235, v228, v70
	v_fmac_f32_e32 v236, v228, v74
	v_fmac_f32_e32 v237, v228, v78
	v_fmac_f32_e32 v234, v229, v67
	v_fmac_f32_e32 v235, v229, v71
	v_fmac_f32_e32 v236, v229, v75
	v_fmac_f32_e32 v237, v229, v79
	v_add_f32_dpp v234, v234, v234 quad_perm:[1,0,3,2] row_mask:0xf bank_mask:0xf
	v_add_f32_dpp v235, v235, v235 quad_perm:[1,0,3,2] row_mask:0xf bank_mask:0xf
	v_add_f32_dpp v236, v236, v236 quad_perm:[1,0,3,2] row_mask:0xf bank_mask:0xf
	v_add_f32_dpp v237, v237, v237 quad_perm:[1,0,3,2] row_mask:0xf bank_mask:0xf
	v_add_f32_dpp v234, v234, v234 quad_perm:[2,3,0,1] row_mask:0xf bank_mask:0xf
	v_add_f32_dpp v235, v235, v235 quad_perm:[2,3,0,1] row_mask:0xf bank_mask:0xf
	v_add_f32_dpp v236, v236, v236 quad_perm:[2,3,0,1] row_mask:0xf bank_mask:0xf
	v_add_f32_dpp v237, v237, v237 quad_perm:[2,3,0,1] row_mask:0xf bank_mask:0xf
	v_add_f32_dpp v234, v234, v234 row_half_mirror row_mask:0xf bank_mask:0xf
	v_add_f32_dpp v235, v235, v235 row_half_mirror row_mask:0xf bank_mask:0xf
	v_add_f32_dpp v236, v236, v236 row_half_mirror row_mask:0xf bank_mask:0xf
	v_add_f32_dpp v237, v237, v237 row_half_mirror row_mask:0xf bank_mask:0xf
	s_mov_b32 exec_lo, 0x1000100
	s_mov_b32 exec_hi, 0x1000100
	ds_write_b32 v155, v234 offset:2496
	ds_write_b32 v155, v235 offset:2512
	ds_write_b32 v155, v236 offset:2528
	ds_write_b32 v155, v237 offset:2544
	s_mov_b64 exec, -1
	s_waitcnt lgkmcnt(0)
; __device__ __forceinline__ void peer_token(const Params& P, int t, int lane, int* sidx, float* sval, const int* sid, const float* sgate, const unsigned* szero) {
;     ...
;         for (int hh = 0; hh < 2; ++hh)
; #pragma unroll
;             for (int st = 0; st < 4; ++st) abuf[0][hh][st] = *(const uint4*)(Ub + (off2[hh] + 128 * st));
; #pragma unroll
;         for (int T = 0; T < 8; ++T) {
;             if (T + 1 < 8) {
; #pragma unroll
;                 for (int hh = 0; hh < 2; ++hh) off2[hh] = (unsigned)sid[16 * (T + 1) + 8 * hh + (lr & 7)] * 512u + lofs;
; #pragma unroll
;                 for (int hh = 0; hh < 2; ++hh)
; #pragma unroll
;                     for (int st = 0; st < 4; ++st) abuf[(T + 1) & 1][hh][st] = *(const uint4*)(Ub + (off2[hh] + 128 * st));
;             }
; #pragma unroll
;             for (int hh = 0; hh < 2; ++hh) {
;                 f32x4 au = (f32x4){0.f, 0.f, 0.f, 0.f};
; #pragma unroll
;                 for (int st = 0; st < 4; ++st) {
;                     const uint4 a4 = abuf[T & 1][hh][st];
;                     const v8i Av = {(int)a4.x, (int)a4.y, (int)a4.z, (int)a4.w, 0, 0, 0, 0};
;                     au = __builtin_amdgcn_mfma_scale_f32_16x16x128_f8f6f4(Av, Bv[st], au, 4, 0, 0, 0x7f7f7f7f, 0, 0x7f7f7f7f);
;                 }
;                 if (owner) *(f32x4*)(sact + 16 * T + 8 * hh) = au;
;             }
;         }
	v_lshl_add_u32 v230, v230, 9, v144
	v_lshl_add_u32 v231, v231, 9, v144
	v_lshl_add_u32 v232, v232, 9, v144
	v_lshl_add_u32 v233, v233, 9, v144
	global_load_dwordx4 v[32:35], v230, s[10:11]
	global_load_dwordx4 v[36:39], v230, s[10:11] offset:256
	global_load_dwordx4 v[40:43], v231, s[10:11]
	global_load_dwordx4 v[44:47], v231, s[10:11] offset:256
	global_load_dwordx4 v[48:51], v232, s[10:11]
	global_load_dwordx4 v[52:55], v232, s[10:11] offset:256
	global_load_dwordx4 v[56:59], v233, s[10:11]
	global_load_dwordx4 v[60:63], v233, s[10:11] offset:256
	s_waitcnt vmcnt(8)
	v_mfma_scale_f32_16x16x128_f8f6f4 v[64:67], v[0:3], v[194:201], 0, v133, v133 op_sel_hi:[0,0,0] cbsz:4
	v_mfma_scale_f32_16x16x128_f8f6f4 v[64:67], v[4:7], v[202:209], v[64:67], v133, v133 op_sel_hi:[0,0,0] cbsz:4
	v_mfma_scale_f32_16x16x128_f8f6f4 v[68:71], v[8:11], v[194:201], 0, v133, v133 op_sel_hi:[0,0,0] cbsz:4
	v_mfma_scale_f32_16x16x128_f8f6f4 v[68:71], v[12:15], v[202:209], v[68:71], v133, v133 op_sel_hi:[0,0,0] cbsz:4
	v_mfma_scale_f32_16x16x128_f8f6f4 v[72:75], v[16:19], v[194:201], 0, v133, v133 op_sel_hi:[0,0,0] cbsz:4
	v_mfma_scale_f32_16x16x128_f8f6f4 v[72:75], v[20:23], v[202:209], v[72:75], v133, v133 op_sel_hi:[0,0,0] cbsz:4
	v_mfma_scale_f32_16x16x128_f8f6f4 v[76:79], v[24:27], v[194:201], 0, v133, v133 op_sel_hi:[0,0,0] cbsz:4
	v_mfma_scale_f32_16x16x128_f8f6f4 v[76:79], v[28:31], v[202:209], v[76:79], v133, v133 op_sel_hi:[0,0,0] cbsz:4
	s_nop 3
	v_mul_f32_e32 v234, v226, v80
	v_mul_f32_e32 v235, v226, v84
	v_mul_f32_e32 v236, v226, v88
	v_mul_f32_e32 v237, v226, v92
	v_fmac_f32_e32 v234, v227, v81
	v_fmac_f32_e32 v235, v227, v85
	v_fmac_f32_e32 v236, v227, v89
	v_fmac_f32_e32 v237, v227, v93
	v_fmac_f32_e32 v234, v228, v82
	v_fmac_f32_e32 v235, v228, v86
	v_fmac_f32_e32 v236, v228, v90
	v_fmac_f32_e32 v237, v228, v94
	v_fmac_f32_e32 v234, v229, v83
	v_fmac_f32_e32 v235, v229, v87
	v_fmac_f32_e32 v236, v229, v91
	v_fmac_f32_e32 v237, v229, v95
	v_add_f32_dpp v234, v234, v234 quad_perm:[1,0,3,2] row_mask:0xf bank_mask:0xf
	v_add_f32_dpp v235, v235, v235 quad_perm:[1,0,3,2] row_mask:0xf bank_mask:0xf
	v_add_f32_dpp v236, v236, v236 quad_perm:[1,0,3,2] row_mask:0xf bank_mask:0xf
	v_add_f32_dpp v237, v237, v237 quad_perm:[1,0,3,2] row_mask:0xf bank_mask:0xf
	v_add_f32_dpp v234, v234, v234 quad_perm:[2,3,0,1] row_mask:0xf bank_mask:0xf
	v_add_f32_dpp v235, v235, v235 quad_perm:[2,3,0,1] row_mask:0xf bank_mask:0xf
	v_add_f32_dpp v236, v236, v236 quad_perm:[2,3,0,1] row_mask:0xf bank_mask:0xf
	v_add_f32_dpp v237, v237, v237 quad_perm:[2,3,0,1] row_mask:0xf bank_mask:0xf
	v_add_f32_dpp v234, v234, v234 row_half_mirror row_mask:0xf bank_mask:0xf
	v_add_f32_dpp v235, v235, v235 row_half_mirror row_mask:0xf bank_mask:0xf
	v_add_f32_dpp v236, v236, v236 row_half_mirror row_mask:0xf bank_mask:0xf
	v_add_f32_dpp v237, v237, v237 row_half_mirror row_mask:0xf bank_mask:0xf
	s_mov_b32 exec_lo, 0x1000100
	s_mov_b32 exec_hi, 0x1000100
	ds_write_b32 v155, v234 offset:3008
	ds_write_b32 v155, v235 offset:3024
	ds_write_b32 v155, v236 offset:3040
	ds_write_b32 v155, v237 offset:3056
	s_mov_b64 exec, -1
	s_waitcnt vmcnt(0)
; __device__ __forceinline__ void peer_token(const Params& P, int t, int lane, int* sidx, float* sval, const int* sid, const float* sgate, const unsigned* szero) {
;     ...
;         for (int hh = 0; hh < 2; ++hh)
; #pragma unroll
;             for (int st = 0; st < 4; ++st) abuf[0][hh][st] = *(const uint4*)(Ub + (off2[hh] + 128 * st));
; #pragma unroll
;         for (int T = 0; T < 8; ++T) {
;             if (T + 1 < 8) {
; #pragma unroll
;                 for (int hh = 0; hh < 2; ++hh) off2[hh] = (unsigned)sid[16 * (T + 1) + 8 * hh + (lr & 7)] * 512u + lofs;
; #pragma unroll
;                 for (int hh = 0; hh < 2; ++hh)
; #pragma unroll
;                     for (int st = 0; st < 4; ++st) abuf[(T + 1) & 1][hh][st] = *(const uint4*)(Ub + (off2[hh] + 128 * st));
;             }
; #pragma unroll
;             for (int hh = 0; hh < 2; ++hh) {
;                 f32x4 au = (f32x4){0.f, 0.f, 0.f, 0.f};
; #pragma unroll
;                 for (int st = 0; st < 4; ++st) {
;                     const uint4 a4 = abuf[T & 1][hh][st];
;                     const v8i Av = {(int)a4.x, (int)a4.y, (int)a4.z, (int)a4.w, 0, 0, 0, 0};
;                     au = __builtin_amdgcn_mfma_scale_f32_16x16x128_f8f6f4(Av, Bv[st], au, 4, 0, 0, 0x7f7f7f7f, 0, 0x7f7f7f7f);
;                 }
;                 if (owner) *(f32x4*)(sact + 16 * T + 8 * hh) = au;
;             }
;         }
	v_mfma_scale_f32_16x16x128_f8f6f4 v[80:83], v[32:35], v[210:217], 0, v133, v133 op_sel_hi:[0,0,0] cbsz:4
	v_mfma_scale_f32_16x16x128_f8f6f4 v[80:83], v[36:39], v[218:225], v[80:83], v133, v133 op_sel_hi:[0,0,0] cbsz:4
	v_mfma_scale_f32_16x16x128_f8f6f4 v[84:87], v[40:43], v[210:217], 0, v133, v133 op_sel_hi:[0,0,0] cbsz:4
	v_mfma_scale_f32_16x16x128_f8f6f4 v[84:87], v[44:47], v[218:225], v[84:87], v133, v133 op_sel_hi:[0,0,0] cbsz:4
	v_mfma_scale_f32_16x16x128_f8f6f4 v[88:91], v[48:51], v[210:217], 0, v133, v133 op_sel_hi:[0,0,0] cbsz:4
	v_mfma_scale_f32_16x16x128_f8f6f4 v[88:91], v[52:55], v[218:225], v[88:91], v133, v133 op_sel_hi:[0,0,0] cbsz:4
	v_mfma_scale_f32_16x16x128_f8f6f4 v[92:95], v[56:59], v[210:217], 0, v133, v133 op_sel_hi:[0,0,0] cbsz:4
	v_mfma_scale_f32_16x16x128_f8f6f4 v[92:95], v[60:63], v[218:225], v[92:95], v133, v133 op_sel_hi:[0,0,0] cbsz:4
	s_nop 3
	v_mul_f32_e32 v234, v226, v64
	v_mul_f32_e32 v235, v226, v68
	v_mul_f32_e32 v236, v226, v72
	v_mul_f32_e32 v237, v226, v76
	v_fmac_f32_e32 v234, v227, v65
	v_fmac_f32_e32 v235, v227, v69
	v_fmac_f32_e32 v236, v227, v73
	v_fmac_f32_e32 v237, v227, v77
	v_fmac_f32_e32 v234, v228, v66
	v_fmac_f32_e32 v235, v228, v70
	v_fmac_f32_e32 v236, v228, v74
	v_fmac_f32_e32 v237, v228, v78
	v_fmac_f32_e32 v234, v229, v67
	v_fmac_f32_e32 v235, v229, v71
	v_fmac_f32_e32 v236, v229, v75
	v_fmac_f32_e32 v237, v229, v79
	v_add_f32_dpp v234, v234, v234 quad_perm:[1,0,3,2] row_mask:0xf bank_mask:0xf
	v_add_f32_dpp v235, v235, v235 quad_perm:[1,0,3,2] row_mask:0xf bank_mask:0xf
	v_add_f32_dpp v236, v236, v236 quad_perm:[1,0,3,2] row_mask:0xf bank_mask:0xf
	v_add_f32_dpp v237, v237, v237 quad_perm:[1,0,3,2] row_mask:0xf bank_mask:0xf
	v_add_f32_dpp v234, v234, v234 quad_perm:[2,3,0,1] row_mask:0xf bank_mask:0xf
	v_add_f32_dpp v235, v235, v235 quad_perm:[2,3,0,1] row_mask:0xf bank_mask:0xf
	v_add_f32_dpp v236, v236, v236 quad_perm:[2,3,0,1] row_mask:0xf bank_mask:0xf
	v_add_f32_dpp v237, v237, v237 quad_perm:[2,3,0,1] row_mask:0xf bank_mask:0xf
	v_add_f32_dpp v234, v234, v234 row_half_mirror row_mask:0xf bank_mask:0xf
	v_add_f32_dpp v235, v235, v235 row_half_mirror row_mask:0xf bank_mask:0xf
	v_add_f32_dpp v236, v236, v236 row_half_mirror row_mask:0xf bank_mask:0xf
	v_add_f32_dpp v237, v237, v237 row_half_mirror row_mask:0xf bank_mask:0xf
	s_mov_b32 exec_lo, 0x1000100
	s_mov_b32 exec_hi, 0x1000100
	ds_write_b32 v155, v234 offset:3520
	ds_write_b32 v155, v235 offset:3536
	ds_write_b32 v155, v236 offset:3552
	ds_write_b32 v155, v237 offset:3568
	s_mov_b64 exec, -1
	s_nop 11
	v_mul_f32_e32 v234, v226, v80
	v_mul_f32_e32 v235, v226, v84
	v_mul_f32_e32 v236, v226, v88
	v_mul_f32_e32 v237, v226, v92
	v_fmac_f32_e32 v234, v227, v81
	v_fmac_f32_e32 v235, v227, v85
	v_fmac_f32_e32 v236, v227, v89
	v_fmac_f32_e32 v237, v227, v93
	v_fmac_f32_e32 v234, v228, v82
	v_fmac_f32_e32 v235, v228, v86
	v_fmac_f32_e32 v236, v228, v90
	v_fmac_f32_e32 v237, v228, v94
	v_fmac_f32_e32 v234, v229, v83
	v_fmac_f32_e32 v235, v229, v87
	v_fmac_f32_e32 v236, v229, v91
	v_fmac_f32_e32 v237, v229, v95
	v_add_f32_dpp v234, v234, v234 quad_perm:[1,0,3,2] row_mask:0xf bank_mask:0xf
	v_add_f32_dpp v235, v235, v235 quad_perm:[1,0,3,2] row_mask:0xf bank_mask:0xf
	v_add_f32_dpp v236, v236, v236 quad_perm:[1,0,3,2] row_mask:0xf bank_mask:0xf
	v_add_f32_dpp v237, v237, v237 quad_perm:[1,0,3,2] row_mask:0xf bank_mask:0xf
	v_add_f32_dpp v234, v234, v234 quad_perm:[2,3,0,1] row_mask:0xf bank_mask:0xf
	v_add_f32_dpp v235, v235, v235 quad_perm:[2,3,0,1] row_mask:0xf bank_mask:0xf
	v_add_f32_dpp v236, v236, v236 quad_perm:[2,3,0,1] row_mask:0xf bank_mask:0xf
	v_add_f32_dpp v237, v237, v237 quad_perm:[2,3,0,1] row_mask:0xf bank_mask:0xf
	v_add_f32_dpp v234, v234, v234 row_half_mirror row_mask:0xf bank_mask:0xf
	v_add_f32_dpp v235, v235, v235 row_half_mirror row_mask:0xf bank_mask:0xf
	v_add_f32_dpp v236, v236, v236 row_half_mirror row_mask:0xf bank_mask:0xf
	v_add_f32_dpp v237, v237, v237 row_half_mirror row_mask:0xf bank_mask:0xf
	s_mov_b32 exec_lo, 0x1000100
	s_mov_b32 exec_hi, 0x1000100
	ds_write_b32 v155, v234 offset:4032
	ds_write_b32 v155, v235 offset:4048
	ds_write_b32 v155, v236 offset:4064
	ds_write_b32 v155, v237 offset:4080
	s_mov_b64 exec, -1
	s_waitcnt lgkmcnt(0)
	s_mov_b32 s85, 0
